# GEMM K-loops: LDS-DMA loads use SGPR base + 32-bit VGPR offset instead of per-load 64-bit VALU address adds
# baseline (speedup 1.0000x reference)
.LBB0_213:
	v_add_u32_e32 v206, 0x80, v130
	v_add_u32_e32 v207, 0x80, v134
	v_add_u32_e32 v208, 0x80, v128
	v_add_u32_e32 v209, 0x80, v132
	ds_read_b128 v[154:157], v147
	ds_read_b128 v[158:161], v147 offset:1024
	ds_read_b128 v[162:165], v147 offset:2048
	ds_read_b128 v[166:169], v147 offset:3072
	ds_read_b128 v[170:173], v149
	ds_read_b128 v[174:177], v149 offset:1024
	ds_read_b128 v[178:181], v149 offset:2048
	ds_read_b128 v[182:185], v149 offset:3072
	s_add_u32 s26, s46, 0xfffc0080
	s_addc_u32 s27, s47, -1
	s_cmp_eq_u32 s72, 12
	s_cselect_b32 s53, s7, s27
	s_cselect_b32 s52, s21, s26
	s_cselect_b32 s49, s17, s71
	s_cselect_b32 s48, s69, s70
	s_add_i32 m0, s51, 0xc000
	ds_read_b128 v[186:189], v151
	ds_read_b128 v[190:193], v151 offset:1024
	ds_read_b128 v[194:197], v151 offset:2048
	ds_read_b128 v[198:201], v151 offset:3072
	ds_read_b128 v[202:205], v151 offset:4096
	ds_read_b128 v[212:215], v151 offset:5120
	ds_read_b128 v[216:219], v151 offset:6144
	ds_read_b128 v[220:223], v151 offset:7168
	global_load_lds_dwordx4 v136, s[46:47]
	s_add_i32 m0, s51, 0xe000
	s_nop 0
	global_load_lds_dwordx4 v138, s[46:47]
	s_waitcnt vmcnt(8)
	s_waitcnt lgkmcnt(0)
	s_barrier
	s_setprio 1
	s_waitcnt lgkmcnt(0)
	v_mfma_f32_16x16x32_bf16 v[124:127], v[154:157], v[186:189], v[124:127]
	v_mfma_f32_16x16x32_bf16 v[120:123], v[162:165], v[186:189], v[120:123]
	v_mfma_f32_16x16x32_bf16 v[108:111], v[154:157], v[194:197], v[108:111]
	v_mfma_f32_16x16x32_bf16 v[104:107], v[162:165], v[194:197], v[104:107]
	v_mfma_f32_16x16x32_bf16 v[92:95], v[154:157], v[202:205], v[92:95]
	v_mfma_f32_16x16x32_bf16 v[88:91], v[162:165], v[202:205], v[88:91]
	v_mfma_f32_16x16x32_bf16 v[76:79], v[154:157], v[216:219], v[76:79]
	v_mfma_f32_16x16x32_bf16 v[72:75], v[162:165], v[216:219], v[72:75]
	v_mfma_f32_16x16x32_bf16 v[124:127], v[158:161], v[190:193], v[124:127]
	v_mfma_f32_16x16x32_bf16 v[120:123], v[166:169], v[190:193], v[120:123]
	v_mfma_f32_16x16x32_bf16 v[108:111], v[158:161], v[198:201], v[108:111]
	v_mfma_f32_16x16x32_bf16 v[104:107], v[166:169], v[198:201], v[104:107]
	v_mfma_f32_16x16x32_bf16 v[92:95], v[158:161], v[212:215], v[92:95]
	v_mfma_f32_16x16x32_bf16 v[88:91], v[166:169], v[212:215], v[88:91]
	v_mfma_f32_16x16x32_bf16 v[76:79], v[158:161], v[220:223], v[76:79]
	v_mfma_f32_16x16x32_bf16 v[72:75], v[166:169], v[220:223], v[72:75]
	s_setprio 0
	s_setprio 1
	v_mfma_f32_16x16x32_bf16 v[116:119], v[170:173], v[186:189], v[116:119]
	v_mfma_f32_16x16x32_bf16 v[112:115], v[178:181], v[186:189], v[112:115]
	v_mfma_f32_16x16x32_bf16 v[100:103], v[170:173], v[194:197], v[100:103]
	v_mfma_f32_16x16x32_bf16 v[96:99], v[178:181], v[194:197], v[96:99]
	v_mfma_f32_16x16x32_bf16 v[84:87], v[170:173], v[202:205], v[84:87]
	v_mfma_f32_16x16x32_bf16 v[80:83], v[178:181], v[202:205], v[80:83]
	v_mfma_f32_16x16x32_bf16 v[68:71], v[170:173], v[216:219], v[68:71]
	v_mfma_f32_16x16x32_bf16 v[64:67], v[178:181], v[216:219], v[64:67]
	v_mfma_f32_16x16x32_bf16 v[116:119], v[174:177], v[190:193], v[116:119]
	v_mfma_f32_16x16x32_bf16 v[112:115], v[182:185], v[190:193], v[112:115]
	v_mfma_f32_16x16x32_bf16 v[100:103], v[174:177], v[198:201], v[100:103]
	v_mfma_f32_16x16x32_bf16 v[96:99], v[182:185], v[198:201], v[96:99]
	v_mfma_f32_16x16x32_bf16 v[84:87], v[174:177], v[212:215], v[84:87]
	v_mfma_f32_16x16x32_bf16 v[80:83], v[182:185], v[212:215], v[80:83]
	v_mfma_f32_16x16x32_bf16 v[68:71], v[174:177], v[220:223], v[68:71]
	v_mfma_f32_16x16x32_bf16 v[64:67], v[182:185], v[220:223], v[64:67]
	s_setprio 0
	s_barrier
	s_add_i32 s26, s64, s50
	s_mov_b32 m0, s26
	ds_read_b128 v[186:189], v151 offset:16384
	ds_read_b128 v[190:193], v151 offset:17408
	ds_read_b128 v[194:197], v151 offset:18432
	ds_read_b128 v[198:201], v151 offset:19456
	ds_read_b128 v[202:205], v151 offset:20480
	ds_read_b128 v[212:215], v151 offset:21504
	ds_read_b128 v[216:219], v151 offset:22528
	ds_read_b128 v[220:223], v151 offset:23552
	global_load_lds_dwordx4 v130, s[48:49]
	s_add_i32 m0, s26, 0x2000
	s_add_u32 s26, s48, 0x40000
	s_mov_b64 s[92:93], s[48:49]
	s_addc_u32 s27, s49, 0
	s_add_i32 s73, s65, s50
	global_load_lds_dwordx4 v134, s[92:93]
	s_mov_b32 m0, s73
	s_nop 0
	global_load_lds_dwordx4 v130, s[26:27]
	s_add_i32 m0, s73, 0x2000
	s_nop 0
	global_load_lds_dwordx4 v134, s[26:27]
	s_mov_b32 m0, s51
	s_nop 0
	global_load_lds_dwordx4 v128, s[52:53]
	s_mov_b32 m0, s54
	s_nop 0
	global_load_lds_dwordx4 v132, s[52:53]
	s_waitcnt vmcnt(8)
	s_waitcnt lgkmcnt(0)
	s_barrier
	s_setprio 1
	s_waitcnt lgkmcnt(0)
	v_mfma_f32_16x16x32_bf16 v[60:63], v[154:157], v[186:189], v[60:63]
	v_mfma_f32_16x16x32_bf16 v[56:59], v[162:165], v[186:189], v[56:59]
	v_mfma_f32_16x16x32_bf16 v[44:47], v[154:157], v[194:197], v[44:47]
	v_mfma_f32_16x16x32_bf16 v[40:43], v[162:165], v[194:197], v[40:43]
	v_mfma_f32_16x16x32_bf16 v[28:31], v[154:157], v[202:205], v[28:31]
	v_mfma_f32_16x16x32_bf16 v[24:27], v[162:165], v[202:205], v[24:27]
	v_mfma_f32_16x16x32_bf16 v[12:15], v[154:157], v[216:219], v[12:15]
	v_mfma_f32_16x16x32_bf16 v[8:11], v[162:165], v[216:219], v[8:11]
	v_mfma_f32_16x16x32_bf16 v[60:63], v[158:161], v[190:193], v[60:63]
	v_mfma_f32_16x16x32_bf16 v[56:59], v[166:169], v[190:193], v[56:59]
	v_mfma_f32_16x16x32_bf16 v[44:47], v[158:161], v[198:201], v[44:47]
	v_mfma_f32_16x16x32_bf16 v[40:43], v[166:169], v[198:201], v[40:43]
	v_mfma_f32_16x16x32_bf16 v[28:31], v[158:161], v[212:215], v[28:31]
	v_mfma_f32_16x16x32_bf16 v[24:27], v[166:169], v[212:215], v[24:27]
	v_mfma_f32_16x16x32_bf16 v[12:15], v[158:161], v[220:223], v[12:15]
	v_mfma_f32_16x16x32_bf16 v[8:11], v[166:169], v[220:223], v[8:11]
	s_setprio 0
	s_setprio 1
	v_mfma_f32_16x16x32_bf16 v[52:55], v[170:173], v[186:189], v[52:55]
	v_mfma_f32_16x16x32_bf16 v[48:51], v[178:181], v[186:189], v[48:51]
	v_mfma_f32_16x16x32_bf16 v[36:39], v[170:173], v[194:197], v[36:39]
	v_mfma_f32_16x16x32_bf16 v[32:35], v[178:181], v[194:197], v[32:35]
	v_mfma_f32_16x16x32_bf16 v[20:23], v[170:173], v[202:205], v[20:23]
	v_mfma_f32_16x16x32_bf16 v[16:19], v[178:181], v[202:205], v[16:19]
	v_mfma_f32_16x16x32_bf16 v[4:7], v[170:173], v[216:219], v[4:7]
	v_mfma_f32_16x16x32_bf16 v[0:3], v[178:181], v[216:219], v[0:3]
	v_mfma_f32_16x16x32_bf16 v[52:55], v[174:177], v[190:193], v[52:55]
	v_mfma_f32_16x16x32_bf16 v[48:51], v[182:185], v[190:193], v[48:51]
	v_mfma_f32_16x16x32_bf16 v[36:39], v[174:177], v[198:201], v[36:39]
	v_mfma_f32_16x16x32_bf16 v[32:35], v[182:185], v[198:201], v[32:35]
	v_mfma_f32_16x16x32_bf16 v[20:23], v[174:177], v[212:215], v[20:23]
	v_mfma_f32_16x16x32_bf16 v[16:19], v[182:185], v[212:215], v[16:19]
	v_mfma_f32_16x16x32_bf16 v[4:7], v[174:177], v[220:223], v[4:7]
	v_mfma_f32_16x16x32_bf16 v[0:3], v[182:185], v[220:223], v[0:3]
	s_setprio 0
	s_barrier
	s_add_i32 s73, 0, 0x18000
	v_add_u32_e32 v146, s73, v145
	s_add_i32 s74, 0, 0x1c000
	ds_read_b128 v[154:157], v146
	ds_read_b128 v[158:161], v146 offset:1024
	ds_read_b128 v[162:165], v146 offset:2048
	ds_read_b128 v[166:169], v146 offset:3072
	v_add_u32_e32 v146, s74, v145
	ds_read_b128 v[170:173], v146
	ds_read_b128 v[174:177], v146 offset:1024
	ds_read_b128 v[178:181], v146 offset:2048
	ds_read_b128 v[182:185], v146 offset:3072
	s_add_u32 s26, s52, 0x40000
	s_addc_u32 s27, s53, 0
	s_mov_b32 m0, s55
	ds_read_b128 v[186:189], v151 offset:32768
	ds_read_b128 v[190:193], v151 offset:33792
	ds_read_b128 v[194:197], v151 offset:34816
	ds_read_b128 v[198:201], v151 offset:35840
	ds_read_b128 v[202:205], v151 offset:36864
	ds_read_b128 v[212:215], v151 offset:37888
	ds_read_b128 v[216:219], v151 offset:38912
	ds_read_b128 v[220:223], v151 offset:39936
	global_load_lds_dwordx4 v128, s[26:27]
	s_mov_b32 m0, s56
	s_nop 0
	global_load_lds_dwordx4 v132, s[26:27]
	s_waitcnt vmcnt(8)
	s_waitcnt lgkmcnt(0)
	s_barrier
	s_setprio 1
	s_waitcnt lgkmcnt(0)
	v_mfma_f32_16x16x32_bf16 v[124:127], v[154:157], v[186:189], v[124:127]
	v_mfma_f32_16x16x32_bf16 v[120:123], v[162:165], v[186:189], v[120:123]
	v_mfma_f32_16x16x32_bf16 v[108:111], v[154:157], v[194:197], v[108:111]
	v_mfma_f32_16x16x32_bf16 v[104:107], v[162:165], v[194:197], v[104:107]
	v_mfma_f32_16x16x32_bf16 v[92:95], v[154:157], v[202:205], v[92:95]
	v_mfma_f32_16x16x32_bf16 v[88:91], v[162:165], v[202:205], v[88:91]
	v_mfma_f32_16x16x32_bf16 v[76:79], v[154:157], v[216:219], v[76:79]
	v_mfma_f32_16x16x32_bf16 v[72:75], v[162:165], v[216:219], v[72:75]
	v_mfma_f32_16x16x32_bf16 v[124:127], v[158:161], v[190:193], v[124:127]
	v_mfma_f32_16x16x32_bf16 v[120:123], v[166:169], v[190:193], v[120:123]
	v_mfma_f32_16x16x32_bf16 v[108:111], v[158:161], v[198:201], v[108:111]
	v_mfma_f32_16x16x32_bf16 v[104:107], v[166:169], v[198:201], v[104:107]
	v_mfma_f32_16x16x32_bf16 v[92:95], v[158:161], v[212:215], v[92:95]
	v_mfma_f32_16x16x32_bf16 v[88:91], v[166:169], v[212:215], v[88:91]
	v_mfma_f32_16x16x32_bf16 v[76:79], v[158:161], v[220:223], v[76:79]
	v_mfma_f32_16x16x32_bf16 v[72:75], v[166:169], v[220:223], v[72:75]
	s_setprio 0
	s_setprio 1
	v_mfma_f32_16x16x32_bf16 v[116:119], v[170:173], v[186:189], v[116:119]
	v_mfma_f32_16x16x32_bf16 v[112:115], v[178:181], v[186:189], v[112:115]
	v_mfma_f32_16x16x32_bf16 v[100:103], v[170:173], v[194:197], v[100:103]
	v_mfma_f32_16x16x32_bf16 v[96:99], v[178:181], v[194:197], v[96:99]
	v_mfma_f32_16x16x32_bf16 v[84:87], v[170:173], v[202:205], v[84:87]
	v_mfma_f32_16x16x32_bf16 v[80:83], v[178:181], v[202:205], v[80:83]
	v_mfma_f32_16x16x32_bf16 v[68:71], v[170:173], v[216:219], v[68:71]
	v_mfma_f32_16x16x32_bf16 v[64:67], v[178:181], v[216:219], v[64:67]
	v_mfma_f32_16x16x32_bf16 v[116:119], v[174:177], v[190:193], v[116:119]
	v_mfma_f32_16x16x32_bf16 v[112:115], v[182:185], v[190:193], v[112:115]
	v_mfma_f32_16x16x32_bf16 v[100:103], v[174:177], v[198:201], v[100:103]
	v_mfma_f32_16x16x32_bf16 v[96:99], v[182:185], v[198:201], v[96:99]
	v_mfma_f32_16x16x32_bf16 v[84:87], v[174:177], v[212:215], v[84:87]
	v_mfma_f32_16x16x32_bf16 v[80:83], v[182:185], v[212:215], v[80:83]
	v_mfma_f32_16x16x32_bf16 v[68:71], v[174:177], v[220:223], v[68:71]
	v_mfma_f32_16x16x32_bf16 v[64:67], v[182:185], v[220:223], v[64:67]
	s_setprio 0
	s_barrier
	s_add_i32 s26, s73, s50
	s_mov_b32 m0, s26
	ds_read_b128 v[186:189], v151 offset:49152
	ds_read_b128 v[190:193], v151 offset:50176
	ds_read_b128 v[194:197], v151 offset:51200
	ds_read_b128 v[198:201], v151 offset:52224
	ds_read_b128 v[202:205], v151 offset:53248
	ds_read_b128 v[212:215], v151 offset:54272
	ds_read_b128 v[216:219], v151 offset:55296
	ds_read_b128 v[220:223], v151 offset:56320
	global_load_lds_dwordx4 v206, s[48:49]
	s_add_i32 m0, s26, 0x2000
	s_add_u32 s26, s48, 0x40080
	s_addc_u32 s27, s49, 0
	s_add_i32 s48, s74, s50
	global_load_lds_dwordx4 v207, s[92:93]
	s_mov_b32 m0, s48
	s_nop 0
	global_load_lds_dwordx4 v130, s[26:27]
	s_add_i32 m0, s48, 0x2000
	s_nop 0
	global_load_lds_dwordx4 v134, s[26:27]
	s_mov_b32 m0, s60
	s_nop 0
	global_load_lds_dwordx4 v208, s[52:53]
	s_mov_b32 m0, s61
	s_nop 0
	global_load_lds_dwordx4 v209, s[52:53]
	s_waitcnt vmcnt(8)
	s_waitcnt lgkmcnt(0)
	s_barrier
	s_setprio 1
	s_waitcnt lgkmcnt(0)
	v_mfma_f32_16x16x32_bf16 v[60:63], v[154:157], v[186:189], v[60:63]
	v_mfma_f32_16x16x32_bf16 v[56:59], v[162:165], v[186:189], v[56:59]
	v_mfma_f32_16x16x32_bf16 v[44:47], v[154:157], v[194:197], v[44:47]
	v_mfma_f32_16x16x32_bf16 v[40:43], v[162:165], v[194:197], v[40:43]
	v_mfma_f32_16x16x32_bf16 v[28:31], v[154:157], v[202:205], v[28:31]
	v_mfma_f32_16x16x32_bf16 v[24:27], v[162:165], v[202:205], v[24:27]
	v_mfma_f32_16x16x32_bf16 v[12:15], v[154:157], v[216:219], v[12:15]
	v_mfma_f32_16x16x32_bf16 v[8:11], v[162:165], v[216:219], v[8:11]
	v_mfma_f32_16x16x32_bf16 v[60:63], v[158:161], v[190:193], v[60:63]
	v_mfma_f32_16x16x32_bf16 v[56:59], v[166:169], v[190:193], v[56:59]
	v_mfma_f32_16x16x32_bf16 v[44:47], v[158:161], v[198:201], v[44:47]
	v_mfma_f32_16x16x32_bf16 v[40:43], v[166:169], v[198:201], v[40:43]
	v_mfma_f32_16x16x32_bf16 v[28:31], v[158:161], v[212:215], v[28:31]
	v_mfma_f32_16x16x32_bf16 v[24:27], v[166:169], v[212:215], v[24:27]
	v_mfma_f32_16x16x32_bf16 v[12:15], v[158:161], v[220:223], v[12:15]
	v_mfma_f32_16x16x32_bf16 v[8:11], v[166:169], v[220:223], v[8:11]
	s_setprio 0
	s_setprio 1
	v_mfma_f32_16x16x32_bf16 v[52:55], v[170:173], v[186:189], v[52:55]
	v_mfma_f32_16x16x32_bf16 v[48:51], v[178:181], v[186:189], v[48:51]
	v_mfma_f32_16x16x32_bf16 v[36:39], v[170:173], v[194:197], v[36:39]
	v_mfma_f32_16x16x32_bf16 v[32:35], v[178:181], v[194:197], v[32:35]
	v_mfma_f32_16x16x32_bf16 v[20:23], v[170:173], v[202:205], v[20:23]
	v_mfma_f32_16x16x32_bf16 v[16:19], v[178:181], v[202:205], v[16:19]
	v_mfma_f32_16x16x32_bf16 v[4:7], v[170:173], v[216:219], v[4:7]
	v_mfma_f32_16x16x32_bf16 v[0:3], v[178:181], v[216:219], v[0:3]
	v_mfma_f32_16x16x32_bf16 v[52:55], v[174:177], v[190:193], v[52:55]
	v_mfma_f32_16x16x32_bf16 v[48:51], v[182:185], v[190:193], v[48:51]
	v_mfma_f32_16x16x32_bf16 v[36:39], v[174:177], v[198:201], v[36:39]
	v_mfma_f32_16x16x32_bf16 v[32:35], v[182:185], v[198:201], v[32:35]
	v_mfma_f32_16x16x32_bf16 v[20:23], v[174:177], v[212:215], v[20:23]
	v_mfma_f32_16x16x32_bf16 v[16:19], v[182:185], v[212:215], v[16:19]
	v_mfma_f32_16x16x32_bf16 v[4:7], v[174:177], v[220:223], v[4:7]
	v_mfma_f32_16x16x32_bf16 v[0:3], v[182:185], v[220:223], v[0:3]
	s_setprio 0
	s_barrier
	s_add_i32 s72, s72, 2
	s_add_u32 s46, s46, 0x100
	s_addc_u32 s47, s47, 0
	s_add_u32 s70, s70, 0x100
	s_addc_u32 s71, s71, 0
	s_cmp_gt_u32 s72, 13
	s_cbranch_scc0 .LBB0_213
	s_and_b64 vcc, exec, s[12:13]
	s_cbranch_vccz .LBB0_216
	s_barrier

.LBB0_299:
	v_add_u32_e32 v216, 0x80, v178
	v_add_u32_e32 v217, 0x80, v182
	v_add_u32_e32 v218, 0x80, v176
	v_add_u32_e32 v219, 0x80, v180
	ds_read_b128 v[128:131], v205
	ds_read_b128 v[132:135], v205 offset:1024
	ds_read_b128 v[136:139], v205 offset:2048
	ds_read_b128 v[140:143], v205 offset:3072
	ds_read_b128 v[144:147], v206
	ds_read_b128 v[148:151], v206 offset:1024
	ds_read_b128 v[152:155], v206 offset:2048
	ds_read_b128 v[156:159], v206 offset:3072
	s_add_u32 s48, s46, 0x100
	s_addc_u32 s49, s47, 0
	s_cmp_eq_u32 s73, 40
	s_cselect_b32 s55, s9, s49
	s_cselect_b32 s54, s8, s48
	s_cselect_b32 s53, s25, s72
	s_cselect_b32 s52, s24, s71
	s_add_i32 m0, s33, 0xc000
	ds_read_b128 v[160:163], v207
	ds_read_b128 v[164:167], v207 offset:1024
	ds_read_b128 v[168:171], v207 offset:2048
	ds_read_b128 v[172:175], v207 offset:3072
	ds_read_b128 v[192:195], v207 offset:4096
	ds_read_b128 v[196:199], v207 offset:5120
	ds_read_b128 v[200:203], v207 offset:6144
	ds_read_b128 v[212:215], v207 offset:7168
	global_load_lds_dwordx4 v184, s[46:47]
	s_add_i32 m0, s33, 0xe000
	s_nop 0
	global_load_lds_dwordx4 v186, s[46:47]
	s_waitcnt vmcnt(8)
	s_waitcnt lgkmcnt(0)
	s_barrier
	s_setprio 1
	s_waitcnt lgkmcnt(0)
	v_mfma_f32_16x16x32_bf16 v[124:127], v[128:131], v[160:163], v[124:127]
	v_mfma_f32_16x16x32_bf16 v[120:123], v[136:139], v[160:163], v[120:123]
	v_mfma_f32_16x16x32_bf16 v[108:111], v[128:131], v[168:171], v[108:111]
	v_mfma_f32_16x16x32_bf16 v[104:107], v[136:139], v[168:171], v[104:107]
	v_mfma_f32_16x16x32_bf16 v[92:95], v[128:131], v[192:195], v[92:95]
	v_mfma_f32_16x16x32_bf16 v[88:91], v[136:139], v[192:195], v[88:91]
	v_mfma_f32_16x16x32_bf16 v[76:79], v[128:131], v[200:203], v[76:79]
	v_mfma_f32_16x16x32_bf16 v[72:75], v[136:139], v[200:203], v[72:75]
	v_mfma_f32_16x16x32_bf16 v[124:127], v[132:135], v[164:167], v[124:127]
	v_mfma_f32_16x16x32_bf16 v[120:123], v[140:143], v[164:167], v[120:123]
	v_mfma_f32_16x16x32_bf16 v[108:111], v[132:135], v[172:175], v[108:111]
	v_mfma_f32_16x16x32_bf16 v[104:107], v[140:143], v[172:175], v[104:107]
	v_mfma_f32_16x16x32_bf16 v[92:95], v[132:135], v[196:199], v[92:95]
	v_mfma_f32_16x16x32_bf16 v[88:91], v[140:143], v[196:199], v[88:91]
	v_mfma_f32_16x16x32_bf16 v[76:79], v[132:135], v[212:215], v[76:79]
	v_mfma_f32_16x16x32_bf16 v[72:75], v[140:143], v[212:215], v[72:75]
	s_setprio 0
	s_setprio 1
	v_mfma_f32_16x16x32_bf16 v[116:119], v[144:147], v[160:163], v[116:119]
	v_mfma_f32_16x16x32_bf16 v[112:115], v[152:155], v[160:163], v[112:115]
	v_mfma_f32_16x16x32_bf16 v[100:103], v[144:147], v[168:171], v[100:103]
	v_mfma_f32_16x16x32_bf16 v[96:99], v[152:155], v[168:171], v[96:99]
	v_mfma_f32_16x16x32_bf16 v[84:87], v[144:147], v[192:195], v[84:87]
	v_mfma_f32_16x16x32_bf16 v[80:83], v[152:155], v[192:195], v[80:83]
	v_mfma_f32_16x16x32_bf16 v[68:71], v[144:147], v[200:203], v[68:71]
	v_mfma_f32_16x16x32_bf16 v[64:67], v[152:155], v[200:203], v[64:67]
	v_mfma_f32_16x16x32_bf16 v[116:119], v[148:151], v[164:167], v[116:119]
	v_mfma_f32_16x16x32_bf16 v[112:115], v[156:159], v[164:167], v[112:115]
	v_mfma_f32_16x16x32_bf16 v[100:103], v[148:151], v[172:175], v[100:103]
	v_mfma_f32_16x16x32_bf16 v[96:99], v[156:159], v[172:175], v[96:99]
	v_mfma_f32_16x16x32_bf16 v[84:87], v[148:151], v[196:199], v[84:87]
	v_mfma_f32_16x16x32_bf16 v[80:83], v[156:159], v[196:199], v[80:83]
	v_mfma_f32_16x16x32_bf16 v[68:71], v[148:151], v[212:215], v[68:71]
	v_mfma_f32_16x16x32_bf16 v[64:67], v[156:159], v[212:215], v[64:67]
	s_setprio 0
	s_barrier
	s_add_i32 s4, s65, s3
	s_mov_b32 m0, s4
	ds_read_b128 v[160:163], v207 offset:16384
	ds_read_b128 v[164:167], v207 offset:17408
	ds_read_b128 v[168:171], v207 offset:18432
	ds_read_b128 v[172:175], v207 offset:19456
	ds_read_b128 v[192:195], v207 offset:20480
	ds_read_b128 v[196:199], v207 offset:21504
	ds_read_b128 v[200:203], v207 offset:22528
	ds_read_b128 v[212:215], v207 offset:23552
	global_load_lds_dwordx4 v178, s[52:53]
	s_add_i32 m0, s4, 0x2000
	s_add_u32 s4, s52, 0xb0000
	s_addc_u32 s5, s53, 0
	s_add_i32 s26, s66, s3
	global_load_lds_dwordx4 v182, s[52:53]
	s_mov_b32 m0, s26
	s_nop 0
	global_load_lds_dwordx4 v178, s[4:5]
	s_add_i32 m0, s26, 0x2000
	s_nop 0
	global_load_lds_dwordx4 v182, s[4:5]
	s_mov_b32 m0, s33
	s_nop 0
	global_load_lds_dwordx4 v176, s[54:55]
	s_mov_b32 m0, s50
	s_nop 0
	global_load_lds_dwordx4 v180, s[54:55]
	s_waitcnt vmcnt(8)
	s_waitcnt lgkmcnt(0)
	s_barrier
	s_setprio 1
	s_waitcnt lgkmcnt(0)
	v_mfma_f32_16x16x32_bf16 v[60:63], v[128:131], v[160:163], v[60:63]
	v_mfma_f32_16x16x32_bf16 v[56:59], v[136:139], v[160:163], v[56:59]
	v_mfma_f32_16x16x32_bf16 v[44:47], v[128:131], v[168:171], v[44:47]
	v_mfma_f32_16x16x32_bf16 v[40:43], v[136:139], v[168:171], v[40:43]
	v_mfma_f32_16x16x32_bf16 v[28:31], v[128:131], v[192:195], v[28:31]
	v_mfma_f32_16x16x32_bf16 v[24:27], v[136:139], v[192:195], v[24:27]
	v_mfma_f32_16x16x32_bf16 v[12:15], v[128:131], v[200:203], v[12:15]
	v_mfma_f32_16x16x32_bf16 v[8:11], v[136:139], v[200:203], v[8:11]
	v_mfma_f32_16x16x32_bf16 v[60:63], v[132:135], v[164:167], v[60:63]
	v_mfma_f32_16x16x32_bf16 v[56:59], v[140:143], v[164:167], v[56:59]
	v_mfma_f32_16x16x32_bf16 v[44:47], v[132:135], v[172:175], v[44:47]
	v_mfma_f32_16x16x32_bf16 v[40:43], v[140:143], v[172:175], v[40:43]
	v_mfma_f32_16x16x32_bf16 v[28:31], v[132:135], v[196:199], v[28:31]
	v_mfma_f32_16x16x32_bf16 v[24:27], v[140:143], v[196:199], v[24:27]
	v_mfma_f32_16x16x32_bf16 v[12:15], v[132:135], v[212:215], v[12:15]
	v_mfma_f32_16x16x32_bf16 v[8:11], v[140:143], v[212:215], v[8:11]
	s_setprio 0
	s_setprio 1
	v_mfma_f32_16x16x32_bf16 v[52:55], v[144:147], v[160:163], v[52:55]
	v_mfma_f32_16x16x32_bf16 v[48:51], v[152:155], v[160:163], v[48:51]
	v_mfma_f32_16x16x32_bf16 v[36:39], v[144:147], v[168:171], v[36:39]
	v_mfma_f32_16x16x32_bf16 v[32:35], v[152:155], v[168:171], v[32:35]
	v_mfma_f32_16x16x32_bf16 v[20:23], v[144:147], v[192:195], v[20:23]
	v_mfma_f32_16x16x32_bf16 v[16:19], v[152:155], v[192:195], v[16:19]
	v_mfma_f32_16x16x32_bf16 v[4:7], v[144:147], v[200:203], v[4:7]
	v_mfma_f32_16x16x32_bf16 v[0:3], v[152:155], v[200:203], v[0:3]
	v_mfma_f32_16x16x32_bf16 v[52:55], v[148:151], v[164:167], v[52:55]
	v_mfma_f32_16x16x32_bf16 v[48:51], v[156:159], v[164:167], v[48:51]
	v_mfma_f32_16x16x32_bf16 v[36:39], v[148:151], v[172:175], v[36:39]
	v_mfma_f32_16x16x32_bf16 v[32:35], v[156:159], v[172:175], v[32:35]
	v_mfma_f32_16x16x32_bf16 v[20:23], v[148:151], v[196:199], v[20:23]
	v_mfma_f32_16x16x32_bf16 v[16:19], v[156:159], v[196:199], v[16:19]
	v_mfma_f32_16x16x32_bf16 v[4:7], v[148:151], v[212:215], v[4:7]
	v_mfma_f32_16x16x32_bf16 v[0:3], v[156:159], v[212:215], v[0:3]
	s_setprio 0
	s_barrier
	s_add_i32 s26, 0, 0x18000
	s_add_i32 s27, 0, 0x1c000
	v_add_u32_e32 v140, s26, v204
	v_add_u32_e32 v156, s27, v204
	ds_read_b128 v[128:131], v140
	ds_read_b128 v[132:135], v140 offset:1024
	ds_read_b128 v[136:139], v140 offset:2048
	ds_read_b128 v[140:143], v140 offset:3072
	ds_read_b128 v[144:147], v156
	ds_read_b128 v[148:151], v156 offset:1024
	ds_read_b128 v[152:155], v156 offset:2048
	ds_read_b128 v[156:159], v156 offset:3072
	s_add_u32 s4, s54, 0xb0000
	s_addc_u32 s5, s55, 0
	s_mov_b32 m0, s51
	ds_read_b128 v[160:163], v207 offset:32768
	ds_read_b128 v[164:167], v207 offset:33792
	ds_read_b128 v[168:171], v207 offset:34816
	ds_read_b128 v[172:175], v207 offset:35840
	ds_read_b128 v[192:195], v207 offset:36864
	ds_read_b128 v[196:199], v207 offset:37888
	ds_read_b128 v[200:203], v207 offset:38912
	ds_read_b128 v[212:215], v207 offset:39936
	global_load_lds_dwordx4 v176, s[4:5]
	s_mov_b32 m0, s56
	s_nop 0
	global_load_lds_dwordx4 v180, s[4:5]
	s_waitcnt vmcnt(8)
	s_waitcnt lgkmcnt(0)
	s_barrier
	s_setprio 1
	s_waitcnt lgkmcnt(0)
	v_mfma_f32_16x16x32_bf16 v[124:127], v[128:131], v[160:163], v[124:127]
	v_mfma_f32_16x16x32_bf16 v[120:123], v[136:139], v[160:163], v[120:123]
	v_mfma_f32_16x16x32_bf16 v[108:111], v[128:131], v[168:171], v[108:111]
	v_mfma_f32_16x16x32_bf16 v[104:107], v[136:139], v[168:171], v[104:107]
	v_mfma_f32_16x16x32_bf16 v[92:95], v[128:131], v[192:195], v[92:95]
	v_mfma_f32_16x16x32_bf16 v[88:91], v[136:139], v[192:195], v[88:91]
	v_mfma_f32_16x16x32_bf16 v[76:79], v[128:131], v[200:203], v[76:79]
	v_mfma_f32_16x16x32_bf16 v[72:75], v[136:139], v[200:203], v[72:75]
	v_mfma_f32_16x16x32_bf16 v[124:127], v[132:135], v[164:167], v[124:127]
	v_mfma_f32_16x16x32_bf16 v[120:123], v[140:143], v[164:167], v[120:123]
	v_mfma_f32_16x16x32_bf16 v[108:111], v[132:135], v[172:175], v[108:111]
	v_mfma_f32_16x16x32_bf16 v[104:107], v[140:143], v[172:175], v[104:107]
	v_mfma_f32_16x16x32_bf16 v[92:95], v[132:135], v[196:199], v[92:95]
	v_mfma_f32_16x16x32_bf16 v[88:91], v[140:143], v[196:199], v[88:91]
	v_mfma_f32_16x16x32_bf16 v[76:79], v[132:135], v[212:215], v[76:79]
	v_mfma_f32_16x16x32_bf16 v[72:75], v[140:143], v[212:215], v[72:75]
	s_setprio 0
	s_setprio 1
	v_mfma_f32_16x16x32_bf16 v[116:119], v[144:147], v[160:163], v[116:119]
	v_mfma_f32_16x16x32_bf16 v[112:115], v[152:155], v[160:163], v[112:115]
	v_mfma_f32_16x16x32_bf16 v[100:103], v[144:147], v[168:171], v[100:103]
	v_mfma_f32_16x16x32_bf16 v[96:99], v[152:155], v[168:171], v[96:99]
	v_mfma_f32_16x16x32_bf16 v[84:87], v[144:147], v[192:195], v[84:87]
	v_mfma_f32_16x16x32_bf16 v[80:83], v[152:155], v[192:195], v[80:83]
	v_mfma_f32_16x16x32_bf16 v[68:71], v[144:147], v[200:203], v[68:71]
	v_mfma_f32_16x16x32_bf16 v[64:67], v[152:155], v[200:203], v[64:67]
	v_mfma_f32_16x16x32_bf16 v[116:119], v[148:151], v[164:167], v[116:119]
	v_mfma_f32_16x16x32_bf16 v[112:115], v[156:159], v[164:167], v[112:115]
	v_mfma_f32_16x16x32_bf16 v[100:103], v[148:151], v[172:175], v[100:103]
	v_mfma_f32_16x16x32_bf16 v[96:99], v[156:159], v[172:175], v[96:99]
	v_mfma_f32_16x16x32_bf16 v[84:87], v[148:151], v[196:199], v[84:87]
	v_mfma_f32_16x16x32_bf16 v[80:83], v[156:159], v[196:199], v[80:83]
	v_mfma_f32_16x16x32_bf16 v[68:71], v[148:151], v[212:215], v[68:71]
	v_mfma_f32_16x16x32_bf16 v[64:67], v[156:159], v[212:215], v[64:67]
	s_setprio 0
	s_barrier
	s_add_i32 s4, s26, s3
	s_mov_b32 m0, s4
	ds_read_b128 v[160:163], v207 offset:49152
	ds_read_b128 v[164:167], v207 offset:50176
	ds_read_b128 v[168:171], v207 offset:51200
	ds_read_b128 v[172:175], v207 offset:52224
	ds_read_b128 v[192:195], v207 offset:53248
	ds_read_b128 v[196:199], v207 offset:54272
	ds_read_b128 v[200:203], v207 offset:55296
	ds_read_b128 v[212:215], v207 offset:56320
	global_load_lds_dwordx4 v216, s[52:53]
	s_add_i32 m0, s4, 0x2000
	s_add_u32 s4, s52, 0xb0080
	s_addc_u32 s5, s53, 0
	s_add_i32 s26, s27, s3
	global_load_lds_dwordx4 v217, s[52:53]
	s_mov_b32 m0, s26
	s_nop 0
	global_load_lds_dwordx4 v178, s[4:5]
	s_add_i32 m0, s26, 0x2000
	s_nop 0
	global_load_lds_dwordx4 v182, s[4:5]
	s_mov_b32 m0, s60
	s_nop 0
	global_load_lds_dwordx4 v218, s[54:55]
	s_mov_b32 m0, s61
	s_nop 0
	global_load_lds_dwordx4 v219, s[54:55]
	s_waitcnt vmcnt(8)
	s_waitcnt lgkmcnt(0)
	s_barrier
	s_setprio 1
	s_waitcnt lgkmcnt(0)
	v_mfma_f32_16x16x32_bf16 v[60:63], v[128:131], v[160:163], v[60:63]
	v_mfma_f32_16x16x32_bf16 v[56:59], v[136:139], v[160:163], v[56:59]
	v_mfma_f32_16x16x32_bf16 v[44:47], v[128:131], v[168:171], v[44:47]
	v_mfma_f32_16x16x32_bf16 v[40:43], v[136:139], v[168:171], v[40:43]
	v_mfma_f32_16x16x32_bf16 v[28:31], v[128:131], v[192:195], v[28:31]
	v_mfma_f32_16x16x32_bf16 v[24:27], v[136:139], v[192:195], v[24:27]
	v_mfma_f32_16x16x32_bf16 v[12:15], v[128:131], v[200:203], v[12:15]
	v_mfma_f32_16x16x32_bf16 v[8:11], v[136:139], v[200:203], v[8:11]
	v_mfma_f32_16x16x32_bf16 v[60:63], v[132:135], v[164:167], v[60:63]
	v_mfma_f32_16x16x32_bf16 v[56:59], v[140:143], v[164:167], v[56:59]
	v_mfma_f32_16x16x32_bf16 v[44:47], v[132:135], v[172:175], v[44:47]
	v_mfma_f32_16x16x32_bf16 v[40:43], v[140:143], v[172:175], v[40:43]
	v_mfma_f32_16x16x32_bf16 v[28:31], v[132:135], v[196:199], v[28:31]
	v_mfma_f32_16x16x32_bf16 v[24:27], v[140:143], v[196:199], v[24:27]
	v_mfma_f32_16x16x32_bf16 v[12:15], v[132:135], v[212:215], v[12:15]
	v_mfma_f32_16x16x32_bf16 v[8:11], v[140:143], v[212:215], v[8:11]
	s_setprio 0
	s_setprio 1
	v_mfma_f32_16x16x32_bf16 v[52:55], v[144:147], v[160:163], v[52:55]
	v_mfma_f32_16x16x32_bf16 v[48:51], v[152:155], v[160:163], v[48:51]
	v_mfma_f32_16x16x32_bf16 v[36:39], v[144:147], v[168:171], v[36:39]
	v_mfma_f32_16x16x32_bf16 v[32:35], v[152:155], v[168:171], v[32:35]
	v_mfma_f32_16x16x32_bf16 v[20:23], v[144:147], v[192:195], v[20:23]
	v_mfma_f32_16x16x32_bf16 v[16:19], v[152:155], v[192:195], v[16:19]
	v_mfma_f32_16x16x32_bf16 v[4:7], v[144:147], v[200:203], v[4:7]
	v_mfma_f32_16x16x32_bf16 v[0:3], v[152:155], v[200:203], v[0:3]
	v_mfma_f32_16x16x32_bf16 v[52:55], v[148:151], v[164:167], v[52:55]
	v_mfma_f32_16x16x32_bf16 v[48:51], v[156:159], v[164:167], v[48:51]
	v_mfma_f32_16x16x32_bf16 v[36:39], v[148:151], v[172:175], v[36:39]
	v_mfma_f32_16x16x32_bf16 v[32:35], v[156:159], v[172:175], v[32:35]
	v_mfma_f32_16x16x32_bf16 v[20:23], v[148:151], v[196:199], v[20:23]
	v_mfma_f32_16x16x32_bf16 v[16:19], v[156:159], v[196:199], v[16:19]
	v_mfma_f32_16x16x32_bf16 v[4:7], v[148:151], v[212:215], v[4:7]
	v_mfma_f32_16x16x32_bf16 v[0:3], v[156:159], v[212:215], v[0:3]
	s_setprio 0
	s_barrier
	s_add_i32 s73, s73, 2
	s_add_u32 s71, s71, 0x100
	s_addc_u32 s72, s72, 0
	s_cmp_gt_u32 s73, 41
	s_mov_b64 s[46:47], s[48:49]
	s_cbranch_scc0 .LBB0_299
	s_and_b64 vcc, exec, s[22:23]
	s_cbranch_vccz .LBB0_302
	s_barrier

.LBB0_394:
	v_add_u32_e32 v208, 0x80, v128
	v_add_u32_e32 v209, 0x80, v130
	ds_read_b128 v[144:147], v172
	ds_read_b128 v[148:151], v172 offset:1024
	ds_read_b128 v[152:155], v172 offset:2048
	ds_read_b128 v[156:159], v172 offset:3072
	ds_read_b128 v[160:163], v173
	ds_read_b128 v[164:167], v173 offset:1024
	ds_read_b128 v[168:171], v173 offset:2048
	ds_read_b128 v[176:179], v173 offset:3072
	s_add_u32 s4, s10, 0xfffc0080
	s_addc_u32 s5, s11, -1
	s_cmp_eq_u32 s73, 12
	s_cselect_b32 s15, s9, s5
	s_cselect_b32 s14, s16, s4
	s_cselect_b32 s13, s17, s71
	s_cselect_b32 s12, s24, s51
	s_add_i32 m0, s69, 0xc000
	ds_read_b128 v[180:183], v174
	ds_read_b128 v[184:187], v174 offset:1024
	ds_read_b128 v[188:191], v174 offset:2048
	ds_read_b128 v[192:195], v174 offset:3072
	ds_read_b128 v[196:199], v174 offset:4096
	ds_read_b128 v[200:203], v174 offset:5120
	ds_read_b128 v[204:207], v174 offset:6144
	ds_read_b128 v[212:215], v174 offset:7168
	global_load_lds_dwordx4 v134, s[10:11]
	s_add_i32 m0, s69, 0xe000
	s_nop 0
	global_load_lds_dwordx4 v136, s[10:11]
	s_waitcnt vmcnt(8)
	s_waitcnt lgkmcnt(0)
	s_barrier
	s_setprio 1
	s_waitcnt lgkmcnt(0)
	v_mfma_f32_16x16x32_bf16 v[124:127], v[144:147], v[180:183], v[124:127]
	v_mfma_f32_16x16x32_bf16 v[120:123], v[152:155], v[180:183], v[120:123]
	v_mfma_f32_16x16x32_bf16 v[108:111], v[144:147], v[188:191], v[108:111]
	v_mfma_f32_16x16x32_bf16 v[104:107], v[152:155], v[188:191], v[104:107]
	v_mfma_f32_16x16x32_bf16 v[92:95], v[144:147], v[196:199], v[92:95]
	v_mfma_f32_16x16x32_bf16 v[88:91], v[152:155], v[196:199], v[88:91]
	v_mfma_f32_16x16x32_bf16 v[76:79], v[144:147], v[204:207], v[76:79]
	v_mfma_f32_16x16x32_bf16 v[72:75], v[152:155], v[204:207], v[72:75]
	v_mfma_f32_16x16x32_bf16 v[124:127], v[148:151], v[184:187], v[124:127]
	v_mfma_f32_16x16x32_bf16 v[120:123], v[156:159], v[184:187], v[120:123]
	v_mfma_f32_16x16x32_bf16 v[108:111], v[148:151], v[192:195], v[108:111]
	v_mfma_f32_16x16x32_bf16 v[104:107], v[156:159], v[192:195], v[104:107]
	v_mfma_f32_16x16x32_bf16 v[92:95], v[148:151], v[200:203], v[92:95]
	v_mfma_f32_16x16x32_bf16 v[88:91], v[156:159], v[200:203], v[88:91]
	v_mfma_f32_16x16x32_bf16 v[76:79], v[148:151], v[212:215], v[76:79]
	v_mfma_f32_16x16x32_bf16 v[72:75], v[156:159], v[212:215], v[72:75]
	s_setprio 0
	s_setprio 1
	v_mfma_f32_16x16x32_bf16 v[116:119], v[160:163], v[180:183], v[116:119]
	v_mfma_f32_16x16x32_bf16 v[112:115], v[168:171], v[180:183], v[112:115]
	v_mfma_f32_16x16x32_bf16 v[100:103], v[160:163], v[188:191], v[100:103]
	v_mfma_f32_16x16x32_bf16 v[96:99], v[168:171], v[188:191], v[96:99]
	v_mfma_f32_16x16x32_bf16 v[84:87], v[160:163], v[196:199], v[84:87]
	v_mfma_f32_16x16x32_bf16 v[80:83], v[168:171], v[196:199], v[80:83]
	v_mfma_f32_16x16x32_bf16 v[68:71], v[160:163], v[204:207], v[68:71]
	v_mfma_f32_16x16x32_bf16 v[64:67], v[168:171], v[204:207], v[64:67]
	v_mfma_f32_16x16x32_bf16 v[116:119], v[164:167], v[184:187], v[116:119]
	v_mfma_f32_16x16x32_bf16 v[112:115], v[176:179], v[184:187], v[112:115]
	v_mfma_f32_16x16x32_bf16 v[100:103], v[164:167], v[192:195], v[100:103]
	v_mfma_f32_16x16x32_bf16 v[96:99], v[176:179], v[192:195], v[96:99]
	v_mfma_f32_16x16x32_bf16 v[84:87], v[164:167], v[200:203], v[84:87]
	v_mfma_f32_16x16x32_bf16 v[80:83], v[176:179], v[200:203], v[80:83]
	v_mfma_f32_16x16x32_bf16 v[68:71], v[164:167], v[212:215], v[68:71]
	v_mfma_f32_16x16x32_bf16 v[64:67], v[176:179], v[212:215], v[64:67]
	s_setprio 0
	s_barrier
	s_add_i32 s4, s96, s3
	s_mov_b32 m0, s4
	ds_read_b128 v[180:183], v174 offset:16384
	ds_read_b128 v[184:187], v174 offset:17408
	ds_read_b128 v[188:191], v174 offset:18432
	ds_read_b128 v[192:195], v174 offset:19456
	ds_read_b128 v[196:199], v174 offset:20480
	ds_read_b128 v[200:203], v174 offset:21504
	ds_read_b128 v[204:207], v174 offset:22528
	ds_read_b128 v[212:215], v174 offset:23552
	global_load_lds_dwordx4 v128, s[12:13]
	s_add_i32 m0, s4, 0x2000
	s_add_u32 s4, s12, 0x40000
	s_mov_b64 s[98:99], s[12:13]
	s_addc_u32 s5, s13, 0
	s_add_i32 s26, s97, s3
	global_load_lds_dwordx4 v130, s[98:99]
	s_mov_b32 m0, s26
	s_nop 0
	global_load_lds_dwordx4 v128, s[4:5]
	s_add_i32 m0, s26, 0x2000
	s_nop 0
	global_load_lds_dwordx4 v130, s[4:5]
	s_mov_b32 m0, s69
	s_nop 0
	global_load_lds_dwordx4 v128, s[14:15]
	s_mov_b32 m0, s82
	s_nop 0
	global_load_lds_dwordx4 v130, s[14:15]
	s_waitcnt vmcnt(8)
	s_waitcnt lgkmcnt(0)
	s_barrier
	s_setprio 1
	s_waitcnt lgkmcnt(0)
	v_mfma_f32_16x16x32_bf16 v[60:63], v[144:147], v[180:183], v[60:63]
	v_mfma_f32_16x16x32_bf16 v[56:59], v[152:155], v[180:183], v[56:59]
	v_mfma_f32_16x16x32_bf16 v[44:47], v[144:147], v[188:191], v[44:47]
	v_mfma_f32_16x16x32_bf16 v[40:43], v[152:155], v[188:191], v[40:43]
	v_mfma_f32_16x16x32_bf16 v[28:31], v[144:147], v[196:199], v[28:31]
	v_mfma_f32_16x16x32_bf16 v[24:27], v[152:155], v[196:199], v[24:27]
	v_mfma_f32_16x16x32_bf16 v[12:15], v[144:147], v[204:207], v[12:15]
	v_mfma_f32_16x16x32_bf16 v[8:11], v[152:155], v[204:207], v[8:11]
	v_mfma_f32_16x16x32_bf16 v[60:63], v[148:151], v[184:187], v[60:63]
	v_mfma_f32_16x16x32_bf16 v[56:59], v[156:159], v[184:187], v[56:59]
	v_mfma_f32_16x16x32_bf16 v[44:47], v[148:151], v[192:195], v[44:47]
	v_mfma_f32_16x16x32_bf16 v[40:43], v[156:159], v[192:195], v[40:43]
	v_mfma_f32_16x16x32_bf16 v[28:31], v[148:151], v[200:203], v[28:31]
	v_mfma_f32_16x16x32_bf16 v[24:27], v[156:159], v[200:203], v[24:27]
	v_mfma_f32_16x16x32_bf16 v[12:15], v[148:151], v[212:215], v[12:15]
	v_mfma_f32_16x16x32_bf16 v[8:11], v[156:159], v[212:215], v[8:11]
	s_setprio 0
	s_setprio 1
	v_mfma_f32_16x16x32_bf16 v[52:55], v[160:163], v[180:183], v[52:55]
	v_mfma_f32_16x16x32_bf16 v[48:51], v[168:171], v[180:183], v[48:51]
	v_mfma_f32_16x16x32_bf16 v[36:39], v[160:163], v[188:191], v[36:39]
	v_mfma_f32_16x16x32_bf16 v[32:35], v[168:171], v[188:191], v[32:35]
	v_mfma_f32_16x16x32_bf16 v[20:23], v[160:163], v[196:199], v[20:23]
	v_mfma_f32_16x16x32_bf16 v[16:19], v[168:171], v[196:199], v[16:19]
	v_mfma_f32_16x16x32_bf16 v[4:7], v[160:163], v[204:207], v[4:7]
	v_mfma_f32_16x16x32_bf16 v[0:3], v[168:171], v[204:207], v[0:3]
	v_mfma_f32_16x16x32_bf16 v[52:55], v[164:167], v[184:187], v[52:55]
	v_mfma_f32_16x16x32_bf16 v[48:51], v[176:179], v[184:187], v[48:51]
	v_mfma_f32_16x16x32_bf16 v[36:39], v[164:167], v[192:195], v[36:39]
	v_mfma_f32_16x16x32_bf16 v[32:35], v[176:179], v[192:195], v[32:35]
	v_mfma_f32_16x16x32_bf16 v[20:23], v[164:167], v[200:203], v[20:23]
	v_mfma_f32_16x16x32_bf16 v[16:19], v[176:179], v[200:203], v[16:19]
	v_mfma_f32_16x16x32_bf16 v[4:7], v[164:167], v[212:215], v[4:7]
	v_mfma_f32_16x16x32_bf16 v[0:3], v[176:179], v[212:215], v[0:3]
	s_setprio 0
	s_barrier
	s_add_i32 s26, 0, 0x18000
	v_add_u32_e32 v132, s26, v143
	s_add_i32 s27, 0, 0x1c000
	ds_read_b128 v[144:147], v132
	ds_read_b128 v[148:151], v132 offset:1024
	ds_read_b128 v[152:155], v132 offset:2048
	ds_read_b128 v[156:159], v132 offset:3072
	v_add_u32_e32 v132, s27, v143
	ds_read_b128 v[160:163], v132
	ds_read_b128 v[164:167], v132 offset:1024
	ds_read_b128 v[168:171], v132 offset:2048
	ds_read_b128 v[176:179], v132 offset:3072
	s_add_u32 s4, s14, 0x40000
	s_addc_u32 s5, s15, 0
	s_mov_b32 m0, s83
	ds_read_b128 v[180:183], v174 offset:32768
	ds_read_b128 v[184:187], v174 offset:33792
	ds_read_b128 v[188:191], v174 offset:34816
	ds_read_b128 v[192:195], v174 offset:35840
	ds_read_b128 v[196:199], v174 offset:36864
	ds_read_b128 v[200:203], v174 offset:37888
	ds_read_b128 v[204:207], v174 offset:38912
	ds_read_b128 v[212:215], v174 offset:39936
	global_load_lds_dwordx4 v128, s[4:5]
	s_mov_b32 m0, s85
	s_nop 0
	global_load_lds_dwordx4 v130, s[4:5]
	s_waitcnt vmcnt(8)
	s_waitcnt lgkmcnt(0)
	s_barrier
	s_setprio 1
	s_waitcnt lgkmcnt(0)
	v_mfma_f32_16x16x32_bf16 v[124:127], v[144:147], v[180:183], v[124:127]
	v_mfma_f32_16x16x32_bf16 v[120:123], v[152:155], v[180:183], v[120:123]
	v_mfma_f32_16x16x32_bf16 v[108:111], v[144:147], v[188:191], v[108:111]
	v_mfma_f32_16x16x32_bf16 v[104:107], v[152:155], v[188:191], v[104:107]
	v_mfma_f32_16x16x32_bf16 v[92:95], v[144:147], v[196:199], v[92:95]
	v_mfma_f32_16x16x32_bf16 v[88:91], v[152:155], v[196:199], v[88:91]
	v_mfma_f32_16x16x32_bf16 v[76:79], v[144:147], v[204:207], v[76:79]
	v_mfma_f32_16x16x32_bf16 v[72:75], v[152:155], v[204:207], v[72:75]
	v_mfma_f32_16x16x32_bf16 v[124:127], v[148:151], v[184:187], v[124:127]
	v_mfma_f32_16x16x32_bf16 v[120:123], v[156:159], v[184:187], v[120:123]
	v_mfma_f32_16x16x32_bf16 v[108:111], v[148:151], v[192:195], v[108:111]
	v_mfma_f32_16x16x32_bf16 v[104:107], v[156:159], v[192:195], v[104:107]
	v_mfma_f32_16x16x32_bf16 v[92:95], v[148:151], v[200:203], v[92:95]
	v_mfma_f32_16x16x32_bf16 v[88:91], v[156:159], v[200:203], v[88:91]
	v_mfma_f32_16x16x32_bf16 v[76:79], v[148:151], v[212:215], v[76:79]
	v_mfma_f32_16x16x32_bf16 v[72:75], v[156:159], v[212:215], v[72:75]
	s_setprio 0
	s_setprio 1
	v_mfma_f32_16x16x32_bf16 v[116:119], v[160:163], v[180:183], v[116:119]
	v_mfma_f32_16x16x32_bf16 v[112:115], v[168:171], v[180:183], v[112:115]
	v_mfma_f32_16x16x32_bf16 v[100:103], v[160:163], v[188:191], v[100:103]
	v_mfma_f32_16x16x32_bf16 v[96:99], v[168:171], v[188:191], v[96:99]
	v_mfma_f32_16x16x32_bf16 v[84:87], v[160:163], v[196:199], v[84:87]
	v_mfma_f32_16x16x32_bf16 v[80:83], v[168:171], v[196:199], v[80:83]
	v_mfma_f32_16x16x32_bf16 v[68:71], v[160:163], v[204:207], v[68:71]
	v_mfma_f32_16x16x32_bf16 v[64:67], v[168:171], v[204:207], v[64:67]
	v_mfma_f32_16x16x32_bf16 v[116:119], v[164:167], v[184:187], v[116:119]
	v_mfma_f32_16x16x32_bf16 v[112:115], v[176:179], v[184:187], v[112:115]
	v_mfma_f32_16x16x32_bf16 v[100:103], v[164:167], v[192:195], v[100:103]
	v_mfma_f32_16x16x32_bf16 v[96:99], v[176:179], v[192:195], v[96:99]
	v_mfma_f32_16x16x32_bf16 v[84:87], v[164:167], v[200:203], v[84:87]
	v_mfma_f32_16x16x32_bf16 v[80:83], v[176:179], v[200:203], v[80:83]
	v_mfma_f32_16x16x32_bf16 v[68:71], v[164:167], v[212:215], v[68:71]
	v_mfma_f32_16x16x32_bf16 v[64:67], v[176:179], v[212:215], v[64:67]
	s_setprio 0
	s_barrier
	s_add_i32 s4, s26, s3
	s_mov_b32 m0, s4
	ds_read_b128 v[180:183], v174 offset:49152
	ds_read_b128 v[184:187], v174 offset:50176
	ds_read_b128 v[188:191], v174 offset:51200
	ds_read_b128 v[192:195], v174 offset:52224
	ds_read_b128 v[196:199], v174 offset:53248
	ds_read_b128 v[200:203], v174 offset:54272
	ds_read_b128 v[204:207], v174 offset:55296
	ds_read_b128 v[212:215], v174 offset:56320
	global_load_lds_dwordx4 v208, s[12:13]
	s_add_i32 m0, s4, 0x2000
	s_add_u32 s4, s12, 0x40080
	s_addc_u32 s5, s13, 0
	s_add_i32 s12, s27, s3
	global_load_lds_dwordx4 v209, s[98:99]
	s_mov_b32 m0, s12
	s_nop 0
	global_load_lds_dwordx4 v128, s[4:5]
	s_add_i32 m0, s12, 0x2000
	s_nop 0
	global_load_lds_dwordx4 v130, s[4:5]
	s_mov_b32 m0, s91
	s_nop 0
	global_load_lds_dwordx4 v208, s[14:15]
	s_mov_b32 m0, s92
	s_nop 0
	global_load_lds_dwordx4 v209, s[14:15]
	s_waitcnt vmcnt(8)
	s_waitcnt lgkmcnt(0)
	s_barrier
	s_setprio 1
	s_waitcnt lgkmcnt(0)
	v_mfma_f32_16x16x32_bf16 v[60:63], v[144:147], v[180:183], v[60:63]
	v_mfma_f32_16x16x32_bf16 v[56:59], v[152:155], v[180:183], v[56:59]
	v_mfma_f32_16x16x32_bf16 v[44:47], v[144:147], v[188:191], v[44:47]
	v_mfma_f32_16x16x32_bf16 v[40:43], v[152:155], v[188:191], v[40:43]
	v_mfma_f32_16x16x32_bf16 v[28:31], v[144:147], v[196:199], v[28:31]
	v_mfma_f32_16x16x32_bf16 v[24:27], v[152:155], v[196:199], v[24:27]
	v_mfma_f32_16x16x32_bf16 v[12:15], v[144:147], v[204:207], v[12:15]
	v_mfma_f32_16x16x32_bf16 v[8:11], v[152:155], v[204:207], v[8:11]
	v_mfma_f32_16x16x32_bf16 v[60:63], v[148:151], v[184:187], v[60:63]
	v_mfma_f32_16x16x32_bf16 v[56:59], v[156:159], v[184:187], v[56:59]
	v_mfma_f32_16x16x32_bf16 v[44:47], v[148:151], v[192:195], v[44:47]
	v_mfma_f32_16x16x32_bf16 v[40:43], v[156:159], v[192:195], v[40:43]
	v_mfma_f32_16x16x32_bf16 v[28:31], v[148:151], v[200:203], v[28:31]
	v_mfma_f32_16x16x32_bf16 v[24:27], v[156:159], v[200:203], v[24:27]
	v_mfma_f32_16x16x32_bf16 v[12:15], v[148:151], v[212:215], v[12:15]
	v_mfma_f32_16x16x32_bf16 v[8:11], v[156:159], v[212:215], v[8:11]
	s_setprio 0
	s_setprio 1
	v_mfma_f32_16x16x32_bf16 v[52:55], v[160:163], v[180:183], v[52:55]
	v_mfma_f32_16x16x32_bf16 v[48:51], v[168:171], v[180:183], v[48:51]
	v_mfma_f32_16x16x32_bf16 v[36:39], v[160:163], v[188:191], v[36:39]
	v_mfma_f32_16x16x32_bf16 v[32:35], v[168:171], v[188:191], v[32:35]
	v_mfma_f32_16x16x32_bf16 v[20:23], v[160:163], v[196:199], v[20:23]
	v_mfma_f32_16x16x32_bf16 v[16:19], v[168:171], v[196:199], v[16:19]
	v_mfma_f32_16x16x32_bf16 v[4:7], v[160:163], v[204:207], v[4:7]
	v_mfma_f32_16x16x32_bf16 v[0:3], v[168:171], v[204:207], v[0:3]
	v_mfma_f32_16x16x32_bf16 v[52:55], v[164:167], v[184:187], v[52:55]
	v_mfma_f32_16x16x32_bf16 v[48:51], v[176:179], v[184:187], v[48:51]
	v_mfma_f32_16x16x32_bf16 v[36:39], v[164:167], v[192:195], v[36:39]
	v_mfma_f32_16x16x32_bf16 v[32:35], v[176:179], v[192:195], v[32:35]
	v_mfma_f32_16x16x32_bf16 v[20:23], v[164:167], v[200:203], v[20:23]
	v_mfma_f32_16x16x32_bf16 v[16:19], v[176:179], v[200:203], v[16:19]
	v_mfma_f32_16x16x32_bf16 v[4:7], v[164:167], v[212:215], v[4:7]
	v_mfma_f32_16x16x32_bf16 v[0:3], v[176:179], v[212:215], v[0:3]
	s_setprio 0
	s_barrier
	s_add_i32 s73, s73, 2
	s_add_u32 s10, s10, 0x100
	s_addc_u32 s11, s11, 0
	s_add_u32 s51, s51, 0x100
	s_addc_u32 s71, s71, 0
	s_cmp_gt_u32 s73, 13
	s_cbranch_scc0 .LBB0_394
	s_and_b64 vcc, exec, s[62:63]
	s_cbranch_vccz .LBB0_397
	s_barrier

.LBB0_801:
	v_add_u32_e32 v142, 0x80, v130
	v_add_u32_e32 v143, 0x80, v134
	v_add_u32_e32 v216, 0x80, v128
	v_add_u32_e32 v217, 0x80, v132
	s_add_u32 s24, s64, s70
	s_addc_u32 s25, s65, 0
	s_add_u32 s27, s24, 0x100
	s_addc_u32 s50, s25, 0
	s_and_b64 s[4:5], s[68:69], exec
	s_cselect_b32 s73, s19, s50
	s_cselect_b32 s72, s94, s27
	s_add_u32 s4, s62, s70
	s_addc_u32 s5, s63, 0
	s_add_u32 s27, s4, 0x100
	s_addc_u32 s50, s5, 0
	s_and_b64 s[4:5], s[68:69], exec
	s_cselect_b32 s75, s17, s50
	s_cselect_b32 s74, s95, s27
	s_add_u32 s78, s24, 0x10080
	ds_read_b128 v[150:153], v145
	ds_read_b128 v[154:157], v145 offset:1024
	ds_read_b128 v[158:161], v145 offset:2048
	ds_read_b128 v[162:165], v145 offset:3072
	ds_read_b128 v[166:169], v146
	ds_read_b128 v[170:173], v146 offset:1024
	ds_read_b128 v[174:177], v146 offset:2048
	ds_read_b128 v[178:181], v146 offset:3072
	s_addc_u32 s79, s25, 0
	s_add_i32 s5, s91, s47
	s_add_i32 m0, s26, 0xc000
	s_add_i32 s50, s26, 0xe000
	s_add_i32 s52, s5, 0x2000
	s_add_u32 s76, s74, 0x10000
	s_addc_u32 s77, s75, 0
	s_add_i32 s53, s92, s47
	s_add_i32 s4, s53, 0x2000
	s_add_i32 s25, 0, 0x18000
	s_add_i32 vcc_lo, 0, 0x1c000
	s_add_u32 s70, s72, 0x10000
	s_addc_u32 s71, s73, 0
	s_add_i32 vcc_hi, s25, s47
	s_add_i32 s97, vcc_hi, 0x2000
	s_add_u32 s68, s74, 0x10080
	s_addc_u32 s69, s75, 0
	s_add_i32 s96, vcc_lo, s47
	s_add_i32 s24, s96, 0x2000
	ds_read_b128 v[182:185], v147
	ds_read_b128 v[186:189], v147 offset:1024
	ds_read_b128 v[190:193], v147 offset:2048
	ds_read_b128 v[194:197], v147 offset:3072
	ds_read_b128 v[198:201], v147 offset:4096
	ds_read_b128 v[202:205], v147 offset:5120
	ds_read_b128 v[206:209], v147 offset:6144
	ds_read_b128 v[212:215], v147 offset:7168
	global_load_lds_dwordx4 v128, s[78:79]
	s_mov_b32 m0, s50
	s_nop 0
	global_load_lds_dwordx4 v132, s[78:79]
	s_waitcnt vmcnt(8)
	s_waitcnt lgkmcnt(0)
	s_barrier
	s_setprio 1
	s_waitcnt lgkmcnt(0)
	v_mfma_f32_16x16x32_bf16 v[124:127], v[150:153], v[182:185], v[124:127]
	v_mfma_f32_16x16x32_bf16 v[120:123], v[158:161], v[182:185], v[120:123]
	v_mfma_f32_16x16x32_bf16 v[116:119], v[150:153], v[190:193], v[116:119]
	v_mfma_f32_16x16x32_bf16 v[112:115], v[158:161], v[190:193], v[112:115]
	v_mfma_f32_16x16x32_bf16 v[96:99], v[150:153], v[198:201], v[96:99]
	v_mfma_f32_16x16x32_bf16 v[92:95], v[158:161], v[198:201], v[92:95]
	v_mfma_f32_16x16x32_bf16 v[84:87], v[150:153], v[206:209], v[84:87]
	v_mfma_f32_16x16x32_bf16 v[76:79], v[158:161], v[206:209], v[76:79]
	v_mfma_f32_16x16x32_bf16 v[124:127], v[154:157], v[186:189], v[124:127]
	v_mfma_f32_16x16x32_bf16 v[120:123], v[162:165], v[186:189], v[120:123]
	v_mfma_f32_16x16x32_bf16 v[116:119], v[154:157], v[194:197], v[116:119]
	v_mfma_f32_16x16x32_bf16 v[112:115], v[162:165], v[194:197], v[112:115]
	v_mfma_f32_16x16x32_bf16 v[96:99], v[154:157], v[202:205], v[96:99]
	v_mfma_f32_16x16x32_bf16 v[92:95], v[162:165], v[202:205], v[92:95]
	v_mfma_f32_16x16x32_bf16 v[84:87], v[154:157], v[212:215], v[84:87]
	v_mfma_f32_16x16x32_bf16 v[76:79], v[162:165], v[212:215], v[76:79]
	s_setprio 0
	s_setprio 1
	v_mfma_f32_16x16x32_bf16 v[108:111], v[166:169], v[182:185], v[108:111]
	v_mfma_f32_16x16x32_bf16 v[104:107], v[174:177], v[182:185], v[104:107]
	v_mfma_f32_16x16x32_bf16 v[100:103], v[166:169], v[190:193], v[100:103]
	v_mfma_f32_16x16x32_bf16 v[88:91], v[174:177], v[190:193], v[88:91]
	v_mfma_f32_16x16x32_bf16 v[80:83], v[166:169], v[198:201], v[80:83]
	v_mfma_f32_16x16x32_bf16 v[72:75], v[174:177], v[198:201], v[72:75]
	v_mfma_f32_16x16x32_bf16 v[68:71], v[166:169], v[206:209], v[68:71]
	v_mfma_f32_16x16x32_bf16 v[64:67], v[174:177], v[206:209], v[64:67]
	v_mfma_f32_16x16x32_bf16 v[108:111], v[170:173], v[186:189], v[108:111]
	v_mfma_f32_16x16x32_bf16 v[104:107], v[178:181], v[186:189], v[104:107]
	v_mfma_f32_16x16x32_bf16 v[100:103], v[170:173], v[194:197], v[100:103]
	v_mfma_f32_16x16x32_bf16 v[88:91], v[178:181], v[194:197], v[88:91]
	v_mfma_f32_16x16x32_bf16 v[80:83], v[170:173], v[202:205], v[80:83]
	v_mfma_f32_16x16x32_bf16 v[72:75], v[178:181], v[202:205], v[72:75]
	v_mfma_f32_16x16x32_bf16 v[68:71], v[170:173], v[212:215], v[68:71]
	v_mfma_f32_16x16x32_bf16 v[64:67], v[178:181], v[212:215], v[64:67]
	s_setprio 0
	s_barrier
	s_mov_b32 m0, s5
	ds_read_b128 v[182:185], v147 offset:16384
	ds_read_b128 v[186:189], v147 offset:17408
	ds_read_b128 v[190:193], v147 offset:18432
	ds_read_b128 v[194:197], v147 offset:19456
	ds_read_b128 v[198:201], v147 offset:20480
	ds_read_b128 v[202:205], v147 offset:21504
	ds_read_b128 v[206:209], v147 offset:22528
	ds_read_b128 v[212:215], v147 offset:23552
	global_load_lds_dwordx4 v130, s[74:75]
	s_mov_b32 m0, s52
	s_nop 0
	global_load_lds_dwordx4 v134, s[74:75]
	s_mov_b32 m0, s53
	s_nop 0
	global_load_lds_dwordx4 v130, s[76:77]
	s_mov_b32 m0, s4
	s_nop 0
	global_load_lds_dwordx4 v134, s[76:77]
	s_mov_b32 m0, s26
	s_nop 0
	global_load_lds_dwordx4 v128, s[72:73]
	s_mov_b32 m0, s51
	s_nop 0
	global_load_lds_dwordx4 v132, s[72:73]
	s_waitcnt vmcnt(8)
	s_waitcnt lgkmcnt(0)
	s_barrier
	s_setprio 1
	s_waitcnt lgkmcnt(0)
	v_mfma_f32_16x16x32_bf16 v[60:63], v[150:153], v[182:185], v[60:63]
	v_mfma_f32_16x16x32_bf16 v[56:59], v[158:161], v[182:185], v[56:59]
	v_mfma_f32_16x16x32_bf16 v[52:55], v[150:153], v[190:193], v[52:55]
	v_mfma_f32_16x16x32_bf16 v[44:47], v[158:161], v[190:193], v[44:47]
	v_mfma_f32_16x16x32_bf16 v[36:39], v[150:153], v[198:201], v[36:39]
	v_mfma_f32_16x16x32_bf16 v[28:31], v[158:161], v[198:201], v[28:31]
	v_mfma_f32_16x16x32_bf16 v[20:23], v[150:153], v[206:209], v[20:23]
	v_mfma_f32_16x16x32_bf16 v[12:15], v[158:161], v[206:209], v[12:15]
	v_mfma_f32_16x16x32_bf16 v[60:63], v[154:157], v[186:189], v[60:63]
	v_mfma_f32_16x16x32_bf16 v[56:59], v[162:165], v[186:189], v[56:59]
	v_mfma_f32_16x16x32_bf16 v[52:55], v[154:157], v[194:197], v[52:55]
	v_mfma_f32_16x16x32_bf16 v[44:47], v[162:165], v[194:197], v[44:47]
	v_mfma_f32_16x16x32_bf16 v[36:39], v[154:157], v[202:205], v[36:39]
	v_mfma_f32_16x16x32_bf16 v[28:31], v[162:165], v[202:205], v[28:31]
	v_mfma_f32_16x16x32_bf16 v[20:23], v[154:157], v[212:215], v[20:23]
	v_mfma_f32_16x16x32_bf16 v[12:15], v[162:165], v[212:215], v[12:15]
	s_setprio 0
	s_setprio 1
	v_mfma_f32_16x16x32_bf16 v[48:51], v[166:169], v[182:185], v[48:51]
	v_mfma_f32_16x16x32_bf16 v[40:43], v[174:177], v[182:185], v[40:43]
	v_mfma_f32_16x16x32_bf16 v[32:35], v[166:169], v[190:193], v[32:35]
	v_mfma_f32_16x16x32_bf16 v[24:27], v[174:177], v[190:193], v[24:27]
	v_mfma_f32_16x16x32_bf16 v[16:19], v[166:169], v[198:201], v[16:19]
	v_mfma_f32_16x16x32_bf16 v[8:11], v[174:177], v[198:201], v[8:11]
	v_mfma_f32_16x16x32_bf16 v[4:7], v[166:169], v[206:209], v[4:7]
	v_mfma_f32_16x16x32_bf16 v[0:3], v[174:177], v[206:209], v[0:3]
	v_mfma_f32_16x16x32_bf16 v[48:51], v[170:173], v[186:189], v[48:51]
	v_mfma_f32_16x16x32_bf16 v[40:43], v[178:181], v[186:189], v[40:43]
	v_mfma_f32_16x16x32_bf16 v[32:35], v[170:173], v[194:197], v[32:35]
	v_mfma_f32_16x16x32_bf16 v[24:27], v[178:181], v[194:197], v[24:27]
	v_mfma_f32_16x16x32_bf16 v[16:19], v[170:173], v[202:205], v[16:19]
	v_mfma_f32_16x16x32_bf16 v[8:11], v[178:181], v[202:205], v[8:11]
	v_mfma_f32_16x16x32_bf16 v[4:7], v[170:173], v[212:215], v[4:7]
	v_mfma_f32_16x16x32_bf16 v[0:3], v[178:181], v[212:215], v[0:3]
	s_setprio 0
	s_barrier
	v_add_u32_e32 v144, s25, v141
	ds_read_b128 v[150:153], v144
	ds_read_b128 v[154:157], v144 offset:1024
	ds_read_b128 v[158:161], v144 offset:2048
	ds_read_b128 v[162:165], v144 offset:3072
	v_add_u32_e32 v144, vcc_lo, v141
	ds_read_b128 v[166:169], v144
	ds_read_b128 v[170:173], v144 offset:1024
	ds_read_b128 v[174:177], v144 offset:2048
	ds_read_b128 v[178:181], v144 offset:3072
	s_mov_b32 m0, s80
	ds_read_b128 v[182:185], v147 offset:32768
	ds_read_b128 v[186:189], v147 offset:33792
	ds_read_b128 v[190:193], v147 offset:34816
	ds_read_b128 v[194:197], v147 offset:35840
	ds_read_b128 v[198:201], v147 offset:36864
	ds_read_b128 v[202:205], v147 offset:37888
	ds_read_b128 v[206:209], v147 offset:38912
	ds_read_b128 v[212:215], v147 offset:39936
	global_load_lds_dwordx4 v128, s[70:71]
	s_mov_b32 m0, s81
	s_nop 0
	global_load_lds_dwordx4 v132, s[70:71]
	s_waitcnt vmcnt(8)
	s_waitcnt lgkmcnt(0)
	s_barrier
	s_setprio 1
	s_waitcnt lgkmcnt(0)
	v_mfma_f32_16x16x32_bf16 v[124:127], v[150:153], v[182:185], v[124:127]
	v_mfma_f32_16x16x32_bf16 v[120:123], v[158:161], v[182:185], v[120:123]
	v_mfma_f32_16x16x32_bf16 v[116:119], v[150:153], v[190:193], v[116:119]
	v_mfma_f32_16x16x32_bf16 v[112:115], v[158:161], v[190:193], v[112:115]
	v_mfma_f32_16x16x32_bf16 v[96:99], v[150:153], v[198:201], v[96:99]
	v_mfma_f32_16x16x32_bf16 v[92:95], v[158:161], v[198:201], v[92:95]
	v_mfma_f32_16x16x32_bf16 v[84:87], v[150:153], v[206:209], v[84:87]
	v_mfma_f32_16x16x32_bf16 v[76:79], v[158:161], v[206:209], v[76:79]
	v_mfma_f32_16x16x32_bf16 v[124:127], v[154:157], v[186:189], v[124:127]
	v_mfma_f32_16x16x32_bf16 v[120:123], v[162:165], v[186:189], v[120:123]
	v_mfma_f32_16x16x32_bf16 v[116:119], v[154:157], v[194:197], v[116:119]
	v_mfma_f32_16x16x32_bf16 v[112:115], v[162:165], v[194:197], v[112:115]
	v_mfma_f32_16x16x32_bf16 v[96:99], v[154:157], v[202:205], v[96:99]
	v_mfma_f32_16x16x32_bf16 v[92:95], v[162:165], v[202:205], v[92:95]
	v_mfma_f32_16x16x32_bf16 v[84:87], v[154:157], v[212:215], v[84:87]
	v_mfma_f32_16x16x32_bf16 v[76:79], v[162:165], v[212:215], v[76:79]
	s_setprio 0
	s_setprio 1
	v_mfma_f32_16x16x32_bf16 v[108:111], v[166:169], v[182:185], v[108:111]
	v_mfma_f32_16x16x32_bf16 v[104:107], v[174:177], v[182:185], v[104:107]
	v_mfma_f32_16x16x32_bf16 v[100:103], v[166:169], v[190:193], v[100:103]
	v_mfma_f32_16x16x32_bf16 v[88:91], v[174:177], v[190:193], v[88:91]
	v_mfma_f32_16x16x32_bf16 v[80:83], v[166:169], v[198:201], v[80:83]
	v_mfma_f32_16x16x32_bf16 v[72:75], v[174:177], v[198:201], v[72:75]
	v_mfma_f32_16x16x32_bf16 v[68:71], v[166:169], v[206:209], v[68:71]
	v_mfma_f32_16x16x32_bf16 v[64:67], v[174:177], v[206:209], v[64:67]
	v_mfma_f32_16x16x32_bf16 v[108:111], v[170:173], v[186:189], v[108:111]
	v_mfma_f32_16x16x32_bf16 v[104:107], v[178:181], v[186:189], v[104:107]
	v_mfma_f32_16x16x32_bf16 v[100:103], v[170:173], v[194:197], v[100:103]
	v_mfma_f32_16x16x32_bf16 v[88:91], v[178:181], v[194:197], v[88:91]
	v_mfma_f32_16x16x32_bf16 v[80:83], v[170:173], v[202:205], v[80:83]
	v_mfma_f32_16x16x32_bf16 v[72:75], v[178:181], v[202:205], v[72:75]
	v_mfma_f32_16x16x32_bf16 v[68:71], v[170:173], v[212:215], v[68:71]
	v_mfma_f32_16x16x32_bf16 v[64:67], v[178:181], v[212:215], v[64:67]
	s_setprio 0
	s_barrier
	s_mov_b32 m0, vcc_hi
	ds_read_b128 v[182:185], v147 offset:49152
	ds_read_b128 v[186:189], v147 offset:50176
	ds_read_b128 v[190:193], v147 offset:51200
	ds_read_b128 v[194:197], v147 offset:52224
	ds_read_b128 v[198:201], v147 offset:53248
	ds_read_b128 v[202:205], v147 offset:54272
	ds_read_b128 v[206:209], v147 offset:55296
	ds_read_b128 v[212:215], v147 offset:56320
	global_load_lds_dwordx4 v142, s[74:75]
	s_mov_b32 m0, s97
	s_nop 0
	global_load_lds_dwordx4 v143, s[74:75]
	s_mov_b32 m0, s96
	s_nop 0
	global_load_lds_dwordx4 v130, s[68:69]
	s_mov_b32 m0, s24
	s_nop 0
	global_load_lds_dwordx4 v134, s[68:69]
	s_mov_b32 m0, s87
	s_nop 0
	global_load_lds_dwordx4 v216, s[72:73]
	s_mov_b32 m0, s88
	s_nop 0
	global_load_lds_dwordx4 v217, s[72:73]
	s_waitcnt vmcnt(8)
	s_waitcnt lgkmcnt(0)
	s_barrier
	s_setprio 1
	s_waitcnt lgkmcnt(0)
	v_mfma_f32_16x16x32_bf16 v[60:63], v[150:153], v[182:185], v[60:63]
	v_mfma_f32_16x16x32_bf16 v[56:59], v[158:161], v[182:185], v[56:59]
	v_mfma_f32_16x16x32_bf16 v[52:55], v[150:153], v[190:193], v[52:55]
	v_mfma_f32_16x16x32_bf16 v[44:47], v[158:161], v[190:193], v[44:47]
	v_mfma_f32_16x16x32_bf16 v[36:39], v[150:153], v[198:201], v[36:39]
	v_mfma_f32_16x16x32_bf16 v[28:31], v[158:161], v[198:201], v[28:31]
	v_mfma_f32_16x16x32_bf16 v[20:23], v[150:153], v[206:209], v[20:23]
	v_mfma_f32_16x16x32_bf16 v[12:15], v[158:161], v[206:209], v[12:15]
	v_mfma_f32_16x16x32_bf16 v[60:63], v[154:157], v[186:189], v[60:63]
	v_mfma_f32_16x16x32_bf16 v[56:59], v[162:165], v[186:189], v[56:59]
	v_mfma_f32_16x16x32_bf16 v[52:55], v[154:157], v[194:197], v[52:55]
	v_mfma_f32_16x16x32_bf16 v[44:47], v[162:165], v[194:197], v[44:47]
	v_mfma_f32_16x16x32_bf16 v[36:39], v[154:157], v[202:205], v[36:39]
	v_mfma_f32_16x16x32_bf16 v[28:31], v[162:165], v[202:205], v[28:31]
	v_mfma_f32_16x16x32_bf16 v[20:23], v[154:157], v[212:215], v[20:23]
	v_mfma_f32_16x16x32_bf16 v[12:15], v[162:165], v[212:215], v[12:15]
	s_setprio 0
	s_setprio 1
	v_mfma_f32_16x16x32_bf16 v[48:51], v[166:169], v[182:185], v[48:51]
	v_mfma_f32_16x16x32_bf16 v[40:43], v[174:177], v[182:185], v[40:43]
	v_mfma_f32_16x16x32_bf16 v[32:35], v[166:169], v[190:193], v[32:35]
	v_mfma_f32_16x16x32_bf16 v[24:27], v[174:177], v[190:193], v[24:27]
	v_mfma_f32_16x16x32_bf16 v[16:19], v[166:169], v[198:201], v[16:19]
	v_mfma_f32_16x16x32_bf16 v[8:11], v[174:177], v[198:201], v[8:11]
	v_mfma_f32_16x16x32_bf16 v[4:7], v[166:169], v[206:209], v[4:7]
	v_mfma_f32_16x16x32_bf16 v[0:3], v[174:177], v[206:209], v[0:3]
	v_mfma_f32_16x16x32_bf16 v[48:51], v[170:173], v[186:189], v[48:51]
	v_mfma_f32_16x16x32_bf16 v[40:43], v[178:181], v[186:189], v[40:43]
	v_mfma_f32_16x16x32_bf16 v[32:35], v[170:173], v[194:197], v[32:35]
	v_mfma_f32_16x16x32_bf16 v[24:27], v[178:181], v[194:197], v[24:27]
	v_mfma_f32_16x16x32_bf16 v[16:19], v[170:173], v[202:205], v[16:19]
	v_mfma_f32_16x16x32_bf16 v[8:11], v[178:181], v[202:205], v[8:11]
	v_mfma_f32_16x16x32_bf16 v[4:7], v[170:173], v[212:215], v[4:7]
	v_mfma_f32_16x16x32_bf16 v[0:3], v[178:181], v[212:215], v[0:3]
	s_setprio 0
	s_barrier
	s_movk_i32 s70, 0x100
	s_andn2_b64 vcc, exec, s[66:67]
	s_mov_b64 s[68:69], -1
	s_mov_b64 s[66:67], 0
	s_cbranch_vccz .LBB0_801
	s_and_b64 vcc, exec, s[14:15]
	s_cbranch_vccz .LBB0_804
	s_barrier

.LBB0_1122:
	v_add_u32_e32 v208, 0x80, v178
	v_add_u32_e32 v209, 0x80, v182
	v_add_u32_e32 v216, 0x80, v176
	v_add_u32_e32 v217, 0x80, v180
	ds_read_b128 v[128:131], v213
	ds_read_b128 v[132:135], v213 offset:1024
	ds_read_b128 v[136:139], v213 offset:2048
	ds_read_b128 v[140:143], v213 offset:3072
	ds_read_b128 v[144:147], v214
	ds_read_b128 v[148:151], v214 offset:1024
	ds_read_b128 v[152:155], v214 offset:2048
	ds_read_b128 v[156:159], v214 offset:3072
	s_add_u32 s4, s58, 0xfffc0080
	s_addc_u32 s5, s59, -1
	s_cmp_eq_u32 s79, 12
	s_cselect_b32 s63, s19, s5
	s_cselect_b32 s62, s57, s4
	s_cselect_b32 s61, s17, s78
	s_cselect_b32 s60, s76, s77
	s_add_i32 m0, s47, 0xc000
	ds_read_b128 v[160:163], v215
	ds_read_b128 v[164:167], v215 offset:1024
	ds_read_b128 v[168:171], v215 offset:2048
	ds_read_b128 v[172:175], v215 offset:3072
	ds_read_b128 v[192:195], v215 offset:4096
	ds_read_b128 v[196:199], v215 offset:5120
	ds_read_b128 v[200:203], v215 offset:6144
	ds_read_b128 v[204:207], v215 offset:7168
	global_load_lds_dwordx4 v184, s[58:59]
	s_add_i32 m0, s47, 0xe000
	s_nop 0
	global_load_lds_dwordx4 v186, s[58:59]
	s_waitcnt vmcnt(8)
	s_waitcnt lgkmcnt(0)
	s_barrier
	s_setprio 1
	s_waitcnt lgkmcnt(0)
	v_mfma_f32_16x16x32_bf16 v[124:127], v[128:131], v[160:163], v[124:127]
	v_mfma_f32_16x16x32_bf16 v[120:123], v[136:139], v[160:163], v[120:123]
	v_mfma_f32_16x16x32_bf16 v[108:111], v[128:131], v[168:171], v[108:111]
	v_mfma_f32_16x16x32_bf16 v[104:107], v[136:139], v[168:171], v[104:107]
	v_mfma_f32_16x16x32_bf16 v[92:95], v[128:131], v[192:195], v[92:95]
	v_mfma_f32_16x16x32_bf16 v[88:91], v[136:139], v[192:195], v[88:91]
	v_mfma_f32_16x16x32_bf16 v[76:79], v[128:131], v[200:203], v[76:79]
	v_mfma_f32_16x16x32_bf16 v[72:75], v[136:139], v[200:203], v[72:75]
	v_mfma_f32_16x16x32_bf16 v[124:127], v[132:135], v[164:167], v[124:127]
	v_mfma_f32_16x16x32_bf16 v[120:123], v[140:143], v[164:167], v[120:123]
	v_mfma_f32_16x16x32_bf16 v[108:111], v[132:135], v[172:175], v[108:111]
	v_mfma_f32_16x16x32_bf16 v[104:107], v[140:143], v[172:175], v[104:107]
	v_mfma_f32_16x16x32_bf16 v[92:95], v[132:135], v[196:199], v[92:95]
	v_mfma_f32_16x16x32_bf16 v[88:91], v[140:143], v[196:199], v[88:91]
	v_mfma_f32_16x16x32_bf16 v[76:79], v[132:135], v[204:207], v[76:79]
	v_mfma_f32_16x16x32_bf16 v[72:75], v[140:143], v[204:207], v[72:75]
	s_setprio 0
	s_setprio 1
	v_mfma_f32_16x16x32_bf16 v[116:119], v[144:147], v[160:163], v[116:119]
	v_mfma_f32_16x16x32_bf16 v[112:115], v[152:155], v[160:163], v[112:115]
	v_mfma_f32_16x16x32_bf16 v[100:103], v[144:147], v[168:171], v[100:103]
	v_mfma_f32_16x16x32_bf16 v[96:99], v[152:155], v[168:171], v[96:99]
	v_mfma_f32_16x16x32_bf16 v[84:87], v[144:147], v[192:195], v[84:87]
	v_mfma_f32_16x16x32_bf16 v[80:83], v[152:155], v[192:195], v[80:83]
	v_mfma_f32_16x16x32_bf16 v[68:71], v[144:147], v[200:203], v[68:71]
	v_mfma_f32_16x16x32_bf16 v[64:67], v[152:155], v[200:203], v[64:67]
	v_mfma_f32_16x16x32_bf16 v[116:119], v[148:151], v[164:167], v[116:119]
	v_mfma_f32_16x16x32_bf16 v[112:115], v[156:159], v[164:167], v[112:115]
	v_mfma_f32_16x16x32_bf16 v[100:103], v[148:151], v[172:175], v[100:103]
	v_mfma_f32_16x16x32_bf16 v[96:99], v[156:159], v[172:175], v[96:99]
	v_mfma_f32_16x16x32_bf16 v[84:87], v[148:151], v[196:199], v[84:87]
	v_mfma_f32_16x16x32_bf16 v[80:83], v[156:159], v[196:199], v[80:83]
	v_mfma_f32_16x16x32_bf16 v[68:71], v[148:151], v[204:207], v[68:71]
	v_mfma_f32_16x16x32_bf16 v[64:67], v[156:159], v[204:207], v[64:67]
	s_setprio 0
	s_barrier
	s_add_i32 s4, s73, s46
	s_mov_b32 m0, s4
	ds_read_b128 v[160:163], v215 offset:16384
	ds_read_b128 v[164:167], v215 offset:17408
	ds_read_b128 v[168:171], v215 offset:18432
	ds_read_b128 v[172:175], v215 offset:19456
	ds_read_b128 v[192:195], v215 offset:20480
	ds_read_b128 v[196:199], v215 offset:21504
	ds_read_b128 v[200:203], v215 offset:22528
	ds_read_b128 v[204:207], v215 offset:23552
	global_load_lds_dwordx4 v178, s[60:61]
	s_add_i32 m0, s4, 0x2000
	s_add_u32 s4, s60, 0x40000
	s_addc_u32 s5, s61, 0
	s_add_i32 s24, s74, s46
	global_load_lds_dwordx4 v182, s[60:61]
	s_mov_b32 m0, s24
	s_nop 0
	global_load_lds_dwordx4 v178, s[4:5]
	s_add_i32 m0, s24, 0x2000
	s_nop 0
	global_load_lds_dwordx4 v182, s[4:5]
	s_mov_b32 m0, s47
	s_nop 0
	global_load_lds_dwordx4 v176, s[62:63]
	s_mov_b32 m0, s50
	s_nop 0
	global_load_lds_dwordx4 v180, s[62:63]
	s_waitcnt vmcnt(8)
	s_waitcnt lgkmcnt(0)
	s_barrier
	s_setprio 1
	s_waitcnt lgkmcnt(0)
	v_mfma_f32_16x16x32_bf16 v[60:63], v[128:131], v[160:163], v[60:63]
	v_mfma_f32_16x16x32_bf16 v[56:59], v[136:139], v[160:163], v[56:59]
	v_mfma_f32_16x16x32_bf16 v[44:47], v[128:131], v[168:171], v[44:47]
	v_mfma_f32_16x16x32_bf16 v[40:43], v[136:139], v[168:171], v[40:43]
	v_mfma_f32_16x16x32_bf16 v[28:31], v[128:131], v[192:195], v[28:31]
	v_mfma_f32_16x16x32_bf16 v[24:27], v[136:139], v[192:195], v[24:27]
	v_mfma_f32_16x16x32_bf16 v[12:15], v[128:131], v[200:203], v[12:15]
	v_mfma_f32_16x16x32_bf16 v[8:11], v[136:139], v[200:203], v[8:11]
	v_mfma_f32_16x16x32_bf16 v[60:63], v[132:135], v[164:167], v[60:63]
	v_mfma_f32_16x16x32_bf16 v[56:59], v[140:143], v[164:167], v[56:59]
	v_mfma_f32_16x16x32_bf16 v[44:47], v[132:135], v[172:175], v[44:47]
	v_mfma_f32_16x16x32_bf16 v[40:43], v[140:143], v[172:175], v[40:43]
	v_mfma_f32_16x16x32_bf16 v[28:31], v[132:135], v[196:199], v[28:31]
	v_mfma_f32_16x16x32_bf16 v[24:27], v[140:143], v[196:199], v[24:27]
	v_mfma_f32_16x16x32_bf16 v[12:15], v[132:135], v[204:207], v[12:15]
	v_mfma_f32_16x16x32_bf16 v[8:11], v[140:143], v[204:207], v[8:11]
	s_setprio 0
	s_setprio 1
	v_mfma_f32_16x16x32_bf16 v[52:55], v[144:147], v[160:163], v[52:55]
	v_mfma_f32_16x16x32_bf16 v[48:51], v[152:155], v[160:163], v[48:51]
	v_mfma_f32_16x16x32_bf16 v[36:39], v[144:147], v[168:171], v[36:39]
	v_mfma_f32_16x16x32_bf16 v[32:35], v[152:155], v[168:171], v[32:35]
	v_mfma_f32_16x16x32_bf16 v[20:23], v[144:147], v[192:195], v[20:23]
	v_mfma_f32_16x16x32_bf16 v[16:19], v[152:155], v[192:195], v[16:19]
	v_mfma_f32_16x16x32_bf16 v[4:7], v[144:147], v[200:203], v[4:7]
	v_mfma_f32_16x16x32_bf16 v[0:3], v[152:155], v[200:203], v[0:3]
	v_mfma_f32_16x16x32_bf16 v[52:55], v[148:151], v[164:167], v[52:55]
	v_mfma_f32_16x16x32_bf16 v[48:51], v[156:159], v[164:167], v[48:51]
	v_mfma_f32_16x16x32_bf16 v[36:39], v[148:151], v[172:175], v[36:39]
	v_mfma_f32_16x16x32_bf16 v[32:35], v[156:159], v[172:175], v[32:35]
	v_mfma_f32_16x16x32_bf16 v[20:23], v[148:151], v[196:199], v[20:23]
	v_mfma_f32_16x16x32_bf16 v[16:19], v[156:159], v[196:199], v[16:19]
	v_mfma_f32_16x16x32_bf16 v[4:7], v[148:151], v[204:207], v[4:7]
	v_mfma_f32_16x16x32_bf16 v[0:3], v[156:159], v[204:207], v[0:3]
	s_setprio 0
	s_barrier
	s_add_i32 s24, 0, 0x18000
	s_add_i32 s25, 0, 0x1c000
	v_add_u32_e32 v140, s24, v212
	v_add_u32_e32 v156, s25, v212
	ds_read_b128 v[128:131], v140
	ds_read_b128 v[132:135], v140 offset:1024
	ds_read_b128 v[136:139], v140 offset:2048
	ds_read_b128 v[140:143], v140 offset:3072
	ds_read_b128 v[144:147], v156
	ds_read_b128 v[148:151], v156 offset:1024
	ds_read_b128 v[152:155], v156 offset:2048
	ds_read_b128 v[156:159], v156 offset:3072
	s_add_u32 s4, s62, 0x40000
	s_addc_u32 s5, s63, 0
	s_mov_b32 m0, s51
	ds_read_b128 v[160:163], v215 offset:32768
	ds_read_b128 v[164:167], v215 offset:33792
	ds_read_b128 v[168:171], v215 offset:34816
	ds_read_b128 v[172:175], v215 offset:35840
	ds_read_b128 v[192:195], v215 offset:36864
	ds_read_b128 v[196:199], v215 offset:37888
	ds_read_b128 v[200:203], v215 offset:38912
	ds_read_b128 v[204:207], v215 offset:39936
	global_load_lds_dwordx4 v176, s[4:5]
	s_mov_b32 m0, s64
	s_nop 0
	global_load_lds_dwordx4 v180, s[4:5]
	s_waitcnt vmcnt(8)
	s_waitcnt lgkmcnt(0)
	s_barrier
	s_setprio 1
	s_waitcnt lgkmcnt(0)
	v_mfma_f32_16x16x32_bf16 v[124:127], v[128:131], v[160:163], v[124:127]
	v_mfma_f32_16x16x32_bf16 v[120:123], v[136:139], v[160:163], v[120:123]
	v_mfma_f32_16x16x32_bf16 v[108:111], v[128:131], v[168:171], v[108:111]
	v_mfma_f32_16x16x32_bf16 v[104:107], v[136:139], v[168:171], v[104:107]
	v_mfma_f32_16x16x32_bf16 v[92:95], v[128:131], v[192:195], v[92:95]
	v_mfma_f32_16x16x32_bf16 v[88:91], v[136:139], v[192:195], v[88:91]
	v_mfma_f32_16x16x32_bf16 v[76:79], v[128:131], v[200:203], v[76:79]
	v_mfma_f32_16x16x32_bf16 v[72:75], v[136:139], v[200:203], v[72:75]
	v_mfma_f32_16x16x32_bf16 v[124:127], v[132:135], v[164:167], v[124:127]
	v_mfma_f32_16x16x32_bf16 v[120:123], v[140:143], v[164:167], v[120:123]
	v_mfma_f32_16x16x32_bf16 v[108:111], v[132:135], v[172:175], v[108:111]
	v_mfma_f32_16x16x32_bf16 v[104:107], v[140:143], v[172:175], v[104:107]
	v_mfma_f32_16x16x32_bf16 v[92:95], v[132:135], v[196:199], v[92:95]
	v_mfma_f32_16x16x32_bf16 v[88:91], v[140:143], v[196:199], v[88:91]
	v_mfma_f32_16x16x32_bf16 v[76:79], v[132:135], v[204:207], v[76:79]
	v_mfma_f32_16x16x32_bf16 v[72:75], v[140:143], v[204:207], v[72:75]
	s_setprio 0
	s_setprio 1
	v_mfma_f32_16x16x32_bf16 v[116:119], v[144:147], v[160:163], v[116:119]
	v_mfma_f32_16x16x32_bf16 v[112:115], v[152:155], v[160:163], v[112:115]
	v_mfma_f32_16x16x32_bf16 v[100:103], v[144:147], v[168:171], v[100:103]
	v_mfma_f32_16x16x32_bf16 v[96:99], v[152:155], v[168:171], v[96:99]
	v_mfma_f32_16x16x32_bf16 v[84:87], v[144:147], v[192:195], v[84:87]
	v_mfma_f32_16x16x32_bf16 v[80:83], v[152:155], v[192:195], v[80:83]
	v_mfma_f32_16x16x32_bf16 v[68:71], v[144:147], v[200:203], v[68:71]
	v_mfma_f32_16x16x32_bf16 v[64:67], v[152:155], v[200:203], v[64:67]
	v_mfma_f32_16x16x32_bf16 v[116:119], v[148:151], v[164:167], v[116:119]
	v_mfma_f32_16x16x32_bf16 v[112:115], v[156:159], v[164:167], v[112:115]
	v_mfma_f32_16x16x32_bf16 v[100:103], v[148:151], v[172:175], v[100:103]
	v_mfma_f32_16x16x32_bf16 v[96:99], v[156:159], v[172:175], v[96:99]
	v_mfma_f32_16x16x32_bf16 v[84:87], v[148:151], v[196:199], v[84:87]
	v_mfma_f32_16x16x32_bf16 v[80:83], v[156:159], v[196:199], v[80:83]
	v_mfma_f32_16x16x32_bf16 v[68:71], v[148:151], v[204:207], v[68:71]
	v_mfma_f32_16x16x32_bf16 v[64:67], v[156:159], v[204:207], v[64:67]
	s_setprio 0
	s_barrier
	s_add_i32 s4, s24, s46
	s_mov_b32 m0, s4
	ds_read_b128 v[160:163], v215 offset:49152
	ds_read_b128 v[164:167], v215 offset:50176
	ds_read_b128 v[168:171], v215 offset:51200
	ds_read_b128 v[172:175], v215 offset:52224
	ds_read_b128 v[192:195], v215 offset:53248
	ds_read_b128 v[196:199], v215 offset:54272
	ds_read_b128 v[200:203], v215 offset:55296
	ds_read_b128 v[204:207], v215 offset:56320
	global_load_lds_dwordx4 v208, s[60:61]
	s_add_i32 m0, s4, 0x2000
	s_add_u32 s4, s60, 0x40080
	s_addc_u32 s5, s61, 0
	s_add_i32 s24, s25, s46
	global_load_lds_dwordx4 v209, s[60:61]
	s_mov_b32 m0, s24
	s_nop 0
	global_load_lds_dwordx4 v178, s[4:5]
	s_add_i32 m0, s24, 0x2000
	s_nop 0
	global_load_lds_dwordx4 v182, s[4:5]
	s_mov_b32 m0, s68
	s_nop 0
	global_load_lds_dwordx4 v216, s[62:63]
	s_mov_b32 m0, s69
	s_nop 0
	global_load_lds_dwordx4 v217, s[62:63]
	s_waitcnt vmcnt(8)
	s_waitcnt lgkmcnt(0)
	s_barrier
	s_setprio 1
	s_waitcnt lgkmcnt(0)
	v_mfma_f32_16x16x32_bf16 v[60:63], v[128:131], v[160:163], v[60:63]
	v_mfma_f32_16x16x32_bf16 v[56:59], v[136:139], v[160:163], v[56:59]
	v_mfma_f32_16x16x32_bf16 v[44:47], v[128:131], v[168:171], v[44:47]
	v_mfma_f32_16x16x32_bf16 v[40:43], v[136:139], v[168:171], v[40:43]
	v_mfma_f32_16x16x32_bf16 v[28:31], v[128:131], v[192:195], v[28:31]
	v_mfma_f32_16x16x32_bf16 v[24:27], v[136:139], v[192:195], v[24:27]
	v_mfma_f32_16x16x32_bf16 v[12:15], v[128:131], v[200:203], v[12:15]
	v_mfma_f32_16x16x32_bf16 v[8:11], v[136:139], v[200:203], v[8:11]
	v_mfma_f32_16x16x32_bf16 v[60:63], v[132:135], v[164:167], v[60:63]
	v_mfma_f32_16x16x32_bf16 v[56:59], v[140:143], v[164:167], v[56:59]
	v_mfma_f32_16x16x32_bf16 v[44:47], v[132:135], v[172:175], v[44:47]
	v_mfma_f32_16x16x32_bf16 v[40:43], v[140:143], v[172:175], v[40:43]
	v_mfma_f32_16x16x32_bf16 v[28:31], v[132:135], v[196:199], v[28:31]
	v_mfma_f32_16x16x32_bf16 v[24:27], v[140:143], v[196:199], v[24:27]
	v_mfma_f32_16x16x32_bf16 v[12:15], v[132:135], v[204:207], v[12:15]
	v_mfma_f32_16x16x32_bf16 v[8:11], v[140:143], v[204:207], v[8:11]
	s_setprio 0
	s_setprio 1
	v_mfma_f32_16x16x32_bf16 v[52:55], v[144:147], v[160:163], v[52:55]
	v_mfma_f32_16x16x32_bf16 v[48:51], v[152:155], v[160:163], v[48:51]
	v_mfma_f32_16x16x32_bf16 v[36:39], v[144:147], v[168:171], v[36:39]
	v_mfma_f32_16x16x32_bf16 v[32:35], v[152:155], v[168:171], v[32:35]
	v_mfma_f32_16x16x32_bf16 v[20:23], v[144:147], v[192:195], v[20:23]
	v_mfma_f32_16x16x32_bf16 v[16:19], v[152:155], v[192:195], v[16:19]
	v_mfma_f32_16x16x32_bf16 v[4:7], v[144:147], v[200:203], v[4:7]
	v_mfma_f32_16x16x32_bf16 v[0:3], v[152:155], v[200:203], v[0:3]
	v_mfma_f32_16x16x32_bf16 v[52:55], v[148:151], v[164:167], v[52:55]
	v_mfma_f32_16x16x32_bf16 v[48:51], v[156:159], v[164:167], v[48:51]
	v_mfma_f32_16x16x32_bf16 v[36:39], v[148:151], v[172:175], v[36:39]
	v_mfma_f32_16x16x32_bf16 v[32:35], v[156:159], v[172:175], v[32:35]
	v_mfma_f32_16x16x32_bf16 v[20:23], v[148:151], v[196:199], v[20:23]
	v_mfma_f32_16x16x32_bf16 v[16:19], v[156:159], v[196:199], v[16:19]
	v_mfma_f32_16x16x32_bf16 v[4:7], v[148:151], v[204:207], v[4:7]
	v_mfma_f32_16x16x32_bf16 v[0:3], v[156:159], v[204:207], v[0:3]
	s_setprio 0
	s_barrier
	s_add_i32 s79, s79, 2
	s_add_u32 s58, s58, 0x100
	s_addc_u32 s59, s59, 0
	s_add_u32 s77, s77, 0x100
	s_addc_u32 s78, s78, 0
	s_cmp_gt_u32 s79, 13
	s_cbranch_scc0 .LBB0_1122
	s_and_b64 vcc, exec, s[14:15]
	s_cbranch_vccz .LBB0_1125
	s_barrier

.LBB0_1223:
	v_add_u32_e32 v208, 0x80, v130
	v_add_u32_e32 v209, 0x80, v134
	v_add_u32_e32 v220, 0x80, v128
	v_add_u32_e32 v221, 0x80, v132
	ds_read_b128 v[152:155], v147
	ds_read_b128 v[156:159], v147 offset:1024
	ds_read_b128 v[160:163], v147 offset:2048
	ds_read_b128 v[164:167], v147 offset:3072
	ds_read_b128 v[168:171], v149
	ds_read_b128 v[172:175], v149 offset:1024
	ds_read_b128 v[176:179], v149 offset:2048
	ds_read_b128 v[180:183], v149 offset:3072
	s_add_u32 s4, s56, 0xfffc0080
	s_addc_u32 s5, s57, -1
	s_cmp_eq_u32 s80, 12
	s_cselect_b32 s61, s13, s5
	s_cselect_b32 s60, s51, s4
	s_cselect_b32 s59, s23, s79
	s_cselect_b32 s58, s77, s78
	s_add_i32 m0, s47, 0xc000
	ds_read_b128 v[184:187], v151
	ds_read_b128 v[188:191], v151 offset:1024
	ds_read_b128 v[192:195], v151 offset:2048
	ds_read_b128 v[196:199], v151 offset:3072
	ds_read_b128 v[200:203], v151 offset:4096
	ds_read_b128 v[204:207], v151 offset:5120
	ds_read_b128 v[212:215], v151 offset:6144
	ds_read_b128 v[216:219], v151 offset:7168
	global_load_lds_dwordx4 v136, s[56:57]
	s_add_i32 m0, s47, 0xe000
	s_nop 0
	global_load_lds_dwordx4 v138, s[56:57]
	s_waitcnt vmcnt(8)
	s_waitcnt lgkmcnt(0)
	s_barrier
	s_setprio 1
	s_waitcnt lgkmcnt(0)
	v_mfma_f32_16x16x32_bf16 v[124:127], v[152:155], v[184:187], v[124:127]
	v_mfma_f32_16x16x32_bf16 v[120:123], v[160:163], v[184:187], v[120:123]
	v_mfma_f32_16x16x32_bf16 v[108:111], v[152:155], v[192:195], v[108:111]
	v_mfma_f32_16x16x32_bf16 v[104:107], v[160:163], v[192:195], v[104:107]
	v_mfma_f32_16x16x32_bf16 v[92:95], v[152:155], v[200:203], v[92:95]
	v_mfma_f32_16x16x32_bf16 v[88:91], v[160:163], v[200:203], v[88:91]
	v_mfma_f32_16x16x32_bf16 v[76:79], v[152:155], v[212:215], v[76:79]
	v_mfma_f32_16x16x32_bf16 v[72:75], v[160:163], v[212:215], v[72:75]
	v_mfma_f32_16x16x32_bf16 v[124:127], v[156:159], v[188:191], v[124:127]
	v_mfma_f32_16x16x32_bf16 v[120:123], v[164:167], v[188:191], v[120:123]
	v_mfma_f32_16x16x32_bf16 v[108:111], v[156:159], v[196:199], v[108:111]
	v_mfma_f32_16x16x32_bf16 v[104:107], v[164:167], v[196:199], v[104:107]
	v_mfma_f32_16x16x32_bf16 v[92:95], v[156:159], v[204:207], v[92:95]
	v_mfma_f32_16x16x32_bf16 v[88:91], v[164:167], v[204:207], v[88:91]
	v_mfma_f32_16x16x32_bf16 v[76:79], v[156:159], v[216:219], v[76:79]
	v_mfma_f32_16x16x32_bf16 v[72:75], v[164:167], v[216:219], v[72:75]
	s_setprio 0
	s_setprio 1
	v_mfma_f32_16x16x32_bf16 v[116:119], v[168:171], v[184:187], v[116:119]
	v_mfma_f32_16x16x32_bf16 v[112:115], v[176:179], v[184:187], v[112:115]
	v_mfma_f32_16x16x32_bf16 v[100:103], v[168:171], v[192:195], v[100:103]
	v_mfma_f32_16x16x32_bf16 v[96:99], v[176:179], v[192:195], v[96:99]
	v_mfma_f32_16x16x32_bf16 v[84:87], v[168:171], v[200:203], v[84:87]
	v_mfma_f32_16x16x32_bf16 v[80:83], v[176:179], v[200:203], v[80:83]
	v_mfma_f32_16x16x32_bf16 v[68:71], v[168:171], v[212:215], v[68:71]
	v_mfma_f32_16x16x32_bf16 v[64:67], v[176:179], v[212:215], v[64:67]
	v_mfma_f32_16x16x32_bf16 v[116:119], v[172:175], v[188:191], v[116:119]
	v_mfma_f32_16x16x32_bf16 v[112:115], v[180:183], v[188:191], v[112:115]
	v_mfma_f32_16x16x32_bf16 v[100:103], v[172:175], v[196:199], v[100:103]
	v_mfma_f32_16x16x32_bf16 v[96:99], v[180:183], v[196:199], v[96:99]
	v_mfma_f32_16x16x32_bf16 v[84:87], v[172:175], v[204:207], v[84:87]
	v_mfma_f32_16x16x32_bf16 v[80:83], v[180:183], v[204:207], v[80:83]
	v_mfma_f32_16x16x32_bf16 v[68:71], v[172:175], v[216:219], v[68:71]
	v_mfma_f32_16x16x32_bf16 v[64:67], v[180:183], v[216:219], v[64:67]
	s_setprio 0
	s_barrier
	s_add_i32 s4, s72, s46
	s_mov_b32 m0, s4
	ds_read_b128 v[184:187], v151 offset:16384
	ds_read_b128 v[188:191], v151 offset:17408
	ds_read_b128 v[192:195], v151 offset:18432
	ds_read_b128 v[196:199], v151 offset:19456
	ds_read_b128 v[200:203], v151 offset:20480
	ds_read_b128 v[204:207], v151 offset:21504
	ds_read_b128 v[212:215], v151 offset:22528
	ds_read_b128 v[216:219], v151 offset:23552
	global_load_lds_dwordx4 v130, s[58:59]
	s_add_i32 m0, s4, 0x2000
	s_add_u32 s4, s58, 0x40000
	s_addc_u32 s5, s59, 0
	s_add_i32 s24, s73, s46
	global_load_lds_dwordx4 v134, s[58:59]
	s_mov_b32 m0, s24
	s_nop 0
	global_load_lds_dwordx4 v130, s[4:5]
	s_add_i32 m0, s24, 0x2000
	s_nop 0
	global_load_lds_dwordx4 v134, s[4:5]
	s_mov_b32 m0, s47
	s_nop 0
	global_load_lds_dwordx4 v128, s[60:61]
	s_mov_b32 m0, s62
	s_nop 0
	global_load_lds_dwordx4 v132, s[60:61]
	s_waitcnt vmcnt(8)
	s_waitcnt lgkmcnt(0)
	s_barrier
	s_setprio 1
	s_waitcnt lgkmcnt(0)
	v_mfma_f32_16x16x32_bf16 v[60:63], v[152:155], v[184:187], v[60:63]
	v_mfma_f32_16x16x32_bf16 v[56:59], v[160:163], v[184:187], v[56:59]
	v_mfma_f32_16x16x32_bf16 v[44:47], v[152:155], v[192:195], v[44:47]
	v_mfma_f32_16x16x32_bf16 v[40:43], v[160:163], v[192:195], v[40:43]
	v_mfma_f32_16x16x32_bf16 v[28:31], v[152:155], v[200:203], v[28:31]
	v_mfma_f32_16x16x32_bf16 v[24:27], v[160:163], v[200:203], v[24:27]
	v_mfma_f32_16x16x32_bf16 v[12:15], v[152:155], v[212:215], v[12:15]
	v_mfma_f32_16x16x32_bf16 v[8:11], v[160:163], v[212:215], v[8:11]
	v_mfma_f32_16x16x32_bf16 v[60:63], v[156:159], v[188:191], v[60:63]
	v_mfma_f32_16x16x32_bf16 v[56:59], v[164:167], v[188:191], v[56:59]
	v_mfma_f32_16x16x32_bf16 v[44:47], v[156:159], v[196:199], v[44:47]
	v_mfma_f32_16x16x32_bf16 v[40:43], v[164:167], v[196:199], v[40:43]
	v_mfma_f32_16x16x32_bf16 v[28:31], v[156:159], v[204:207], v[28:31]
	v_mfma_f32_16x16x32_bf16 v[24:27], v[164:167], v[204:207], v[24:27]
	v_mfma_f32_16x16x32_bf16 v[12:15], v[156:159], v[216:219], v[12:15]
	v_mfma_f32_16x16x32_bf16 v[8:11], v[164:167], v[216:219], v[8:11]
	s_setprio 0
	s_setprio 1
	v_mfma_f32_16x16x32_bf16 v[52:55], v[168:171], v[184:187], v[52:55]
	v_mfma_f32_16x16x32_bf16 v[48:51], v[176:179], v[184:187], v[48:51]
	v_mfma_f32_16x16x32_bf16 v[36:39], v[168:171], v[192:195], v[36:39]
	v_mfma_f32_16x16x32_bf16 v[32:35], v[176:179], v[192:195], v[32:35]
	v_mfma_f32_16x16x32_bf16 v[20:23], v[168:171], v[200:203], v[20:23]
	v_mfma_f32_16x16x32_bf16 v[16:19], v[176:179], v[200:203], v[16:19]
	v_mfma_f32_16x16x32_bf16 v[4:7], v[168:171], v[212:215], v[4:7]
	v_mfma_f32_16x16x32_bf16 v[0:3], v[176:179], v[212:215], v[0:3]
	v_mfma_f32_16x16x32_bf16 v[52:55], v[172:175], v[188:191], v[52:55]
	v_mfma_f32_16x16x32_bf16 v[48:51], v[180:183], v[188:191], v[48:51]
	v_mfma_f32_16x16x32_bf16 v[36:39], v[172:175], v[196:199], v[36:39]
	v_mfma_f32_16x16x32_bf16 v[32:35], v[180:183], v[196:199], v[32:35]
	v_mfma_f32_16x16x32_bf16 v[20:23], v[172:175], v[204:207], v[20:23]
	v_mfma_f32_16x16x32_bf16 v[16:19], v[180:183], v[204:207], v[16:19]
	v_mfma_f32_16x16x32_bf16 v[4:7], v[172:175], v[216:219], v[4:7]
	v_mfma_f32_16x16x32_bf16 v[0:3], v[180:183], v[216:219], v[0:3]
	s_setprio 0
	s_barrier
	s_add_i32 s24, 0, 0x18000
	v_add_u32_e32 v146, s24, v145
	s_add_i32 s25, 0, 0x1c000
	ds_read_b128 v[152:155], v146
	ds_read_b128 v[156:159], v146 offset:1024
	ds_read_b128 v[160:163], v146 offset:2048
	ds_read_b128 v[164:167], v146 offset:3072
	v_add_u32_e32 v146, s25, v145
	ds_read_b128 v[168:171], v146
	ds_read_b128 v[172:175], v146 offset:1024
	ds_read_b128 v[176:179], v146 offset:2048
	ds_read_b128 v[180:183], v146 offset:3072
	s_add_u32 s4, s60, 0x40000
	s_addc_u32 s5, s61, 0
	s_mov_b32 m0, s63
	ds_read_b128 v[184:187], v151 offset:32768
	ds_read_b128 v[188:191], v151 offset:33792
	ds_read_b128 v[192:195], v151 offset:34816
	ds_read_b128 v[196:199], v151 offset:35840
	ds_read_b128 v[200:203], v151 offset:36864
	ds_read_b128 v[204:207], v151 offset:37888
	ds_read_b128 v[212:215], v151 offset:38912
	ds_read_b128 v[216:219], v151 offset:39936
	global_load_lds_dwordx4 v128, s[4:5]
	s_mov_b32 m0, s64
	s_nop 0
	global_load_lds_dwordx4 v132, s[4:5]
	s_waitcnt vmcnt(8)
	s_waitcnt lgkmcnt(0)
	s_barrier
	s_setprio 1
	s_waitcnt lgkmcnt(0)
	v_mfma_f32_16x16x32_bf16 v[124:127], v[152:155], v[184:187], v[124:127]
	v_mfma_f32_16x16x32_bf16 v[120:123], v[160:163], v[184:187], v[120:123]
	v_mfma_f32_16x16x32_bf16 v[108:111], v[152:155], v[192:195], v[108:111]
	v_mfma_f32_16x16x32_bf16 v[104:107], v[160:163], v[192:195], v[104:107]
	v_mfma_f32_16x16x32_bf16 v[92:95], v[152:155], v[200:203], v[92:95]
	v_mfma_f32_16x16x32_bf16 v[88:91], v[160:163], v[200:203], v[88:91]
	v_mfma_f32_16x16x32_bf16 v[76:79], v[152:155], v[212:215], v[76:79]
	v_mfma_f32_16x16x32_bf16 v[72:75], v[160:163], v[212:215], v[72:75]
	v_mfma_f32_16x16x32_bf16 v[124:127], v[156:159], v[188:191], v[124:127]
	v_mfma_f32_16x16x32_bf16 v[120:123], v[164:167], v[188:191], v[120:123]
	v_mfma_f32_16x16x32_bf16 v[108:111], v[156:159], v[196:199], v[108:111]
	v_mfma_f32_16x16x32_bf16 v[104:107], v[164:167], v[196:199], v[104:107]
	v_mfma_f32_16x16x32_bf16 v[92:95], v[156:159], v[204:207], v[92:95]
	v_mfma_f32_16x16x32_bf16 v[88:91], v[164:167], v[204:207], v[88:91]
	v_mfma_f32_16x16x32_bf16 v[76:79], v[156:159], v[216:219], v[76:79]
	v_mfma_f32_16x16x32_bf16 v[72:75], v[164:167], v[216:219], v[72:75]
	s_setprio 0
	s_setprio 1
	v_mfma_f32_16x16x32_bf16 v[116:119], v[168:171], v[184:187], v[116:119]
	v_mfma_f32_16x16x32_bf16 v[112:115], v[176:179], v[184:187], v[112:115]
	v_mfma_f32_16x16x32_bf16 v[100:103], v[168:171], v[192:195], v[100:103]
	v_mfma_f32_16x16x32_bf16 v[96:99], v[176:179], v[192:195], v[96:99]
	v_mfma_f32_16x16x32_bf16 v[84:87], v[168:171], v[200:203], v[84:87]
	v_mfma_f32_16x16x32_bf16 v[80:83], v[176:179], v[200:203], v[80:83]
	v_mfma_f32_16x16x32_bf16 v[68:71], v[168:171], v[212:215], v[68:71]
	v_mfma_f32_16x16x32_bf16 v[64:67], v[176:179], v[212:215], v[64:67]
	v_mfma_f32_16x16x32_bf16 v[116:119], v[172:175], v[188:191], v[116:119]
	v_mfma_f32_16x16x32_bf16 v[112:115], v[180:183], v[188:191], v[112:115]
	v_mfma_f32_16x16x32_bf16 v[100:103], v[172:175], v[196:199], v[100:103]
	v_mfma_f32_16x16x32_bf16 v[96:99], v[180:183], v[196:199], v[96:99]
	v_mfma_f32_16x16x32_bf16 v[84:87], v[172:175], v[204:207], v[84:87]
	v_mfma_f32_16x16x32_bf16 v[80:83], v[180:183], v[204:207], v[80:83]
	v_mfma_f32_16x16x32_bf16 v[68:71], v[172:175], v[216:219], v[68:71]
	v_mfma_f32_16x16x32_bf16 v[64:67], v[180:183], v[216:219], v[64:67]
	s_setprio 0
	s_barrier
	s_add_i32 s4, s24, s46
	s_mov_b32 m0, s4
	ds_read_b128 v[184:187], v151 offset:49152
	ds_read_b128 v[188:191], v151 offset:50176
	ds_read_b128 v[192:195], v151 offset:51200
	ds_read_b128 v[196:199], v151 offset:52224
	ds_read_b128 v[200:203], v151 offset:53248
	ds_read_b128 v[204:207], v151 offset:54272
	ds_read_b128 v[212:215], v151 offset:55296
	ds_read_b128 v[216:219], v151 offset:56320
	global_load_lds_dwordx4 v208, s[58:59]
	s_add_i32 m0, s4, 0x2000
	s_add_u32 s4, s58, 0x40080
	s_addc_u32 s5, s59, 0
	s_add_i32 s24, s25, s46
	global_load_lds_dwordx4 v209, s[58:59]
	s_mov_b32 m0, s24
	s_nop 0
	global_load_lds_dwordx4 v130, s[4:5]
	s_add_i32 m0, s24, 0x2000
	s_nop 0
	global_load_lds_dwordx4 v134, s[4:5]
	s_mov_b32 m0, s68
	s_nop 0
	global_load_lds_dwordx4 v220, s[60:61]
	s_mov_b32 m0, s69
	s_nop 0
	global_load_lds_dwordx4 v221, s[60:61]
	s_waitcnt vmcnt(8)
	s_waitcnt lgkmcnt(0)
	s_barrier
	s_setprio 1
	s_waitcnt lgkmcnt(0)
	v_mfma_f32_16x16x32_bf16 v[60:63], v[152:155], v[184:187], v[60:63]
	v_mfma_f32_16x16x32_bf16 v[56:59], v[160:163], v[184:187], v[56:59]
	v_mfma_f32_16x16x32_bf16 v[44:47], v[152:155], v[192:195], v[44:47]
	v_mfma_f32_16x16x32_bf16 v[40:43], v[160:163], v[192:195], v[40:43]
	v_mfma_f32_16x16x32_bf16 v[28:31], v[152:155], v[200:203], v[28:31]
	v_mfma_f32_16x16x32_bf16 v[24:27], v[160:163], v[200:203], v[24:27]
	v_mfma_f32_16x16x32_bf16 v[12:15], v[152:155], v[212:215], v[12:15]
	v_mfma_f32_16x16x32_bf16 v[8:11], v[160:163], v[212:215], v[8:11]
	v_mfma_f32_16x16x32_bf16 v[60:63], v[156:159], v[188:191], v[60:63]
	v_mfma_f32_16x16x32_bf16 v[56:59], v[164:167], v[188:191], v[56:59]
	v_mfma_f32_16x16x32_bf16 v[44:47], v[156:159], v[196:199], v[44:47]
	v_mfma_f32_16x16x32_bf16 v[40:43], v[164:167], v[196:199], v[40:43]
	v_mfma_f32_16x16x32_bf16 v[28:31], v[156:159], v[204:207], v[28:31]
	v_mfma_f32_16x16x32_bf16 v[24:27], v[164:167], v[204:207], v[24:27]
	v_mfma_f32_16x16x32_bf16 v[12:15], v[156:159], v[216:219], v[12:15]
	v_mfma_f32_16x16x32_bf16 v[8:11], v[164:167], v[216:219], v[8:11]
	s_setprio 0
	s_setprio 1
	v_mfma_f32_16x16x32_bf16 v[52:55], v[168:171], v[184:187], v[52:55]
	v_mfma_f32_16x16x32_bf16 v[48:51], v[176:179], v[184:187], v[48:51]
	v_mfma_f32_16x16x32_bf16 v[36:39], v[168:171], v[192:195], v[36:39]
	v_mfma_f32_16x16x32_bf16 v[32:35], v[176:179], v[192:195], v[32:35]
	v_mfma_f32_16x16x32_bf16 v[20:23], v[168:171], v[200:203], v[20:23]
	v_mfma_f32_16x16x32_bf16 v[16:19], v[176:179], v[200:203], v[16:19]
	v_mfma_f32_16x16x32_bf16 v[4:7], v[168:171], v[212:215], v[4:7]
	v_mfma_f32_16x16x32_bf16 v[0:3], v[176:179], v[212:215], v[0:3]
	v_mfma_f32_16x16x32_bf16 v[52:55], v[172:175], v[188:191], v[52:55]
	v_mfma_f32_16x16x32_bf16 v[48:51], v[180:183], v[188:191], v[48:51]
	v_mfma_f32_16x16x32_bf16 v[36:39], v[172:175], v[196:199], v[36:39]
	v_mfma_f32_16x16x32_bf16 v[32:35], v[180:183], v[196:199], v[32:35]
	v_mfma_f32_16x16x32_bf16 v[20:23], v[172:175], v[204:207], v[20:23]
	v_mfma_f32_16x16x32_bf16 v[16:19], v[180:183], v[204:207], v[16:19]
	v_mfma_f32_16x16x32_bf16 v[4:7], v[172:175], v[216:219], v[4:7]
	v_mfma_f32_16x16x32_bf16 v[0:3], v[180:183], v[216:219], v[0:3]
	s_setprio 0
	s_barrier
	s_add_i32 s80, s80, 2
	s_add_u32 s56, s56, 0x100
	s_addc_u32 s57, s57, 0
	s_add_u32 s78, s78, 0x100
	s_addc_u32 s79, s79, 0
	s_cmp_gt_u32 s80, 13
	s_cbranch_scc0 .LBB0_1223
	s_and_b64 vcc, exec, s[18:19]
	s_cbranch_vccz .LBB0_1226
	s_barrier

.LBB0_1309:
	v_add_u32_e32 v208, 0x80, v178
	v_add_u32_e32 v209, 0x80, v182
	v_add_u32_e32 v216, 0x80, v176
	v_add_u32_e32 v217, 0x80, v180
	ds_read_b128 v[128:131], v213
	ds_read_b128 v[132:135], v213 offset:1024
	ds_read_b128 v[136:139], v213 offset:2048
	ds_read_b128 v[140:143], v213 offset:3072
	ds_read_b128 v[144:147], v214
	ds_read_b128 v[148:151], v214 offset:1024
	ds_read_b128 v[152:155], v214 offset:2048
	ds_read_b128 v[156:159], v214 offset:3072
	s_add_u32 s54, s52, 0x100
	s_addc_u32 s55, s53, 0
	s_cmp_eq_u32 s77, 40
	s_cselect_b32 s59, s13, s55
	s_cselect_b32 s58, s12, s54
	s_cselect_b32 s57, s51, s76
	s_cselect_b32 s56, s50, s75
	s_add_i32 m0, s33, 0xc000
	ds_read_b128 v[160:163], v215
	ds_read_b128 v[164:167], v215 offset:1024
	ds_read_b128 v[168:171], v215 offset:2048
	ds_read_b128 v[172:175], v215 offset:3072
	ds_read_b128 v[192:195], v215 offset:4096
	ds_read_b128 v[196:199], v215 offset:5120
	ds_read_b128 v[200:203], v215 offset:6144
	ds_read_b128 v[204:207], v215 offset:7168
	global_load_lds_dwordx4 v184, s[52:53]
	s_add_i32 m0, s33, 0xe000
	s_nop 0
	global_load_lds_dwordx4 v186, s[52:53]
	s_waitcnt vmcnt(8)
	s_waitcnt lgkmcnt(0)
	s_barrier
	s_setprio 1
	s_waitcnt lgkmcnt(0)
	v_mfma_f32_16x16x32_bf16 v[124:127], v[128:131], v[160:163], v[124:127]
	v_mfma_f32_16x16x32_bf16 v[120:123], v[136:139], v[160:163], v[120:123]
	v_mfma_f32_16x16x32_bf16 v[108:111], v[128:131], v[168:171], v[108:111]
	v_mfma_f32_16x16x32_bf16 v[104:107], v[136:139], v[168:171], v[104:107]
	v_mfma_f32_16x16x32_bf16 v[92:95], v[128:131], v[192:195], v[92:95]
	v_mfma_f32_16x16x32_bf16 v[88:91], v[136:139], v[192:195], v[88:91]
	v_mfma_f32_16x16x32_bf16 v[76:79], v[128:131], v[200:203], v[76:79]
	v_mfma_f32_16x16x32_bf16 v[72:75], v[136:139], v[200:203], v[72:75]
	v_mfma_f32_16x16x32_bf16 v[124:127], v[132:135], v[164:167], v[124:127]
	v_mfma_f32_16x16x32_bf16 v[120:123], v[140:143], v[164:167], v[120:123]
	v_mfma_f32_16x16x32_bf16 v[108:111], v[132:135], v[172:175], v[108:111]
	v_mfma_f32_16x16x32_bf16 v[104:107], v[140:143], v[172:175], v[104:107]
	v_mfma_f32_16x16x32_bf16 v[92:95], v[132:135], v[196:199], v[92:95]
	v_mfma_f32_16x16x32_bf16 v[88:91], v[140:143], v[196:199], v[88:91]
	v_mfma_f32_16x16x32_bf16 v[76:79], v[132:135], v[204:207], v[76:79]
	v_mfma_f32_16x16x32_bf16 v[72:75], v[140:143], v[204:207], v[72:75]
	s_setprio 0
	s_setprio 1
	v_mfma_f32_16x16x32_bf16 v[116:119], v[144:147], v[160:163], v[116:119]
	v_mfma_f32_16x16x32_bf16 v[112:115], v[152:155], v[160:163], v[112:115]
	v_mfma_f32_16x16x32_bf16 v[100:103], v[144:147], v[168:171], v[100:103]
	v_mfma_f32_16x16x32_bf16 v[96:99], v[152:155], v[168:171], v[96:99]
	v_mfma_f32_16x16x32_bf16 v[84:87], v[144:147], v[192:195], v[84:87]
	v_mfma_f32_16x16x32_bf16 v[80:83], v[152:155], v[192:195], v[80:83]
	v_mfma_f32_16x16x32_bf16 v[68:71], v[144:147], v[200:203], v[68:71]
	v_mfma_f32_16x16x32_bf16 v[64:67], v[152:155], v[200:203], v[64:67]
	v_mfma_f32_16x16x32_bf16 v[116:119], v[148:151], v[164:167], v[116:119]
	v_mfma_f32_16x16x32_bf16 v[112:115], v[156:159], v[164:167], v[112:115]
	v_mfma_f32_16x16x32_bf16 v[100:103], v[148:151], v[172:175], v[100:103]
	v_mfma_f32_16x16x32_bf16 v[96:99], v[156:159], v[172:175], v[96:99]
	v_mfma_f32_16x16x32_bf16 v[84:87], v[148:151], v[196:199], v[84:87]
	v_mfma_f32_16x16x32_bf16 v[80:83], v[156:159], v[196:199], v[80:83]
	v_mfma_f32_16x16x32_bf16 v[68:71], v[148:151], v[204:207], v[68:71]
	v_mfma_f32_16x16x32_bf16 v[64:67], v[156:159], v[204:207], v[64:67]
	s_setprio 0
	s_barrier
	s_add_i32 s4, s69, s3
	s_mov_b32 m0, s4
	ds_read_b128 v[160:163], v215 offset:16384
	ds_read_b128 v[164:167], v215 offset:17408
	ds_read_b128 v[168:171], v215 offset:18432
	ds_read_b128 v[172:175], v215 offset:19456
	ds_read_b128 v[192:195], v215 offset:20480
	ds_read_b128 v[196:199], v215 offset:21504
	ds_read_b128 v[200:203], v215 offset:22528
	ds_read_b128 v[204:207], v215 offset:23552
	global_load_lds_dwordx4 v178, s[56:57]
	s_add_i32 m0, s4, 0x2000
	s_add_u32 s4, s56, 0xb0000
	s_addc_u32 s5, s57, 0
	s_add_i32 s24, s70, s3
	global_load_lds_dwordx4 v182, s[56:57]
	s_mov_b32 m0, s24
	s_nop 0
	global_load_lds_dwordx4 v178, s[4:5]
	s_add_i32 m0, s24, 0x2000
	s_nop 0
	global_load_lds_dwordx4 v182, s[4:5]
	s_mov_b32 m0, s33
	s_nop 0
	global_load_lds_dwordx4 v176, s[58:59]
	s_mov_b32 m0, s46
	s_nop 0
	global_load_lds_dwordx4 v180, s[58:59]
	s_waitcnt vmcnt(8)
	s_waitcnt lgkmcnt(0)
	s_barrier
	s_setprio 1
	s_waitcnt lgkmcnt(0)
	v_mfma_f32_16x16x32_bf16 v[60:63], v[128:131], v[160:163], v[60:63]
	v_mfma_f32_16x16x32_bf16 v[56:59], v[136:139], v[160:163], v[56:59]
	v_mfma_f32_16x16x32_bf16 v[44:47], v[128:131], v[168:171], v[44:47]
	v_mfma_f32_16x16x32_bf16 v[40:43], v[136:139], v[168:171], v[40:43]
	v_mfma_f32_16x16x32_bf16 v[28:31], v[128:131], v[192:195], v[28:31]
	v_mfma_f32_16x16x32_bf16 v[24:27], v[136:139], v[192:195], v[24:27]
	v_mfma_f32_16x16x32_bf16 v[12:15], v[128:131], v[200:203], v[12:15]
	v_mfma_f32_16x16x32_bf16 v[8:11], v[136:139], v[200:203], v[8:11]
	v_mfma_f32_16x16x32_bf16 v[60:63], v[132:135], v[164:167], v[60:63]
	v_mfma_f32_16x16x32_bf16 v[56:59], v[140:143], v[164:167], v[56:59]
	v_mfma_f32_16x16x32_bf16 v[44:47], v[132:135], v[172:175], v[44:47]
	v_mfma_f32_16x16x32_bf16 v[40:43], v[140:143], v[172:175], v[40:43]
	v_mfma_f32_16x16x32_bf16 v[28:31], v[132:135], v[196:199], v[28:31]
	v_mfma_f32_16x16x32_bf16 v[24:27], v[140:143], v[196:199], v[24:27]
	v_mfma_f32_16x16x32_bf16 v[12:15], v[132:135], v[204:207], v[12:15]
	v_mfma_f32_16x16x32_bf16 v[8:11], v[140:143], v[204:207], v[8:11]
	s_setprio 0
	s_setprio 1
	v_mfma_f32_16x16x32_bf16 v[52:55], v[144:147], v[160:163], v[52:55]
	v_mfma_f32_16x16x32_bf16 v[48:51], v[152:155], v[160:163], v[48:51]
	v_mfma_f32_16x16x32_bf16 v[36:39], v[144:147], v[168:171], v[36:39]
	v_mfma_f32_16x16x32_bf16 v[32:35], v[152:155], v[168:171], v[32:35]
	v_mfma_f32_16x16x32_bf16 v[20:23], v[144:147], v[192:195], v[20:23]
	v_mfma_f32_16x16x32_bf16 v[16:19], v[152:155], v[192:195], v[16:19]
	v_mfma_f32_16x16x32_bf16 v[4:7], v[144:147], v[200:203], v[4:7]
	v_mfma_f32_16x16x32_bf16 v[0:3], v[152:155], v[200:203], v[0:3]
	v_mfma_f32_16x16x32_bf16 v[52:55], v[148:151], v[164:167], v[52:55]
	v_mfma_f32_16x16x32_bf16 v[48:51], v[156:159], v[164:167], v[48:51]
	v_mfma_f32_16x16x32_bf16 v[36:39], v[148:151], v[172:175], v[36:39]
	v_mfma_f32_16x16x32_bf16 v[32:35], v[156:159], v[172:175], v[32:35]
	v_mfma_f32_16x16x32_bf16 v[20:23], v[148:151], v[196:199], v[20:23]
	v_mfma_f32_16x16x32_bf16 v[16:19], v[156:159], v[196:199], v[16:19]
	v_mfma_f32_16x16x32_bf16 v[4:7], v[148:151], v[204:207], v[4:7]
	v_mfma_f32_16x16x32_bf16 v[0:3], v[156:159], v[204:207], v[0:3]
	s_setprio 0
	s_barrier
	s_add_i32 s24, 0, 0x18000
	s_add_i32 s25, 0, 0x1c000
	v_add_u32_e32 v140, s24, v212
	v_add_u32_e32 v156, s25, v212
	ds_read_b128 v[128:131], v140
	ds_read_b128 v[132:135], v140 offset:1024
	ds_read_b128 v[136:139], v140 offset:2048
	ds_read_b128 v[140:143], v140 offset:3072
	ds_read_b128 v[144:147], v156
	ds_read_b128 v[148:151], v156 offset:1024
	ds_read_b128 v[152:155], v156 offset:2048
	ds_read_b128 v[156:159], v156 offset:3072
	s_add_u32 s4, s58, 0xb0000
	s_addc_u32 s5, s59, 0
	s_mov_b32 m0, s47
	ds_read_b128 v[160:163], v215 offset:32768
	ds_read_b128 v[164:167], v215 offset:33792
	ds_read_b128 v[168:171], v215 offset:34816
	ds_read_b128 v[172:175], v215 offset:35840
	ds_read_b128 v[192:195], v215 offset:36864
	ds_read_b128 v[196:199], v215 offset:37888
	ds_read_b128 v[200:203], v215 offset:38912
	ds_read_b128 v[204:207], v215 offset:39936
	global_load_lds_dwordx4 v176, s[4:5]
	s_mov_b32 m0, s60
	s_nop 0
	global_load_lds_dwordx4 v180, s[4:5]
	s_waitcnt vmcnt(8)
	s_waitcnt lgkmcnt(0)
	s_barrier
	s_setprio 1
	s_waitcnt lgkmcnt(0)
	v_mfma_f32_16x16x32_bf16 v[124:127], v[128:131], v[160:163], v[124:127]
	v_mfma_f32_16x16x32_bf16 v[120:123], v[136:139], v[160:163], v[120:123]
	v_mfma_f32_16x16x32_bf16 v[108:111], v[128:131], v[168:171], v[108:111]
	v_mfma_f32_16x16x32_bf16 v[104:107], v[136:139], v[168:171], v[104:107]
	v_mfma_f32_16x16x32_bf16 v[92:95], v[128:131], v[192:195], v[92:95]
	v_mfma_f32_16x16x32_bf16 v[88:91], v[136:139], v[192:195], v[88:91]
	v_mfma_f32_16x16x32_bf16 v[76:79], v[128:131], v[200:203], v[76:79]
	v_mfma_f32_16x16x32_bf16 v[72:75], v[136:139], v[200:203], v[72:75]
	v_mfma_f32_16x16x32_bf16 v[124:127], v[132:135], v[164:167], v[124:127]
	v_mfma_f32_16x16x32_bf16 v[120:123], v[140:143], v[164:167], v[120:123]
	v_mfma_f32_16x16x32_bf16 v[108:111], v[132:135], v[172:175], v[108:111]
	v_mfma_f32_16x16x32_bf16 v[104:107], v[140:143], v[172:175], v[104:107]
	v_mfma_f32_16x16x32_bf16 v[92:95], v[132:135], v[196:199], v[92:95]
	v_mfma_f32_16x16x32_bf16 v[88:91], v[140:143], v[196:199], v[88:91]
	v_mfma_f32_16x16x32_bf16 v[76:79], v[132:135], v[204:207], v[76:79]
	v_mfma_f32_16x16x32_bf16 v[72:75], v[140:143], v[204:207], v[72:75]
	s_setprio 0
	s_setprio 1
	v_mfma_f32_16x16x32_bf16 v[116:119], v[144:147], v[160:163], v[116:119]
	v_mfma_f32_16x16x32_bf16 v[112:115], v[152:155], v[160:163], v[112:115]
	v_mfma_f32_16x16x32_bf16 v[100:103], v[144:147], v[168:171], v[100:103]
	v_mfma_f32_16x16x32_bf16 v[96:99], v[152:155], v[168:171], v[96:99]
	v_mfma_f32_16x16x32_bf16 v[84:87], v[144:147], v[192:195], v[84:87]
	v_mfma_f32_16x16x32_bf16 v[80:83], v[152:155], v[192:195], v[80:83]
	v_mfma_f32_16x16x32_bf16 v[68:71], v[144:147], v[200:203], v[68:71]
	v_mfma_f32_16x16x32_bf16 v[64:67], v[152:155], v[200:203], v[64:67]
	v_mfma_f32_16x16x32_bf16 v[116:119], v[148:151], v[164:167], v[116:119]
	v_mfma_f32_16x16x32_bf16 v[112:115], v[156:159], v[164:167], v[112:115]
	v_mfma_f32_16x16x32_bf16 v[100:103], v[148:151], v[172:175], v[100:103]
	v_mfma_f32_16x16x32_bf16 v[96:99], v[156:159], v[172:175], v[96:99]
	v_mfma_f32_16x16x32_bf16 v[84:87], v[148:151], v[196:199], v[84:87]
	v_mfma_f32_16x16x32_bf16 v[80:83], v[156:159], v[196:199], v[80:83]
	v_mfma_f32_16x16x32_bf16 v[68:71], v[148:151], v[204:207], v[68:71]
	v_mfma_f32_16x16x32_bf16 v[64:67], v[156:159], v[204:207], v[64:67]
	s_setprio 0
	s_barrier
	s_add_i32 s4, s24, s3
	s_mov_b32 m0, s4
	ds_read_b128 v[160:163], v215 offset:49152
	ds_read_b128 v[164:167], v215 offset:50176
	ds_read_b128 v[168:171], v215 offset:51200
	ds_read_b128 v[172:175], v215 offset:52224
	ds_read_b128 v[192:195], v215 offset:53248
	ds_read_b128 v[196:199], v215 offset:54272
	ds_read_b128 v[200:203], v215 offset:55296
	ds_read_b128 v[204:207], v215 offset:56320
	global_load_lds_dwordx4 v208, s[56:57]
	s_add_i32 m0, s4, 0x2000
	s_add_u32 s4, s56, 0xb0080
	s_addc_u32 s5, s57, 0
	s_add_i32 s24, s25, s3
	global_load_lds_dwordx4 v209, s[56:57]
	s_mov_b32 m0, s24
	s_nop 0
	global_load_lds_dwordx4 v178, s[4:5]
	s_add_i32 m0, s24, 0x2000
	s_nop 0
	global_load_lds_dwordx4 v182, s[4:5]
	s_mov_b32 m0, s64
	s_nop 0
	global_load_lds_dwordx4 v216, s[58:59]
	s_mov_b32 m0, s65
	s_nop 0
	global_load_lds_dwordx4 v217, s[58:59]
	s_waitcnt vmcnt(8)
	s_waitcnt lgkmcnt(0)
	s_barrier
	s_setprio 1
	s_waitcnt lgkmcnt(0)
	v_mfma_f32_16x16x32_bf16 v[60:63], v[128:131], v[160:163], v[60:63]
	v_mfma_f32_16x16x32_bf16 v[56:59], v[136:139], v[160:163], v[56:59]
	v_mfma_f32_16x16x32_bf16 v[44:47], v[128:131], v[168:171], v[44:47]
	v_mfma_f32_16x16x32_bf16 v[40:43], v[136:139], v[168:171], v[40:43]
	v_mfma_f32_16x16x32_bf16 v[28:31], v[128:131], v[192:195], v[28:31]
	v_mfma_f32_16x16x32_bf16 v[24:27], v[136:139], v[192:195], v[24:27]
	v_mfma_f32_16x16x32_bf16 v[12:15], v[128:131], v[200:203], v[12:15]
	v_mfma_f32_16x16x32_bf16 v[8:11], v[136:139], v[200:203], v[8:11]
	v_mfma_f32_16x16x32_bf16 v[60:63], v[132:135], v[164:167], v[60:63]
	v_mfma_f32_16x16x32_bf16 v[56:59], v[140:143], v[164:167], v[56:59]
	v_mfma_f32_16x16x32_bf16 v[44:47], v[132:135], v[172:175], v[44:47]
	v_mfma_f32_16x16x32_bf16 v[40:43], v[140:143], v[172:175], v[40:43]
	v_mfma_f32_16x16x32_bf16 v[28:31], v[132:135], v[196:199], v[28:31]
	v_mfma_f32_16x16x32_bf16 v[24:27], v[140:143], v[196:199], v[24:27]
	v_mfma_f32_16x16x32_bf16 v[12:15], v[132:135], v[204:207], v[12:15]
	v_mfma_f32_16x16x32_bf16 v[8:11], v[140:143], v[204:207], v[8:11]
	s_setprio 0
	s_setprio 1
	v_mfma_f32_16x16x32_bf16 v[52:55], v[144:147], v[160:163], v[52:55]
	v_mfma_f32_16x16x32_bf16 v[48:51], v[152:155], v[160:163], v[48:51]
	v_mfma_f32_16x16x32_bf16 v[36:39], v[144:147], v[168:171], v[36:39]
	v_mfma_f32_16x16x32_bf16 v[32:35], v[152:155], v[168:171], v[32:35]
	v_mfma_f32_16x16x32_bf16 v[20:23], v[144:147], v[192:195], v[20:23]
	v_mfma_f32_16x16x32_bf16 v[16:19], v[152:155], v[192:195], v[16:19]
	v_mfma_f32_16x16x32_bf16 v[4:7], v[144:147], v[200:203], v[4:7]
	v_mfma_f32_16x16x32_bf16 v[0:3], v[152:155], v[200:203], v[0:3]
	v_mfma_f32_16x16x32_bf16 v[52:55], v[148:151], v[164:167], v[52:55]
	v_mfma_f32_16x16x32_bf16 v[48:51], v[156:159], v[164:167], v[48:51]
	v_mfma_f32_16x16x32_bf16 v[36:39], v[148:151], v[172:175], v[36:39]
	v_mfma_f32_16x16x32_bf16 v[32:35], v[156:159], v[172:175], v[32:35]
	v_mfma_f32_16x16x32_bf16 v[20:23], v[148:151], v[196:199], v[20:23]
	v_mfma_f32_16x16x32_bf16 v[16:19], v[156:159], v[196:199], v[16:19]
	v_mfma_f32_16x16x32_bf16 v[4:7], v[148:151], v[204:207], v[4:7]
	v_mfma_f32_16x16x32_bf16 v[0:3], v[156:159], v[204:207], v[0:3]
	s_setprio 0
	s_barrier
	s_add_i32 s77, s77, 2
	s_add_u32 s75, s75, 0x100
	s_addc_u32 s76, s76, 0
	s_cmp_gt_u32 s77, 41
	s_mov_b64 s[52:53], s[54:55]
	s_cbranch_scc0 .LBB0_1309
	s_and_b64 vcc, exec, s[22:23]
	s_cbranch_vccz .LBB0_1312
	s_barrier

.LBB0_1412:
	v_add_u32_e32 v172, 0x80, v128
	v_add_u32_e32 v173, 0x80, v130
	ds_read_b128 v[144:147], v174
	ds_read_b128 v[148:151], v174 offset:1024
	ds_read_b128 v[152:155], v174 offset:2048
	ds_read_b128 v[156:159], v174 offset:3072
	ds_read_b128 v[160:163], v175
	ds_read_b128 v[164:167], v175 offset:1024
	ds_read_b128 v[168:171], v175 offset:2048
	ds_read_b128 v[178:181], v175 offset:3072
	s_add_u32 s4, s14, 0xfffc0080
	s_addc_u32 s5, s15, -1
	s_cmp_eq_u32 s63, 12
	s_cselect_b32 s67, s13, s5
	s_cselect_b32 s66, s33, s4
	s_cselect_b32 s65, s46, s57
	s_cselect_b32 s64, s47, s55
	s_add_i32 m0, s73, 0xc000
	ds_read_b128 v[182:185], v176
	ds_read_b128 v[186:189], v176 offset:1024
	ds_read_b128 v[190:193], v176 offset:2048
	ds_read_b128 v[194:197], v176 offset:3072
	ds_read_b128 v[198:201], v176 offset:4096
	ds_read_b128 v[202:205], v176 offset:5120
	ds_read_b128 v[206:209], v176 offset:6144
	ds_read_b128 v[212:215], v176 offset:7168
	global_load_lds_dwordx4 v134, s[14:15]
	s_add_i32 m0, s73, 0xe000
	s_nop 0
	global_load_lds_dwordx4 v136, s[14:15]
	s_waitcnt vmcnt(8)
	s_waitcnt lgkmcnt(0)
	s_barrier
	s_setprio 1
	s_waitcnt lgkmcnt(0)
	v_mfma_f32_16x16x32_bf16 v[124:127], v[144:147], v[182:185], v[124:127]
	v_mfma_f32_16x16x32_bf16 v[120:123], v[152:155], v[182:185], v[120:123]
	v_mfma_f32_16x16x32_bf16 v[108:111], v[144:147], v[190:193], v[108:111]
	v_mfma_f32_16x16x32_bf16 v[104:107], v[152:155], v[190:193], v[104:107]
	v_mfma_f32_16x16x32_bf16 v[92:95], v[144:147], v[198:201], v[92:95]
	v_mfma_f32_16x16x32_bf16 v[88:91], v[152:155], v[198:201], v[88:91]
	v_mfma_f32_16x16x32_bf16 v[76:79], v[144:147], v[206:209], v[76:79]
	v_mfma_f32_16x16x32_bf16 v[72:75], v[152:155], v[206:209], v[72:75]
	v_mfma_f32_16x16x32_bf16 v[124:127], v[148:151], v[186:189], v[124:127]
	v_mfma_f32_16x16x32_bf16 v[120:123], v[156:159], v[186:189], v[120:123]
	v_mfma_f32_16x16x32_bf16 v[108:111], v[148:151], v[194:197], v[108:111]
	v_mfma_f32_16x16x32_bf16 v[104:107], v[156:159], v[194:197], v[104:107]
	v_mfma_f32_16x16x32_bf16 v[92:95], v[148:151], v[202:205], v[92:95]
	v_mfma_f32_16x16x32_bf16 v[88:91], v[156:159], v[202:205], v[88:91]
	v_mfma_f32_16x16x32_bf16 v[76:79], v[148:151], v[212:215], v[76:79]
	v_mfma_f32_16x16x32_bf16 v[72:75], v[156:159], v[212:215], v[72:75]
	s_setprio 0
	s_setprio 1
	v_mfma_f32_16x16x32_bf16 v[116:119], v[160:163], v[182:185], v[116:119]
	v_mfma_f32_16x16x32_bf16 v[112:115], v[168:171], v[182:185], v[112:115]
	v_mfma_f32_16x16x32_bf16 v[100:103], v[160:163], v[190:193], v[100:103]
	v_mfma_f32_16x16x32_bf16 v[96:99], v[168:171], v[190:193], v[96:99]
	v_mfma_f32_16x16x32_bf16 v[84:87], v[160:163], v[198:201], v[84:87]
	v_mfma_f32_16x16x32_bf16 v[80:83], v[168:171], v[198:201], v[80:83]
	v_mfma_f32_16x16x32_bf16 v[68:71], v[160:163], v[206:209], v[68:71]
	v_mfma_f32_16x16x32_bf16 v[64:67], v[168:171], v[206:209], v[64:67]
	v_mfma_f32_16x16x32_bf16 v[116:119], v[164:167], v[186:189], v[116:119]
	v_mfma_f32_16x16x32_bf16 v[112:115], v[178:181], v[186:189], v[112:115]
	v_mfma_f32_16x16x32_bf16 v[100:103], v[164:167], v[194:197], v[100:103]
	v_mfma_f32_16x16x32_bf16 v[96:99], v[178:181], v[194:197], v[96:99]
	v_mfma_f32_16x16x32_bf16 v[84:87], v[164:167], v[202:205], v[84:87]
	v_mfma_f32_16x16x32_bf16 v[80:83], v[178:181], v[202:205], v[80:83]
	v_mfma_f32_16x16x32_bf16 v[68:71], v[164:167], v[212:215], v[68:71]
	v_mfma_f32_16x16x32_bf16 v[64:67], v[178:181], v[212:215], v[64:67]
	s_setprio 0
	s_barrier
	s_add_i32 s4, s90, s72
	s_mov_b32 m0, s4
	ds_read_b128 v[182:185], v176 offset:16384
	ds_read_b128 v[186:189], v176 offset:17408
	ds_read_b128 v[190:193], v176 offset:18432
	ds_read_b128 v[194:197], v176 offset:19456
	ds_read_b128 v[198:201], v176 offset:20480
	ds_read_b128 v[202:205], v176 offset:21504
	ds_read_b128 v[206:209], v176 offset:22528
	ds_read_b128 v[212:215], v176 offset:23552
	global_load_lds_dwordx4 v128, s[64:65]
	s_add_i32 m0, s4, 0x2000
	s_add_u32 s4, s64, 0x40000
	s_addc_u32 s5, s65, 0
	s_add_i32 s24, s91, s72
	global_load_lds_dwordx4 v130, s[64:65]
	s_mov_b32 m0, s24
	s_nop 0
	global_load_lds_dwordx4 v128, s[4:5]
	s_add_i32 m0, s24, 0x2000
	s_nop 0
	global_load_lds_dwordx4 v130, s[4:5]
	s_mov_b32 m0, s73
	s_nop 0
	global_load_lds_dwordx4 v128, s[66:67]
	s_mov_b32 m0, s74
	s_nop 0
	global_load_lds_dwordx4 v130, s[66:67]
	s_waitcnt vmcnt(8)
	s_waitcnt lgkmcnt(0)
	s_barrier
	s_setprio 1
	s_waitcnt lgkmcnt(0)
	v_mfma_f32_16x16x32_bf16 v[60:63], v[144:147], v[182:185], v[60:63]
	v_mfma_f32_16x16x32_bf16 v[56:59], v[152:155], v[182:185], v[56:59]
	v_mfma_f32_16x16x32_bf16 v[44:47], v[144:147], v[190:193], v[44:47]
	v_mfma_f32_16x16x32_bf16 v[40:43], v[152:155], v[190:193], v[40:43]
	v_mfma_f32_16x16x32_bf16 v[28:31], v[144:147], v[198:201], v[28:31]
	v_mfma_f32_16x16x32_bf16 v[24:27], v[152:155], v[198:201], v[24:27]
	v_mfma_f32_16x16x32_bf16 v[12:15], v[144:147], v[206:209], v[12:15]
	v_mfma_f32_16x16x32_bf16 v[8:11], v[152:155], v[206:209], v[8:11]
	v_mfma_f32_16x16x32_bf16 v[60:63], v[148:151], v[186:189], v[60:63]
	v_mfma_f32_16x16x32_bf16 v[56:59], v[156:159], v[186:189], v[56:59]
	v_mfma_f32_16x16x32_bf16 v[44:47], v[148:151], v[194:197], v[44:47]
	v_mfma_f32_16x16x32_bf16 v[40:43], v[156:159], v[194:197], v[40:43]
	v_mfma_f32_16x16x32_bf16 v[28:31], v[148:151], v[202:205], v[28:31]
	v_mfma_f32_16x16x32_bf16 v[24:27], v[156:159], v[202:205], v[24:27]
	v_mfma_f32_16x16x32_bf16 v[12:15], v[148:151], v[212:215], v[12:15]
	v_mfma_f32_16x16x32_bf16 v[8:11], v[156:159], v[212:215], v[8:11]
	s_setprio 0
	s_setprio 1
	v_mfma_f32_16x16x32_bf16 v[52:55], v[160:163], v[182:185], v[52:55]
	v_mfma_f32_16x16x32_bf16 v[48:51], v[168:171], v[182:185], v[48:51]
	v_mfma_f32_16x16x32_bf16 v[36:39], v[160:163], v[190:193], v[36:39]
	v_mfma_f32_16x16x32_bf16 v[32:35], v[168:171], v[190:193], v[32:35]
	v_mfma_f32_16x16x32_bf16 v[20:23], v[160:163], v[198:201], v[20:23]
	v_mfma_f32_16x16x32_bf16 v[16:19], v[168:171], v[198:201], v[16:19]
	v_mfma_f32_16x16x32_bf16 v[4:7], v[160:163], v[206:209], v[4:7]
	v_mfma_f32_16x16x32_bf16 v[0:3], v[168:171], v[206:209], v[0:3]
	v_mfma_f32_16x16x32_bf16 v[52:55], v[164:167], v[186:189], v[52:55]
	v_mfma_f32_16x16x32_bf16 v[48:51], v[178:181], v[186:189], v[48:51]
	v_mfma_f32_16x16x32_bf16 v[36:39], v[164:167], v[194:197], v[36:39]
	v_mfma_f32_16x16x32_bf16 v[32:35], v[178:181], v[194:197], v[32:35]
	v_mfma_f32_16x16x32_bf16 v[20:23], v[164:167], v[202:205], v[20:23]
	v_mfma_f32_16x16x32_bf16 v[16:19], v[178:181], v[202:205], v[16:19]
	v_mfma_f32_16x16x32_bf16 v[4:7], v[164:167], v[212:215], v[4:7]
	v_mfma_f32_16x16x32_bf16 v[0:3], v[178:181], v[212:215], v[0:3]
	s_setprio 0
	s_barrier
	s_add_i32 s24, 0, 0x18000
	v_add_u32_e32 v132, s24, v143
	s_add_i32 s25, 0, 0x1c000
	ds_read_b128 v[144:147], v132
	ds_read_b128 v[148:151], v132 offset:1024
	ds_read_b128 v[152:155], v132 offset:2048
	ds_read_b128 v[156:159], v132 offset:3072
	v_add_u32_e32 v132, s25, v143
	ds_read_b128 v[160:163], v132
	ds_read_b128 v[164:167], v132 offset:1024
	ds_read_b128 v[168:171], v132 offset:2048
	ds_read_b128 v[178:181], v132 offset:3072
	s_add_u32 s4, s66, 0x40000
	s_addc_u32 s5, s67, 0
	s_mov_b32 m0, s75
	ds_read_b128 v[182:185], v176 offset:32768
	ds_read_b128 v[186:189], v176 offset:33792
	ds_read_b128 v[190:193], v176 offset:34816
	ds_read_b128 v[194:197], v176 offset:35840
	ds_read_b128 v[198:201], v176 offset:36864
	ds_read_b128 v[202:205], v176 offset:37888
	ds_read_b128 v[206:209], v176 offset:38912
	ds_read_b128 v[212:215], v176 offset:39936
	global_load_lds_dwordx4 v128, s[4:5]
	s_mov_b32 m0, s76
	s_nop 0
	global_load_lds_dwordx4 v130, s[4:5]
	s_waitcnt vmcnt(8)
	s_waitcnt lgkmcnt(0)
	s_barrier
	s_setprio 1
	s_waitcnt lgkmcnt(0)
	v_mfma_f32_16x16x32_bf16 v[124:127], v[144:147], v[182:185], v[124:127]
	v_mfma_f32_16x16x32_bf16 v[120:123], v[152:155], v[182:185], v[120:123]
	v_mfma_f32_16x16x32_bf16 v[108:111], v[144:147], v[190:193], v[108:111]
	v_mfma_f32_16x16x32_bf16 v[104:107], v[152:155], v[190:193], v[104:107]
	v_mfma_f32_16x16x32_bf16 v[92:95], v[144:147], v[198:201], v[92:95]
	v_mfma_f32_16x16x32_bf16 v[88:91], v[152:155], v[198:201], v[88:91]
	v_mfma_f32_16x16x32_bf16 v[76:79], v[144:147], v[206:209], v[76:79]
	v_mfma_f32_16x16x32_bf16 v[72:75], v[152:155], v[206:209], v[72:75]
	v_mfma_f32_16x16x32_bf16 v[124:127], v[148:151], v[186:189], v[124:127]
	v_mfma_f32_16x16x32_bf16 v[120:123], v[156:159], v[186:189], v[120:123]
	v_mfma_f32_16x16x32_bf16 v[108:111], v[148:151], v[194:197], v[108:111]
	v_mfma_f32_16x16x32_bf16 v[104:107], v[156:159], v[194:197], v[104:107]
	v_mfma_f32_16x16x32_bf16 v[92:95], v[148:151], v[202:205], v[92:95]
	v_mfma_f32_16x16x32_bf16 v[88:91], v[156:159], v[202:205], v[88:91]
	v_mfma_f32_16x16x32_bf16 v[76:79], v[148:151], v[212:215], v[76:79]
	v_mfma_f32_16x16x32_bf16 v[72:75], v[156:159], v[212:215], v[72:75]
	s_setprio 0
	s_setprio 1
	v_mfma_f32_16x16x32_bf16 v[116:119], v[160:163], v[182:185], v[116:119]
	v_mfma_f32_16x16x32_bf16 v[112:115], v[168:171], v[182:185], v[112:115]
	v_mfma_f32_16x16x32_bf16 v[100:103], v[160:163], v[190:193], v[100:103]
	v_mfma_f32_16x16x32_bf16 v[96:99], v[168:171], v[190:193], v[96:99]
	v_mfma_f32_16x16x32_bf16 v[84:87], v[160:163], v[198:201], v[84:87]
	v_mfma_f32_16x16x32_bf16 v[80:83], v[168:171], v[198:201], v[80:83]
	v_mfma_f32_16x16x32_bf16 v[68:71], v[160:163], v[206:209], v[68:71]
	v_mfma_f32_16x16x32_bf16 v[64:67], v[168:171], v[206:209], v[64:67]
	v_mfma_f32_16x16x32_bf16 v[116:119], v[164:167], v[186:189], v[116:119]
	v_mfma_f32_16x16x32_bf16 v[112:115], v[178:181], v[186:189], v[112:115]
	v_mfma_f32_16x16x32_bf16 v[100:103], v[164:167], v[194:197], v[100:103]
	v_mfma_f32_16x16x32_bf16 v[96:99], v[178:181], v[194:197], v[96:99]
	v_mfma_f32_16x16x32_bf16 v[84:87], v[164:167], v[202:205], v[84:87]
	v_mfma_f32_16x16x32_bf16 v[80:83], v[178:181], v[202:205], v[80:83]
	v_mfma_f32_16x16x32_bf16 v[68:71], v[164:167], v[212:215], v[68:71]
	v_mfma_f32_16x16x32_bf16 v[64:67], v[178:181], v[212:215], v[64:67]
	s_setprio 0
	s_barrier
	s_add_i32 s4, s24, s72
	s_mov_b32 m0, s4
	ds_read_b128 v[182:185], v176 offset:49152
	ds_read_b128 v[186:189], v176 offset:50176
	ds_read_b128 v[190:193], v176 offset:51200
	ds_read_b128 v[194:197], v176 offset:52224
	ds_read_b128 v[198:201], v176 offset:53248
	ds_read_b128 v[202:205], v176 offset:54272
	ds_read_b128 v[206:209], v176 offset:55296
	ds_read_b128 v[212:215], v176 offset:56320
	global_load_lds_dwordx4 v172, s[64:65]
	s_add_i32 m0, s4, 0x2000
	s_add_u32 s4, s64, 0x40080
	s_addc_u32 s5, s65, 0
	s_add_i32 s24, s25, s72
	global_load_lds_dwordx4 v173, s[64:65]
	s_mov_b32 m0, s24
	s_nop 0
	global_load_lds_dwordx4 v128, s[4:5]
	s_add_i32 m0, s24, 0x2000
	s_nop 0
	global_load_lds_dwordx4 v130, s[4:5]
	s_mov_b32 m0, s82
	s_nop 0
	global_load_lds_dwordx4 v172, s[66:67]
	s_mov_b32 m0, s83
	s_nop 0
	global_load_lds_dwordx4 v173, s[66:67]
	s_waitcnt vmcnt(8)
	s_waitcnt lgkmcnt(0)
	s_barrier
	s_setprio 1
	s_waitcnt lgkmcnt(0)
	v_mfma_f32_16x16x32_bf16 v[60:63], v[144:147], v[182:185], v[60:63]
	v_mfma_f32_16x16x32_bf16 v[56:59], v[152:155], v[182:185], v[56:59]
	v_mfma_f32_16x16x32_bf16 v[44:47], v[144:147], v[190:193], v[44:47]
	v_mfma_f32_16x16x32_bf16 v[40:43], v[152:155], v[190:193], v[40:43]
	v_mfma_f32_16x16x32_bf16 v[28:31], v[144:147], v[198:201], v[28:31]
	v_mfma_f32_16x16x32_bf16 v[24:27], v[152:155], v[198:201], v[24:27]
	v_mfma_f32_16x16x32_bf16 v[12:15], v[144:147], v[206:209], v[12:15]
	v_mfma_f32_16x16x32_bf16 v[8:11], v[152:155], v[206:209], v[8:11]
	v_mfma_f32_16x16x32_bf16 v[60:63], v[148:151], v[186:189], v[60:63]
	v_mfma_f32_16x16x32_bf16 v[56:59], v[156:159], v[186:189], v[56:59]
	v_mfma_f32_16x16x32_bf16 v[44:47], v[148:151], v[194:197], v[44:47]
	v_mfma_f32_16x16x32_bf16 v[40:43], v[156:159], v[194:197], v[40:43]
	v_mfma_f32_16x16x32_bf16 v[28:31], v[148:151], v[202:205], v[28:31]
	v_mfma_f32_16x16x32_bf16 v[24:27], v[156:159], v[202:205], v[24:27]
	v_mfma_f32_16x16x32_bf16 v[12:15], v[148:151], v[212:215], v[12:15]
	v_mfma_f32_16x16x32_bf16 v[8:11], v[156:159], v[212:215], v[8:11]
	s_setprio 0
	s_setprio 1
	v_mfma_f32_16x16x32_bf16 v[52:55], v[160:163], v[182:185], v[52:55]
	v_mfma_f32_16x16x32_bf16 v[48:51], v[168:171], v[182:185], v[48:51]
	v_mfma_f32_16x16x32_bf16 v[36:39], v[160:163], v[190:193], v[36:39]
	v_mfma_f32_16x16x32_bf16 v[32:35], v[168:171], v[190:193], v[32:35]
	v_mfma_f32_16x16x32_bf16 v[20:23], v[160:163], v[198:201], v[20:23]
	v_mfma_f32_16x16x32_bf16 v[16:19], v[168:171], v[198:201], v[16:19]
	v_mfma_f32_16x16x32_bf16 v[4:7], v[160:163], v[206:209], v[4:7]
	v_mfma_f32_16x16x32_bf16 v[0:3], v[168:171], v[206:209], v[0:3]
	v_mfma_f32_16x16x32_bf16 v[52:55], v[164:167], v[186:189], v[52:55]
	v_mfma_f32_16x16x32_bf16 v[48:51], v[178:181], v[186:189], v[48:51]
	v_mfma_f32_16x16x32_bf16 v[36:39], v[164:167], v[194:197], v[36:39]
	v_mfma_f32_16x16x32_bf16 v[32:35], v[178:181], v[194:197], v[32:35]
	v_mfma_f32_16x16x32_bf16 v[20:23], v[164:167], v[202:205], v[20:23]
	v_mfma_f32_16x16x32_bf16 v[16:19], v[178:181], v[202:205], v[16:19]
	v_mfma_f32_16x16x32_bf16 v[4:7], v[164:167], v[212:215], v[4:7]
	v_mfma_f32_16x16x32_bf16 v[0:3], v[178:181], v[212:215], v[0:3]
	s_setprio 0
	s_barrier
	s_add_i32 s63, s63, 2
	s_add_u32 s14, s14, 0x100
	s_addc_u32 s15, s15, 0
	s_add_u32 s55, s55, 0x100
	s_addc_u32 s57, s57, 0
	s_cmp_gt_u32 s63, 13
	s_cbranch_scc0 .LBB0_1412
	s_and_b64 vcc, exec, s[20:21]
	s_cbranch_vccz .LBB0_1415
	s_barrier

.LBB0_1704:
	v_add_u32_e32 v208, 0x80, v130
	v_add_u32_e32 v209, 0x80, v134
	v_add_u32_e32 v220, 0x80, v128
	v_add_u32_e32 v221, 0x80, v132
	ds_read_b128 v[152:155], v147
	ds_read_b128 v[156:159], v147 offset:1024
	ds_read_b128 v[160:163], v147 offset:2048
	ds_read_b128 v[164:167], v147 offset:3072
	ds_read_b128 v[168:171], v149
	ds_read_b128 v[172:175], v149 offset:1024
	ds_read_b128 v[176:179], v149 offset:2048
	ds_read_b128 v[180:183], v149 offset:3072
	s_add_u32 s4, s60, 0xfffc0080
	s_addc_u32 s5, s61, -1
	s_cmp_eq_u32 s85, 12
	s_cselect_b32 s65, s13, s5
	s_cselect_b32 s64, s55, s4
	s_cselect_b32 s63, s23, s83
	s_cselect_b32 s62, s81, s82
	s_add_i32 m0, s47, 0xc000
	ds_read_b128 v[184:187], v151
	ds_read_b128 v[188:191], v151 offset:1024
	ds_read_b128 v[192:195], v151 offset:2048
	ds_read_b128 v[196:199], v151 offset:3072
	ds_read_b128 v[200:203], v151 offset:4096
	ds_read_b128 v[204:207], v151 offset:5120
	ds_read_b128 v[212:215], v151 offset:6144
	ds_read_b128 v[216:219], v151 offset:7168
	global_load_lds_dwordx4 v136, s[60:61]
	s_add_i32 m0, s47, 0xe000
	s_nop 0
	global_load_lds_dwordx4 v138, s[60:61]
	s_waitcnt vmcnt(8)
	s_waitcnt lgkmcnt(0)
	s_barrier
	s_setprio 1
	s_waitcnt lgkmcnt(0)
	v_mfma_f32_16x16x32_bf16 v[124:127], v[152:155], v[184:187], v[124:127]
	v_mfma_f32_16x16x32_bf16 v[120:123], v[160:163], v[184:187], v[120:123]
	v_mfma_f32_16x16x32_bf16 v[108:111], v[152:155], v[192:195], v[108:111]
	v_mfma_f32_16x16x32_bf16 v[104:107], v[160:163], v[192:195], v[104:107]
	v_mfma_f32_16x16x32_bf16 v[92:95], v[152:155], v[200:203], v[92:95]
	v_mfma_f32_16x16x32_bf16 v[88:91], v[160:163], v[200:203], v[88:91]
	v_mfma_f32_16x16x32_bf16 v[76:79], v[152:155], v[212:215], v[76:79]
	v_mfma_f32_16x16x32_bf16 v[72:75], v[160:163], v[212:215], v[72:75]
	v_mfma_f32_16x16x32_bf16 v[124:127], v[156:159], v[188:191], v[124:127]
	v_mfma_f32_16x16x32_bf16 v[120:123], v[164:167], v[188:191], v[120:123]
	v_mfma_f32_16x16x32_bf16 v[108:111], v[156:159], v[196:199], v[108:111]
	v_mfma_f32_16x16x32_bf16 v[104:107], v[164:167], v[196:199], v[104:107]
	v_mfma_f32_16x16x32_bf16 v[92:95], v[156:159], v[204:207], v[92:95]
	v_mfma_f32_16x16x32_bf16 v[88:91], v[164:167], v[204:207], v[88:91]
	v_mfma_f32_16x16x32_bf16 v[76:79], v[156:159], v[216:219], v[76:79]
	v_mfma_f32_16x16x32_bf16 v[72:75], v[164:167], v[216:219], v[72:75]
	s_setprio 0
	s_setprio 1
	v_mfma_f32_16x16x32_bf16 v[116:119], v[168:171], v[184:187], v[116:119]
	v_mfma_f32_16x16x32_bf16 v[112:115], v[176:179], v[184:187], v[112:115]
	v_mfma_f32_16x16x32_bf16 v[100:103], v[168:171], v[192:195], v[100:103]
	v_mfma_f32_16x16x32_bf16 v[96:99], v[176:179], v[192:195], v[96:99]
	v_mfma_f32_16x16x32_bf16 v[84:87], v[168:171], v[200:203], v[84:87]
	v_mfma_f32_16x16x32_bf16 v[80:83], v[176:179], v[200:203], v[80:83]
	v_mfma_f32_16x16x32_bf16 v[68:71], v[168:171], v[212:215], v[68:71]
	v_mfma_f32_16x16x32_bf16 v[64:67], v[176:179], v[212:215], v[64:67]
	v_mfma_f32_16x16x32_bf16 v[116:119], v[172:175], v[188:191], v[116:119]
	v_mfma_f32_16x16x32_bf16 v[112:115], v[180:183], v[188:191], v[112:115]
	v_mfma_f32_16x16x32_bf16 v[100:103], v[172:175], v[196:199], v[100:103]
	v_mfma_f32_16x16x32_bf16 v[96:99], v[180:183], v[196:199], v[96:99]
	v_mfma_f32_16x16x32_bf16 v[84:87], v[172:175], v[204:207], v[84:87]
	v_mfma_f32_16x16x32_bf16 v[80:83], v[180:183], v[204:207], v[80:83]
	v_mfma_f32_16x16x32_bf16 v[68:71], v[172:175], v[216:219], v[68:71]
	v_mfma_f32_16x16x32_bf16 v[64:67], v[180:183], v[216:219], v[64:67]
	s_setprio 0
	s_barrier
	s_add_i32 s4, s76, s46
	s_mov_b32 m0, s4
	ds_read_b128 v[184:187], v151 offset:16384
	ds_read_b128 v[188:191], v151 offset:17408
	ds_read_b128 v[192:195], v151 offset:18432
	ds_read_b128 v[196:199], v151 offset:19456
	ds_read_b128 v[200:203], v151 offset:20480
	ds_read_b128 v[204:207], v151 offset:21504
	ds_read_b128 v[212:215], v151 offset:22528
	ds_read_b128 v[216:219], v151 offset:23552
	global_load_lds_dwordx4 v130, s[62:63]
	s_add_i32 m0, s4, 0x2000
	s_add_u32 s4, s62, 0x40000
	s_addc_u32 s5, s63, 0
	s_add_i32 s24, s77, s46
	global_load_lds_dwordx4 v134, s[62:63]
	s_mov_b32 m0, s24
	s_nop 0
	global_load_lds_dwordx4 v130, s[4:5]
	s_add_i32 m0, s24, 0x2000
	s_nop 0
	global_load_lds_dwordx4 v134, s[4:5]
	s_mov_b32 m0, s47
	s_nop 0
	global_load_lds_dwordx4 v128, s[64:65]
	s_mov_b32 m0, s66
	s_nop 0
	global_load_lds_dwordx4 v132, s[64:65]
	s_waitcnt vmcnt(8)
	s_waitcnt lgkmcnt(0)
	s_barrier
	s_setprio 1
	s_waitcnt lgkmcnt(0)
	v_mfma_f32_16x16x32_bf16 v[60:63], v[152:155], v[184:187], v[60:63]
	v_mfma_f32_16x16x32_bf16 v[56:59], v[160:163], v[184:187], v[56:59]
	v_mfma_f32_16x16x32_bf16 v[44:47], v[152:155], v[192:195], v[44:47]
	v_mfma_f32_16x16x32_bf16 v[40:43], v[160:163], v[192:195], v[40:43]
	v_mfma_f32_16x16x32_bf16 v[28:31], v[152:155], v[200:203], v[28:31]
	v_mfma_f32_16x16x32_bf16 v[24:27], v[160:163], v[200:203], v[24:27]
	v_mfma_f32_16x16x32_bf16 v[12:15], v[152:155], v[212:215], v[12:15]
	v_mfma_f32_16x16x32_bf16 v[8:11], v[160:163], v[212:215], v[8:11]
	v_mfma_f32_16x16x32_bf16 v[60:63], v[156:159], v[188:191], v[60:63]
	v_mfma_f32_16x16x32_bf16 v[56:59], v[164:167], v[188:191], v[56:59]
	v_mfma_f32_16x16x32_bf16 v[44:47], v[156:159], v[196:199], v[44:47]
	v_mfma_f32_16x16x32_bf16 v[40:43], v[164:167], v[196:199], v[40:43]
	v_mfma_f32_16x16x32_bf16 v[28:31], v[156:159], v[204:207], v[28:31]
	v_mfma_f32_16x16x32_bf16 v[24:27], v[164:167], v[204:207], v[24:27]
	v_mfma_f32_16x16x32_bf16 v[12:15], v[156:159], v[216:219], v[12:15]
	v_mfma_f32_16x16x32_bf16 v[8:11], v[164:167], v[216:219], v[8:11]
	s_setprio 0
	s_setprio 1
	v_mfma_f32_16x16x32_bf16 v[52:55], v[168:171], v[184:187], v[52:55]
	v_mfma_f32_16x16x32_bf16 v[48:51], v[176:179], v[184:187], v[48:51]
	v_mfma_f32_16x16x32_bf16 v[36:39], v[168:171], v[192:195], v[36:39]
	v_mfma_f32_16x16x32_bf16 v[32:35], v[176:179], v[192:195], v[32:35]
	v_mfma_f32_16x16x32_bf16 v[20:23], v[168:171], v[200:203], v[20:23]
	v_mfma_f32_16x16x32_bf16 v[16:19], v[176:179], v[200:203], v[16:19]
	v_mfma_f32_16x16x32_bf16 v[4:7], v[168:171], v[212:215], v[4:7]
	v_mfma_f32_16x16x32_bf16 v[0:3], v[176:179], v[212:215], v[0:3]
	v_mfma_f32_16x16x32_bf16 v[52:55], v[172:175], v[188:191], v[52:55]
	v_mfma_f32_16x16x32_bf16 v[48:51], v[180:183], v[188:191], v[48:51]
	v_mfma_f32_16x16x32_bf16 v[36:39], v[172:175], v[196:199], v[36:39]
	v_mfma_f32_16x16x32_bf16 v[32:35], v[180:183], v[196:199], v[32:35]
	v_mfma_f32_16x16x32_bf16 v[20:23], v[172:175], v[204:207], v[20:23]
	v_mfma_f32_16x16x32_bf16 v[16:19], v[180:183], v[204:207], v[16:19]
	v_mfma_f32_16x16x32_bf16 v[4:7], v[172:175], v[216:219], v[4:7]
	v_mfma_f32_16x16x32_bf16 v[0:3], v[180:183], v[216:219], v[0:3]
	s_setprio 0
	s_barrier
	s_add_i32 s24, 0, 0x18000
	v_add_u32_e32 v146, s24, v145
	s_add_i32 s25, 0, 0x1c000
	ds_read_b128 v[152:155], v146
	ds_read_b128 v[156:159], v146 offset:1024
	ds_read_b128 v[160:163], v146 offset:2048
	ds_read_b128 v[164:167], v146 offset:3072
	v_add_u32_e32 v146, s25, v145
	ds_read_b128 v[168:171], v146
	ds_read_b128 v[172:175], v146 offset:1024
	ds_read_b128 v[176:179], v146 offset:2048
	ds_read_b128 v[180:183], v146 offset:3072
	s_add_u32 s4, s64, 0x40000
	s_addc_u32 s5, s65, 0
	s_mov_b32 m0, s67
	ds_read_b128 v[184:187], v151 offset:32768
	ds_read_b128 v[188:191], v151 offset:33792
	ds_read_b128 v[192:195], v151 offset:34816
	ds_read_b128 v[196:199], v151 offset:35840
	ds_read_b128 v[200:203], v151 offset:36864
	ds_read_b128 v[204:207], v151 offset:37888
	ds_read_b128 v[212:215], v151 offset:38912
	ds_read_b128 v[216:219], v151 offset:39936
	global_load_lds_dwordx4 v128, s[4:5]
	s_mov_b32 m0, s68
	s_nop 0
	global_load_lds_dwordx4 v132, s[4:5]
	s_waitcnt vmcnt(8)
	s_waitcnt lgkmcnt(0)
	s_barrier
	s_setprio 1
	s_waitcnt lgkmcnt(0)
	v_mfma_f32_16x16x32_bf16 v[124:127], v[152:155], v[184:187], v[124:127]
	v_mfma_f32_16x16x32_bf16 v[120:123], v[160:163], v[184:187], v[120:123]
	v_mfma_f32_16x16x32_bf16 v[108:111], v[152:155], v[192:195], v[108:111]
	v_mfma_f32_16x16x32_bf16 v[104:107], v[160:163], v[192:195], v[104:107]
	v_mfma_f32_16x16x32_bf16 v[92:95], v[152:155], v[200:203], v[92:95]
	v_mfma_f32_16x16x32_bf16 v[88:91], v[160:163], v[200:203], v[88:91]
	v_mfma_f32_16x16x32_bf16 v[76:79], v[152:155], v[212:215], v[76:79]
	v_mfma_f32_16x16x32_bf16 v[72:75], v[160:163], v[212:215], v[72:75]
	v_mfma_f32_16x16x32_bf16 v[124:127], v[156:159], v[188:191], v[124:127]
	v_mfma_f32_16x16x32_bf16 v[120:123], v[164:167], v[188:191], v[120:123]
	v_mfma_f32_16x16x32_bf16 v[108:111], v[156:159], v[196:199], v[108:111]
	v_mfma_f32_16x16x32_bf16 v[104:107], v[164:167], v[196:199], v[104:107]
	v_mfma_f32_16x16x32_bf16 v[92:95], v[156:159], v[204:207], v[92:95]
	v_mfma_f32_16x16x32_bf16 v[88:91], v[164:167], v[204:207], v[88:91]
	v_mfma_f32_16x16x32_bf16 v[76:79], v[156:159], v[216:219], v[76:79]
	v_mfma_f32_16x16x32_bf16 v[72:75], v[164:167], v[216:219], v[72:75]
	s_setprio 0
	s_setprio 1
	v_mfma_f32_16x16x32_bf16 v[116:119], v[168:171], v[184:187], v[116:119]
	v_mfma_f32_16x16x32_bf16 v[112:115], v[176:179], v[184:187], v[112:115]
	v_mfma_f32_16x16x32_bf16 v[100:103], v[168:171], v[192:195], v[100:103]
	v_mfma_f32_16x16x32_bf16 v[96:99], v[176:179], v[192:195], v[96:99]
	v_mfma_f32_16x16x32_bf16 v[84:87], v[168:171], v[200:203], v[84:87]
	v_mfma_f32_16x16x32_bf16 v[80:83], v[176:179], v[200:203], v[80:83]
	v_mfma_f32_16x16x32_bf16 v[68:71], v[168:171], v[212:215], v[68:71]
	v_mfma_f32_16x16x32_bf16 v[64:67], v[176:179], v[212:215], v[64:67]
	v_mfma_f32_16x16x32_bf16 v[116:119], v[172:175], v[188:191], v[116:119]
	v_mfma_f32_16x16x32_bf16 v[112:115], v[180:183], v[188:191], v[112:115]
	v_mfma_f32_16x16x32_bf16 v[100:103], v[172:175], v[196:199], v[100:103]
	v_mfma_f32_16x16x32_bf16 v[96:99], v[180:183], v[196:199], v[96:99]
	v_mfma_f32_16x16x32_bf16 v[84:87], v[172:175], v[204:207], v[84:87]
	v_mfma_f32_16x16x32_bf16 v[80:83], v[180:183], v[204:207], v[80:83]
	v_mfma_f32_16x16x32_bf16 v[68:71], v[172:175], v[216:219], v[68:71]
	v_mfma_f32_16x16x32_bf16 v[64:67], v[180:183], v[216:219], v[64:67]
	s_setprio 0
	s_barrier
	s_add_i32 s4, s24, s46
	s_mov_b32 m0, s4
	ds_read_b128 v[184:187], v151 offset:49152
	ds_read_b128 v[188:191], v151 offset:50176
	ds_read_b128 v[192:195], v151 offset:51200
	ds_read_b128 v[196:199], v151 offset:52224
	ds_read_b128 v[200:203], v151 offset:53248
	ds_read_b128 v[204:207], v151 offset:54272
	ds_read_b128 v[212:215], v151 offset:55296
	ds_read_b128 v[216:219], v151 offset:56320
	global_load_lds_dwordx4 v208, s[62:63]
	s_add_i32 m0, s4, 0x2000
	s_add_u32 s4, s62, 0x40080
	s_addc_u32 s5, s63, 0
	s_add_i32 s24, s25, s46
	global_load_lds_dwordx4 v209, s[62:63]
	s_mov_b32 m0, s24
	s_nop 0
	global_load_lds_dwordx4 v130, s[4:5]
	s_add_i32 m0, s24, 0x2000
	s_nop 0
	global_load_lds_dwordx4 v134, s[4:5]
	s_mov_b32 m0, s72
	s_nop 0
	global_load_lds_dwordx4 v220, s[64:65]
	s_mov_b32 m0, s73
	s_nop 0
	global_load_lds_dwordx4 v221, s[64:65]
	s_waitcnt vmcnt(8)
	s_waitcnt lgkmcnt(0)
	s_barrier
	s_setprio 1
	s_waitcnt lgkmcnt(0)
	v_mfma_f32_16x16x32_bf16 v[60:63], v[152:155], v[184:187], v[60:63]
	v_mfma_f32_16x16x32_bf16 v[56:59], v[160:163], v[184:187], v[56:59]
	v_mfma_f32_16x16x32_bf16 v[44:47], v[152:155], v[192:195], v[44:47]
	v_mfma_f32_16x16x32_bf16 v[40:43], v[160:163], v[192:195], v[40:43]
	v_mfma_f32_16x16x32_bf16 v[28:31], v[152:155], v[200:203], v[28:31]
	v_mfma_f32_16x16x32_bf16 v[24:27], v[160:163], v[200:203], v[24:27]
	v_mfma_f32_16x16x32_bf16 v[12:15], v[152:155], v[212:215], v[12:15]
	v_mfma_f32_16x16x32_bf16 v[8:11], v[160:163], v[212:215], v[8:11]
	v_mfma_f32_16x16x32_bf16 v[60:63], v[156:159], v[188:191], v[60:63]
	v_mfma_f32_16x16x32_bf16 v[56:59], v[164:167], v[188:191], v[56:59]
	v_mfma_f32_16x16x32_bf16 v[44:47], v[156:159], v[196:199], v[44:47]
	v_mfma_f32_16x16x32_bf16 v[40:43], v[164:167], v[196:199], v[40:43]
	v_mfma_f32_16x16x32_bf16 v[28:31], v[156:159], v[204:207], v[28:31]
	v_mfma_f32_16x16x32_bf16 v[24:27], v[164:167], v[204:207], v[24:27]
	v_mfma_f32_16x16x32_bf16 v[12:15], v[156:159], v[216:219], v[12:15]
	v_mfma_f32_16x16x32_bf16 v[8:11], v[164:167], v[216:219], v[8:11]
	s_setprio 0
	s_setprio 1
	v_mfma_f32_16x16x32_bf16 v[52:55], v[168:171], v[184:187], v[52:55]
	v_mfma_f32_16x16x32_bf16 v[48:51], v[176:179], v[184:187], v[48:51]
	v_mfma_f32_16x16x32_bf16 v[36:39], v[168:171], v[192:195], v[36:39]
	v_mfma_f32_16x16x32_bf16 v[32:35], v[176:179], v[192:195], v[32:35]
	v_mfma_f32_16x16x32_bf16 v[20:23], v[168:171], v[200:203], v[20:23]
	v_mfma_f32_16x16x32_bf16 v[16:19], v[176:179], v[200:203], v[16:19]
	v_mfma_f32_16x16x32_bf16 v[4:7], v[168:171], v[212:215], v[4:7]
	v_mfma_f32_16x16x32_bf16 v[0:3], v[176:179], v[212:215], v[0:3]
	v_mfma_f32_16x16x32_bf16 v[52:55], v[172:175], v[188:191], v[52:55]
	v_mfma_f32_16x16x32_bf16 v[48:51], v[180:183], v[188:191], v[48:51]
	v_mfma_f32_16x16x32_bf16 v[36:39], v[172:175], v[196:199], v[36:39]
	v_mfma_f32_16x16x32_bf16 v[32:35], v[180:183], v[196:199], v[32:35]
	v_mfma_f32_16x16x32_bf16 v[20:23], v[172:175], v[204:207], v[20:23]
	v_mfma_f32_16x16x32_bf16 v[16:19], v[180:183], v[204:207], v[16:19]
	v_mfma_f32_16x16x32_bf16 v[4:7], v[172:175], v[216:219], v[4:7]
	v_mfma_f32_16x16x32_bf16 v[0:3], v[180:183], v[216:219], v[0:3]
	s_setprio 0
	s_barrier
	s_add_i32 s85, s85, 2
	s_add_u32 s60, s60, 0x100
	s_addc_u32 s61, s61, 0
	s_add_u32 s82, s82, 0x100
	s_addc_u32 s83, s83, 0
	s_cmp_gt_u32 s85, 13
	s_cbranch_scc0 .LBB0_1704
	s_and_b64 vcc, exec, s[18:19]
	s_cbranch_vccz .LBB0_1707
	s_barrier

.LBB0_1790:
	v_add_u32_e32 v208, 0x80, v178
	v_add_u32_e32 v209, 0x80, v182
	v_add_u32_e32 v216, 0x80, v176
	v_add_u32_e32 v217, 0x80, v180
	ds_read_b128 v[128:131], v213
	ds_read_b128 v[132:135], v213 offset:1024
	ds_read_b128 v[136:139], v213 offset:2048
	ds_read_b128 v[140:143], v213 offset:3072
	ds_read_b128 v[144:147], v214
	ds_read_b128 v[148:151], v214 offset:1024
	ds_read_b128 v[152:155], v214 offset:2048
	ds_read_b128 v[156:159], v214 offset:3072
	s_add_u32 s58, s56, 0x100
	s_addc_u32 s59, s57, 0
	s_cmp_eq_u32 s81, 40
	s_cselect_b32 s63, s13, s59
	s_cselect_b32 s62, s12, s58
	s_cselect_b32 s61, s55, s80
	s_cselect_b32 s60, s54, s79
	s_add_i32 m0, s33, 0xc000
	ds_read_b128 v[160:163], v215
	ds_read_b128 v[164:167], v215 offset:1024
	ds_read_b128 v[168:171], v215 offset:2048
	ds_read_b128 v[172:175], v215 offset:3072
	ds_read_b128 v[192:195], v215 offset:4096
	ds_read_b128 v[196:199], v215 offset:5120
	ds_read_b128 v[200:203], v215 offset:6144
	ds_read_b128 v[204:207], v215 offset:7168
	global_load_lds_dwordx4 v184, s[56:57]
	s_add_i32 m0, s33, 0xe000
	s_nop 0
	global_load_lds_dwordx4 v186, s[56:57]
	s_waitcnt vmcnt(8)
	s_waitcnt lgkmcnt(0)
	s_barrier
	s_setprio 1
	s_waitcnt lgkmcnt(0)
	v_mfma_f32_16x16x32_bf16 v[124:127], v[128:131], v[160:163], v[124:127]
	v_mfma_f32_16x16x32_bf16 v[120:123], v[136:139], v[160:163], v[120:123]
	v_mfma_f32_16x16x32_bf16 v[108:111], v[128:131], v[168:171], v[108:111]
	v_mfma_f32_16x16x32_bf16 v[104:107], v[136:139], v[168:171], v[104:107]
	v_mfma_f32_16x16x32_bf16 v[92:95], v[128:131], v[192:195], v[92:95]
	v_mfma_f32_16x16x32_bf16 v[88:91], v[136:139], v[192:195], v[88:91]
	v_mfma_f32_16x16x32_bf16 v[76:79], v[128:131], v[200:203], v[76:79]
	v_mfma_f32_16x16x32_bf16 v[72:75], v[136:139], v[200:203], v[72:75]
	v_mfma_f32_16x16x32_bf16 v[124:127], v[132:135], v[164:167], v[124:127]
	v_mfma_f32_16x16x32_bf16 v[120:123], v[140:143], v[164:167], v[120:123]
	v_mfma_f32_16x16x32_bf16 v[108:111], v[132:135], v[172:175], v[108:111]
	v_mfma_f32_16x16x32_bf16 v[104:107], v[140:143], v[172:175], v[104:107]
	v_mfma_f32_16x16x32_bf16 v[92:95], v[132:135], v[196:199], v[92:95]
	v_mfma_f32_16x16x32_bf16 v[88:91], v[140:143], v[196:199], v[88:91]
	v_mfma_f32_16x16x32_bf16 v[76:79], v[132:135], v[204:207], v[76:79]
	v_mfma_f32_16x16x32_bf16 v[72:75], v[140:143], v[204:207], v[72:75]
	s_setprio 0
	s_setprio 1
	v_mfma_f32_16x16x32_bf16 v[116:119], v[144:147], v[160:163], v[116:119]
	v_mfma_f32_16x16x32_bf16 v[112:115], v[152:155], v[160:163], v[112:115]
	v_mfma_f32_16x16x32_bf16 v[100:103], v[144:147], v[168:171], v[100:103]
	v_mfma_f32_16x16x32_bf16 v[96:99], v[152:155], v[168:171], v[96:99]
	v_mfma_f32_16x16x32_bf16 v[84:87], v[144:147], v[192:195], v[84:87]
	v_mfma_f32_16x16x32_bf16 v[80:83], v[152:155], v[192:195], v[80:83]
	v_mfma_f32_16x16x32_bf16 v[68:71], v[144:147], v[200:203], v[68:71]
	v_mfma_f32_16x16x32_bf16 v[64:67], v[152:155], v[200:203], v[64:67]
	v_mfma_f32_16x16x32_bf16 v[116:119], v[148:151], v[164:167], v[116:119]
	v_mfma_f32_16x16x32_bf16 v[112:115], v[156:159], v[164:167], v[112:115]
	v_mfma_f32_16x16x32_bf16 v[100:103], v[148:151], v[172:175], v[100:103]
	v_mfma_f32_16x16x32_bf16 v[96:99], v[156:159], v[172:175], v[96:99]
	v_mfma_f32_16x16x32_bf16 v[84:87], v[148:151], v[196:199], v[84:87]
	v_mfma_f32_16x16x32_bf16 v[80:83], v[156:159], v[196:199], v[80:83]
	v_mfma_f32_16x16x32_bf16 v[68:71], v[148:151], v[204:207], v[68:71]
	v_mfma_f32_16x16x32_bf16 v[64:67], v[156:159], v[204:207], v[64:67]
	s_setprio 0
	s_barrier
	s_add_i32 s4, s73, s3
	s_mov_b32 m0, s4
	ds_read_b128 v[160:163], v215 offset:16384
	ds_read_b128 v[164:167], v215 offset:17408
	ds_read_b128 v[168:171], v215 offset:18432
	ds_read_b128 v[172:175], v215 offset:19456
	ds_read_b128 v[192:195], v215 offset:20480
	ds_read_b128 v[196:199], v215 offset:21504
	ds_read_b128 v[200:203], v215 offset:22528
	ds_read_b128 v[204:207], v215 offset:23552
	global_load_lds_dwordx4 v178, s[60:61]
	s_add_i32 m0, s4, 0x2000
	s_add_u32 s4, s60, 0xb0000
	s_addc_u32 s5, s61, 0
	s_add_i32 s24, s74, s3
	global_load_lds_dwordx4 v182, s[60:61]
	s_mov_b32 m0, s24
	s_nop 0
	global_load_lds_dwordx4 v178, s[4:5]
	s_add_i32 m0, s24, 0x2000
	s_nop 0
	global_load_lds_dwordx4 v182, s[4:5]
	s_mov_b32 m0, s33
	s_nop 0
	global_load_lds_dwordx4 v176, s[62:63]
	s_mov_b32 m0, s46
	s_nop 0
	global_load_lds_dwordx4 v180, s[62:63]
	s_waitcnt vmcnt(8)
	s_waitcnt lgkmcnt(0)
	s_barrier
	s_setprio 1
	s_waitcnt lgkmcnt(0)
	v_mfma_f32_16x16x32_bf16 v[60:63], v[128:131], v[160:163], v[60:63]
	v_mfma_f32_16x16x32_bf16 v[56:59], v[136:139], v[160:163], v[56:59]
	v_mfma_f32_16x16x32_bf16 v[44:47], v[128:131], v[168:171], v[44:47]
	v_mfma_f32_16x16x32_bf16 v[40:43], v[136:139], v[168:171], v[40:43]
	v_mfma_f32_16x16x32_bf16 v[28:31], v[128:131], v[192:195], v[28:31]
	v_mfma_f32_16x16x32_bf16 v[24:27], v[136:139], v[192:195], v[24:27]
	v_mfma_f32_16x16x32_bf16 v[12:15], v[128:131], v[200:203], v[12:15]
	v_mfma_f32_16x16x32_bf16 v[8:11], v[136:139], v[200:203], v[8:11]
	v_mfma_f32_16x16x32_bf16 v[60:63], v[132:135], v[164:167], v[60:63]
	v_mfma_f32_16x16x32_bf16 v[56:59], v[140:143], v[164:167], v[56:59]
	v_mfma_f32_16x16x32_bf16 v[44:47], v[132:135], v[172:175], v[44:47]
	v_mfma_f32_16x16x32_bf16 v[40:43], v[140:143], v[172:175], v[40:43]
	v_mfma_f32_16x16x32_bf16 v[28:31], v[132:135], v[196:199], v[28:31]
	v_mfma_f32_16x16x32_bf16 v[24:27], v[140:143], v[196:199], v[24:27]
	v_mfma_f32_16x16x32_bf16 v[12:15], v[132:135], v[204:207], v[12:15]
	v_mfma_f32_16x16x32_bf16 v[8:11], v[140:143], v[204:207], v[8:11]
	s_setprio 0
	s_setprio 1
	v_mfma_f32_16x16x32_bf16 v[52:55], v[144:147], v[160:163], v[52:55]
	v_mfma_f32_16x16x32_bf16 v[48:51], v[152:155], v[160:163], v[48:51]
	v_mfma_f32_16x16x32_bf16 v[36:39], v[144:147], v[168:171], v[36:39]
	v_mfma_f32_16x16x32_bf16 v[32:35], v[152:155], v[168:171], v[32:35]
	v_mfma_f32_16x16x32_bf16 v[20:23], v[144:147], v[192:195], v[20:23]
	v_mfma_f32_16x16x32_bf16 v[16:19], v[152:155], v[192:195], v[16:19]
	v_mfma_f32_16x16x32_bf16 v[4:7], v[144:147], v[200:203], v[4:7]
	v_mfma_f32_16x16x32_bf16 v[0:3], v[152:155], v[200:203], v[0:3]
	v_mfma_f32_16x16x32_bf16 v[52:55], v[148:151], v[164:167], v[52:55]
	v_mfma_f32_16x16x32_bf16 v[48:51], v[156:159], v[164:167], v[48:51]
	v_mfma_f32_16x16x32_bf16 v[36:39], v[148:151], v[172:175], v[36:39]
	v_mfma_f32_16x16x32_bf16 v[32:35], v[156:159], v[172:175], v[32:35]
	v_mfma_f32_16x16x32_bf16 v[20:23], v[148:151], v[196:199], v[20:23]
	v_mfma_f32_16x16x32_bf16 v[16:19], v[156:159], v[196:199], v[16:19]
	v_mfma_f32_16x16x32_bf16 v[4:7], v[148:151], v[204:207], v[4:7]
	v_mfma_f32_16x16x32_bf16 v[0:3], v[156:159], v[204:207], v[0:3]
	s_setprio 0
	s_barrier
	s_add_i32 s24, 0, 0x18000
	s_add_i32 s25, 0, 0x1c000
	v_add_u32_e32 v140, s24, v212
	v_add_u32_e32 v156, s25, v212
	ds_read_b128 v[128:131], v140
	ds_read_b128 v[132:135], v140 offset:1024
	ds_read_b128 v[136:139], v140 offset:2048
	ds_read_b128 v[140:143], v140 offset:3072
	ds_read_b128 v[144:147], v156
	ds_read_b128 v[148:151], v156 offset:1024
	ds_read_b128 v[152:155], v156 offset:2048
	ds_read_b128 v[156:159], v156 offset:3072
	s_add_u32 s4, s62, 0xb0000
	s_addc_u32 s5, s63, 0
	s_mov_b32 m0, s47
	ds_read_b128 v[160:163], v215 offset:32768
	ds_read_b128 v[164:167], v215 offset:33792
	ds_read_b128 v[168:171], v215 offset:34816
	ds_read_b128 v[172:175], v215 offset:35840
	ds_read_b128 v[192:195], v215 offset:36864
	ds_read_b128 v[196:199], v215 offset:37888
	ds_read_b128 v[200:203], v215 offset:38912
	ds_read_b128 v[204:207], v215 offset:39936
	global_load_lds_dwordx4 v176, s[4:5]
	s_mov_b32 m0, s64
	s_nop 0
	global_load_lds_dwordx4 v180, s[4:5]
	s_waitcnt vmcnt(8)
	s_waitcnt lgkmcnt(0)
	s_barrier
	s_setprio 1
	s_waitcnt lgkmcnt(0)
	v_mfma_f32_16x16x32_bf16 v[124:127], v[128:131], v[160:163], v[124:127]
	v_mfma_f32_16x16x32_bf16 v[120:123], v[136:139], v[160:163], v[120:123]
	v_mfma_f32_16x16x32_bf16 v[108:111], v[128:131], v[168:171], v[108:111]
	v_mfma_f32_16x16x32_bf16 v[104:107], v[136:139], v[168:171], v[104:107]
	v_mfma_f32_16x16x32_bf16 v[92:95], v[128:131], v[192:195], v[92:95]
	v_mfma_f32_16x16x32_bf16 v[88:91], v[136:139], v[192:195], v[88:91]
	v_mfma_f32_16x16x32_bf16 v[76:79], v[128:131], v[200:203], v[76:79]
	v_mfma_f32_16x16x32_bf16 v[72:75], v[136:139], v[200:203], v[72:75]
	v_mfma_f32_16x16x32_bf16 v[124:127], v[132:135], v[164:167], v[124:127]
	v_mfma_f32_16x16x32_bf16 v[120:123], v[140:143], v[164:167], v[120:123]
	v_mfma_f32_16x16x32_bf16 v[108:111], v[132:135], v[172:175], v[108:111]
	v_mfma_f32_16x16x32_bf16 v[104:107], v[140:143], v[172:175], v[104:107]
	v_mfma_f32_16x16x32_bf16 v[92:95], v[132:135], v[196:199], v[92:95]
	v_mfma_f32_16x16x32_bf16 v[88:91], v[140:143], v[196:199], v[88:91]
	v_mfma_f32_16x16x32_bf16 v[76:79], v[132:135], v[204:207], v[76:79]
	v_mfma_f32_16x16x32_bf16 v[72:75], v[140:143], v[204:207], v[72:75]
	s_setprio 0
	s_setprio 1
	v_mfma_f32_16x16x32_bf16 v[116:119], v[144:147], v[160:163], v[116:119]
	v_mfma_f32_16x16x32_bf16 v[112:115], v[152:155], v[160:163], v[112:115]
	v_mfma_f32_16x16x32_bf16 v[100:103], v[144:147], v[168:171], v[100:103]
	v_mfma_f32_16x16x32_bf16 v[96:99], v[152:155], v[168:171], v[96:99]
	v_mfma_f32_16x16x32_bf16 v[84:87], v[144:147], v[192:195], v[84:87]
	v_mfma_f32_16x16x32_bf16 v[80:83], v[152:155], v[192:195], v[80:83]
	v_mfma_f32_16x16x32_bf16 v[68:71], v[144:147], v[200:203], v[68:71]
	v_mfma_f32_16x16x32_bf16 v[64:67], v[152:155], v[200:203], v[64:67]
	v_mfma_f32_16x16x32_bf16 v[116:119], v[148:151], v[164:167], v[116:119]
	v_mfma_f32_16x16x32_bf16 v[112:115], v[156:159], v[164:167], v[112:115]
	v_mfma_f32_16x16x32_bf16 v[100:103], v[148:151], v[172:175], v[100:103]
	v_mfma_f32_16x16x32_bf16 v[96:99], v[156:159], v[172:175], v[96:99]
	v_mfma_f32_16x16x32_bf16 v[84:87], v[148:151], v[196:199], v[84:87]
	v_mfma_f32_16x16x32_bf16 v[80:83], v[156:159], v[196:199], v[80:83]
	v_mfma_f32_16x16x32_bf16 v[68:71], v[148:151], v[204:207], v[68:71]
	v_mfma_f32_16x16x32_bf16 v[64:67], v[156:159], v[204:207], v[64:67]
	s_setprio 0
	s_barrier
	s_add_i32 s4, s24, s3
	s_mov_b32 m0, s4
	ds_read_b128 v[160:163], v215 offset:49152
	ds_read_b128 v[164:167], v215 offset:50176
	ds_read_b128 v[168:171], v215 offset:51200
	ds_read_b128 v[172:175], v215 offset:52224
	ds_read_b128 v[192:195], v215 offset:53248
	ds_read_b128 v[196:199], v215 offset:54272
	ds_read_b128 v[200:203], v215 offset:55296
	ds_read_b128 v[204:207], v215 offset:56320
	global_load_lds_dwordx4 v208, s[60:61]
	s_add_i32 m0, s4, 0x2000
	s_add_u32 s4, s60, 0xb0080
	s_addc_u32 s5, s61, 0
	s_add_i32 s24, s25, s3
	global_load_lds_dwordx4 v209, s[60:61]
	s_mov_b32 m0, s24
	s_nop 0
	global_load_lds_dwordx4 v178, s[4:5]
	s_add_i32 m0, s24, 0x2000
	s_nop 0
	global_load_lds_dwordx4 v182, s[4:5]
	s_mov_b32 m0, s68
	s_nop 0
	global_load_lds_dwordx4 v216, s[62:63]
	s_mov_b32 m0, s69
	s_nop 0
	global_load_lds_dwordx4 v217, s[62:63]
	s_waitcnt vmcnt(8)
	s_waitcnt lgkmcnt(0)
	s_barrier
	s_setprio 1
	s_waitcnt lgkmcnt(0)
	v_mfma_f32_16x16x32_bf16 v[60:63], v[128:131], v[160:163], v[60:63]
	v_mfma_f32_16x16x32_bf16 v[56:59], v[136:139], v[160:163], v[56:59]
	v_mfma_f32_16x16x32_bf16 v[44:47], v[128:131], v[168:171], v[44:47]
	v_mfma_f32_16x16x32_bf16 v[40:43], v[136:139], v[168:171], v[40:43]
	v_mfma_f32_16x16x32_bf16 v[28:31], v[128:131], v[192:195], v[28:31]
	v_mfma_f32_16x16x32_bf16 v[24:27], v[136:139], v[192:195], v[24:27]
	v_mfma_f32_16x16x32_bf16 v[12:15], v[128:131], v[200:203], v[12:15]
	v_mfma_f32_16x16x32_bf16 v[8:11], v[136:139], v[200:203], v[8:11]
	v_mfma_f32_16x16x32_bf16 v[60:63], v[132:135], v[164:167], v[60:63]
	v_mfma_f32_16x16x32_bf16 v[56:59], v[140:143], v[164:167], v[56:59]
	v_mfma_f32_16x16x32_bf16 v[44:47], v[132:135], v[172:175], v[44:47]
	v_mfma_f32_16x16x32_bf16 v[40:43], v[140:143], v[172:175], v[40:43]
	v_mfma_f32_16x16x32_bf16 v[28:31], v[132:135], v[196:199], v[28:31]
	v_mfma_f32_16x16x32_bf16 v[24:27], v[140:143], v[196:199], v[24:27]
	v_mfma_f32_16x16x32_bf16 v[12:15], v[132:135], v[204:207], v[12:15]
	v_mfma_f32_16x16x32_bf16 v[8:11], v[140:143], v[204:207], v[8:11]
	s_setprio 0
	s_setprio 1
	v_mfma_f32_16x16x32_bf16 v[52:55], v[144:147], v[160:163], v[52:55]
	v_mfma_f32_16x16x32_bf16 v[48:51], v[152:155], v[160:163], v[48:51]
	v_mfma_f32_16x16x32_bf16 v[36:39], v[144:147], v[168:171], v[36:39]
	v_mfma_f32_16x16x32_bf16 v[32:35], v[152:155], v[168:171], v[32:35]
	v_mfma_f32_16x16x32_bf16 v[20:23], v[144:147], v[192:195], v[20:23]
	v_mfma_f32_16x16x32_bf16 v[16:19], v[152:155], v[192:195], v[16:19]
	v_mfma_f32_16x16x32_bf16 v[4:7], v[144:147], v[200:203], v[4:7]
	v_mfma_f32_16x16x32_bf16 v[0:3], v[152:155], v[200:203], v[0:3]
	v_mfma_f32_16x16x32_bf16 v[52:55], v[148:151], v[164:167], v[52:55]
	v_mfma_f32_16x16x32_bf16 v[48:51], v[156:159], v[164:167], v[48:51]
	v_mfma_f32_16x16x32_bf16 v[36:39], v[148:151], v[172:175], v[36:39]
	v_mfma_f32_16x16x32_bf16 v[32:35], v[156:159], v[172:175], v[32:35]
	v_mfma_f32_16x16x32_bf16 v[20:23], v[148:151], v[196:199], v[20:23]
	v_mfma_f32_16x16x32_bf16 v[16:19], v[156:159], v[196:199], v[16:19]
	v_mfma_f32_16x16x32_bf16 v[4:7], v[148:151], v[204:207], v[4:7]
	v_mfma_f32_16x16x32_bf16 v[0:3], v[156:159], v[204:207], v[0:3]
	s_setprio 0
	s_barrier
	s_add_i32 s81, s81, 2
	s_add_u32 s79, s79, 0x100
	s_addc_u32 s80, s80, 0
	s_cmp_gt_u32 s81, 41
	s_mov_b64 s[56:57], s[58:59]
	s_cbranch_scc0 .LBB0_1790
	s_and_b64 vcc, exec, s[22:23]
	s_cbranch_vccz .LBB0_1793
	s_barrier

.LBB0_1891:
	v_add_u32_e32 v146, 0x80, v130
	v_add_u32_e32 v147, 0x80, v134
	v_add_u32_e32 v150, 0x80, v128
	v_add_u32_e32 v151, 0x80, v132
	ds_read_b128 v[156:159], v149
	ds_read_b128 v[160:163], v149 offset:1024
	ds_read_b128 v[164:167], v149 offset:2048
	ds_read_b128 v[168:171], v149 offset:3072
	ds_read_b128 v[172:175], v153
	ds_read_b128 v[176:179], v153 offset:1024
	ds_read_b128 v[180:183], v153 offset:2048
	ds_read_b128 v[184:187], v153 offset:3072
	s_add_u32 s4, s68, 0xfffc0080
	s_addc_u32 s5, s69, -1
	s_cmp_eq_u32 s95, 12
	s_cselect_b32 s73, s63, s5
	s_cselect_b32 s72, s91, s4
	s_cselect_b32 s71, s61, s94
	s_cselect_b32 s70, s92, s93
	s_add_i32 m0, s33, 0xc000
	ds_read_b128 v[188:191], v154
	ds_read_b128 v[192:195], v154 offset:1024
	ds_read_b128 v[196:199], v154 offset:2048
	ds_read_b128 v[200:203], v154 offset:3072
	ds_read_b128 v[204:207], v154 offset:4096
	ds_read_b128 v[212:215], v154 offset:5120
	ds_read_b128 v[216:219], v154 offset:6144
	ds_read_b128 v[220:223], v154 offset:7168
	global_load_lds_dwordx4 v136, s[68:69]
	s_add_i32 m0, s33, 0xe000
	s_nop 0
	global_load_lds_dwordx4 v138, s[68:69]
	s_waitcnt vmcnt(8)
	s_waitcnt lgkmcnt(0)
	s_barrier
	s_setprio 1
	s_waitcnt lgkmcnt(0)
	v_mfma_f32_16x16x32_bf16 v[124:127], v[156:159], v[188:191], v[124:127]
	v_mfma_f32_16x16x32_bf16 v[120:123], v[164:167], v[188:191], v[120:123]
	v_mfma_f32_16x16x32_bf16 v[116:119], v[156:159], v[196:199], v[116:119]
	v_mfma_f32_16x16x32_bf16 v[108:111], v[164:167], v[196:199], v[108:111]
	v_mfma_f32_16x16x32_bf16 v[100:103], v[156:159], v[204:207], v[100:103]
	v_mfma_f32_16x16x32_bf16 v[92:95], v[164:167], v[204:207], v[92:95]
	v_mfma_f32_16x16x32_bf16 v[84:87], v[156:159], v[216:219], v[84:87]
	v_mfma_f32_16x16x32_bf16 v[76:79], v[164:167], v[216:219], v[76:79]
	v_mfma_f32_16x16x32_bf16 v[124:127], v[160:163], v[192:195], v[124:127]
	v_mfma_f32_16x16x32_bf16 v[120:123], v[168:171], v[192:195], v[120:123]
	v_mfma_f32_16x16x32_bf16 v[116:119], v[160:163], v[200:203], v[116:119]
	v_mfma_f32_16x16x32_bf16 v[108:111], v[168:171], v[200:203], v[108:111]
	v_mfma_f32_16x16x32_bf16 v[100:103], v[160:163], v[212:215], v[100:103]
	v_mfma_f32_16x16x32_bf16 v[92:95], v[168:171], v[212:215], v[92:95]
	v_mfma_f32_16x16x32_bf16 v[84:87], v[160:163], v[220:223], v[84:87]
	v_mfma_f32_16x16x32_bf16 v[76:79], v[168:171], v[220:223], v[76:79]
	s_setprio 0
	s_setprio 1
	v_mfma_f32_16x16x32_bf16 v[112:115], v[172:175], v[188:191], v[112:115]
	v_mfma_f32_16x16x32_bf16 v[104:107], v[180:183], v[188:191], v[104:107]
	v_mfma_f32_16x16x32_bf16 v[96:99], v[172:175], v[196:199], v[96:99]
	v_mfma_f32_16x16x32_bf16 v[88:91], v[180:183], v[196:199], v[88:91]
	v_mfma_f32_16x16x32_bf16 v[80:83], v[172:175], v[204:207], v[80:83]
	v_mfma_f32_16x16x32_bf16 v[72:75], v[180:183], v[204:207], v[72:75]
	v_mfma_f32_16x16x32_bf16 v[68:71], v[172:175], v[216:219], v[68:71]
	v_mfma_f32_16x16x32_bf16 v[64:67], v[180:183], v[216:219], v[64:67]
	v_mfma_f32_16x16x32_bf16 v[112:115], v[176:179], v[192:195], v[112:115]
	v_mfma_f32_16x16x32_bf16 v[104:107], v[184:187], v[192:195], v[104:107]
	v_mfma_f32_16x16x32_bf16 v[96:99], v[176:179], v[200:203], v[96:99]
	v_mfma_f32_16x16x32_bf16 v[88:91], v[184:187], v[200:203], v[88:91]
	v_mfma_f32_16x16x32_bf16 v[80:83], v[176:179], v[212:215], v[80:83]
	v_mfma_f32_16x16x32_bf16 v[72:75], v[184:187], v[212:215], v[72:75]
	v_mfma_f32_16x16x32_bf16 v[68:71], v[176:179], v[220:223], v[68:71]
	v_mfma_f32_16x16x32_bf16 v[64:67], v[184:187], v[220:223], v[64:67]
	s_setprio 0
	s_barrier
	s_add_i32 s4, s82, s23
	s_mov_b32 m0, s4
	ds_read_b128 v[188:191], v154 offset:16384
	ds_read_b128 v[192:195], v154 offset:17408
	ds_read_b128 v[196:199], v154 offset:18432
	ds_read_b128 v[200:203], v154 offset:19456
	ds_read_b128 v[204:207], v154 offset:20480
	ds_read_b128 v[212:215], v154 offset:21504
	ds_read_b128 v[216:219], v154 offset:22528
	ds_read_b128 v[220:223], v154 offset:23552
	global_load_lds_dwordx4 v130, s[70:71]
	s_add_i32 m0, s4, 0x2000
	s_add_u32 s4, s70, 0x40000
	s_addc_u32 s5, s71, 0
	s_add_i32 s24, s83, s23
	global_load_lds_dwordx4 v134, s[70:71]
	s_mov_b32 m0, s24
	s_nop 0
	global_load_lds_dwordx4 v130, s[4:5]
	s_add_i32 m0, s24, 0x2000
	s_nop 0
	global_load_lds_dwordx4 v134, s[4:5]
	s_mov_b32 m0, s33
	s_nop 0
	global_load_lds_dwordx4 v128, s[72:73]
	s_mov_b32 m0, s46
	s_nop 0
	global_load_lds_dwordx4 v132, s[72:73]
	s_waitcnt vmcnt(8)
	s_waitcnt lgkmcnt(0)
	s_barrier
	s_setprio 1
	s_waitcnt lgkmcnt(0)
	v_mfma_f32_16x16x32_bf16 v[60:63], v[156:159], v[188:191], v[60:63]
	v_mfma_f32_16x16x32_bf16 v[56:59], v[164:167], v[188:191], v[56:59]
	v_mfma_f32_16x16x32_bf16 v[52:55], v[156:159], v[196:199], v[52:55]
	v_mfma_f32_16x16x32_bf16 v[44:47], v[164:167], v[196:199], v[44:47]
	v_mfma_f32_16x16x32_bf16 v[36:39], v[156:159], v[204:207], v[36:39]
	v_mfma_f32_16x16x32_bf16 v[28:31], v[164:167], v[204:207], v[28:31]
	v_mfma_f32_16x16x32_bf16 v[20:23], v[156:159], v[216:219], v[20:23]
	v_mfma_f32_16x16x32_bf16 v[12:15], v[164:167], v[216:219], v[12:15]
	v_mfma_f32_16x16x32_bf16 v[60:63], v[160:163], v[192:195], v[60:63]
	v_mfma_f32_16x16x32_bf16 v[56:59], v[168:171], v[192:195], v[56:59]
	v_mfma_f32_16x16x32_bf16 v[52:55], v[160:163], v[200:203], v[52:55]
	v_mfma_f32_16x16x32_bf16 v[44:47], v[168:171], v[200:203], v[44:47]
	v_mfma_f32_16x16x32_bf16 v[36:39], v[160:163], v[212:215], v[36:39]
	v_mfma_f32_16x16x32_bf16 v[28:31], v[168:171], v[212:215], v[28:31]
	v_mfma_f32_16x16x32_bf16 v[20:23], v[160:163], v[220:223], v[20:23]
	v_mfma_f32_16x16x32_bf16 v[12:15], v[168:171], v[220:223], v[12:15]
	s_setprio 0
	s_setprio 1
	v_mfma_f32_16x16x32_bf16 v[48:51], v[172:175], v[188:191], v[48:51]
	v_mfma_f32_16x16x32_bf16 v[40:43], v[180:183], v[188:191], v[40:43]
	v_mfma_f32_16x16x32_bf16 v[32:35], v[172:175], v[196:199], v[32:35]
	v_mfma_f32_16x16x32_bf16 v[24:27], v[180:183], v[196:199], v[24:27]
	v_mfma_f32_16x16x32_bf16 v[16:19], v[172:175], v[204:207], v[16:19]
	v_mfma_f32_16x16x32_bf16 v[8:11], v[180:183], v[204:207], v[8:11]
	v_mfma_f32_16x16x32_bf16 v[4:7], v[172:175], v[216:219], v[4:7]
	v_mfma_f32_16x16x32_bf16 v[0:3], v[180:183], v[216:219], v[0:3]
	v_mfma_f32_16x16x32_bf16 v[48:51], v[176:179], v[192:195], v[48:51]
	v_mfma_f32_16x16x32_bf16 v[40:43], v[184:187], v[192:195], v[40:43]
	v_mfma_f32_16x16x32_bf16 v[32:35], v[176:179], v[200:203], v[32:35]
	v_mfma_f32_16x16x32_bf16 v[24:27], v[184:187], v[200:203], v[24:27]
	v_mfma_f32_16x16x32_bf16 v[16:19], v[176:179], v[212:215], v[16:19]
	v_mfma_f32_16x16x32_bf16 v[8:11], v[184:187], v[212:215], v[8:11]
	v_mfma_f32_16x16x32_bf16 v[4:7], v[176:179], v[220:223], v[4:7]
	v_mfma_f32_16x16x32_bf16 v[0:3], v[184:187], v[220:223], v[0:3]
	s_setprio 0
	s_barrier
	s_add_i32 s24, 0, 0x18000
	v_add_u32_e32 v148, s24, v145
	s_add_i32 s25, 0, 0x1c000
	ds_read_b128 v[156:159], v148
	ds_read_b128 v[160:163], v148 offset:1024
	ds_read_b128 v[164:167], v148 offset:2048
	ds_read_b128 v[168:171], v148 offset:3072
	v_add_u32_e32 v148, s25, v145
	ds_read_b128 v[172:175], v148
	ds_read_b128 v[176:179], v148 offset:1024
	ds_read_b128 v[180:183], v148 offset:2048
	ds_read_b128 v[184:187], v148 offset:3072
	s_add_u32 s4, s72, 0x40000
	s_addc_u32 s5, s73, 0
	s_mov_b32 m0, s47
	ds_read_b128 v[188:191], v154 offset:32768
	ds_read_b128 v[192:195], v154 offset:33792
	ds_read_b128 v[196:199], v154 offset:34816
	ds_read_b128 v[200:203], v154 offset:35840
	ds_read_b128 v[204:207], v154 offset:36864
	ds_read_b128 v[212:215], v154 offset:37888
	ds_read_b128 v[216:219], v154 offset:38912
	ds_read_b128 v[220:223], v154 offset:39936
	global_load_lds_dwordx4 v128, s[4:5]
	s_mov_b32 m0, s74
	s_nop 0
	global_load_lds_dwordx4 v132, s[4:5]
	s_waitcnt vmcnt(8)
	s_waitcnt lgkmcnt(0)
	s_barrier
	s_setprio 1
	s_waitcnt lgkmcnt(0)
	v_mfma_f32_16x16x32_bf16 v[124:127], v[156:159], v[188:191], v[124:127]
	v_mfma_f32_16x16x32_bf16 v[120:123], v[164:167], v[188:191], v[120:123]
	v_mfma_f32_16x16x32_bf16 v[116:119], v[156:159], v[196:199], v[116:119]
	v_mfma_f32_16x16x32_bf16 v[108:111], v[164:167], v[196:199], v[108:111]
	v_mfma_f32_16x16x32_bf16 v[100:103], v[156:159], v[204:207], v[100:103]
	v_mfma_f32_16x16x32_bf16 v[92:95], v[164:167], v[204:207], v[92:95]
	v_mfma_f32_16x16x32_bf16 v[84:87], v[156:159], v[216:219], v[84:87]
	v_mfma_f32_16x16x32_bf16 v[76:79], v[164:167], v[216:219], v[76:79]
	v_mfma_f32_16x16x32_bf16 v[124:127], v[160:163], v[192:195], v[124:127]
	v_mfma_f32_16x16x32_bf16 v[120:123], v[168:171], v[192:195], v[120:123]
	v_mfma_f32_16x16x32_bf16 v[116:119], v[160:163], v[200:203], v[116:119]
	v_mfma_f32_16x16x32_bf16 v[108:111], v[168:171], v[200:203], v[108:111]
	v_mfma_f32_16x16x32_bf16 v[100:103], v[160:163], v[212:215], v[100:103]
	v_mfma_f32_16x16x32_bf16 v[92:95], v[168:171], v[212:215], v[92:95]
	v_mfma_f32_16x16x32_bf16 v[84:87], v[160:163], v[220:223], v[84:87]
	v_mfma_f32_16x16x32_bf16 v[76:79], v[168:171], v[220:223], v[76:79]
	s_setprio 0
	s_setprio 1
	v_mfma_f32_16x16x32_bf16 v[112:115], v[172:175], v[188:191], v[112:115]
	v_mfma_f32_16x16x32_bf16 v[104:107], v[180:183], v[188:191], v[104:107]
	v_mfma_f32_16x16x32_bf16 v[96:99], v[172:175], v[196:199], v[96:99]
	v_mfma_f32_16x16x32_bf16 v[88:91], v[180:183], v[196:199], v[88:91]
	v_mfma_f32_16x16x32_bf16 v[80:83], v[172:175], v[204:207], v[80:83]
	v_mfma_f32_16x16x32_bf16 v[72:75], v[180:183], v[204:207], v[72:75]
	v_mfma_f32_16x16x32_bf16 v[68:71], v[172:175], v[216:219], v[68:71]
	v_mfma_f32_16x16x32_bf16 v[64:67], v[180:183], v[216:219], v[64:67]
	v_mfma_f32_16x16x32_bf16 v[112:115], v[176:179], v[192:195], v[112:115]
	v_mfma_f32_16x16x32_bf16 v[104:107], v[184:187], v[192:195], v[104:107]
	v_mfma_f32_16x16x32_bf16 v[96:99], v[176:179], v[200:203], v[96:99]
	v_mfma_f32_16x16x32_bf16 v[88:91], v[184:187], v[200:203], v[88:91]
	v_mfma_f32_16x16x32_bf16 v[80:83], v[176:179], v[212:215], v[80:83]
	v_mfma_f32_16x16x32_bf16 v[72:75], v[184:187], v[212:215], v[72:75]
	v_mfma_f32_16x16x32_bf16 v[68:71], v[176:179], v[220:223], v[68:71]
	v_mfma_f32_16x16x32_bf16 v[64:67], v[184:187], v[220:223], v[64:67]
	s_setprio 0
	s_barrier
	s_add_i32 s4, s24, s23
	s_mov_b32 m0, s4
	ds_read_b128 v[188:191], v154 offset:49152
	ds_read_b128 v[192:195], v154 offset:50176
	ds_read_b128 v[196:199], v154 offset:51200
	ds_read_b128 v[200:203], v154 offset:52224
	ds_read_b128 v[204:207], v154 offset:53248
	ds_read_b128 v[212:215], v154 offset:54272
	ds_read_b128 v[216:219], v154 offset:55296
	ds_read_b128 v[220:223], v154 offset:56320
	global_load_lds_dwordx4 v146, s[70:71]
	s_add_i32 m0, s4, 0x2000
	s_add_u32 s4, s70, 0x40080
	s_addc_u32 s5, s71, 0
	s_add_i32 s24, s25, s23
	global_load_lds_dwordx4 v147, s[70:71]
	s_mov_b32 m0, s24
	s_nop 0
	global_load_lds_dwordx4 v130, s[4:5]
	s_add_i32 m0, s24, 0x2000
	s_nop 0
	global_load_lds_dwordx4 v134, s[4:5]
	s_mov_b32 m0, s78
	s_nop 0
	global_load_lds_dwordx4 v150, s[72:73]
	s_mov_b32 m0, s79
	s_nop 0
	global_load_lds_dwordx4 v151, s[72:73]
	s_waitcnt vmcnt(8)
	s_waitcnt lgkmcnt(0)
	s_barrier
	s_setprio 1
	s_waitcnt lgkmcnt(0)
	v_mfma_f32_16x16x32_bf16 v[60:63], v[156:159], v[188:191], v[60:63]
	v_mfma_f32_16x16x32_bf16 v[56:59], v[164:167], v[188:191], v[56:59]
	v_mfma_f32_16x16x32_bf16 v[52:55], v[156:159], v[196:199], v[52:55]
	v_mfma_f32_16x16x32_bf16 v[44:47], v[164:167], v[196:199], v[44:47]
	v_mfma_f32_16x16x32_bf16 v[36:39], v[156:159], v[204:207], v[36:39]
	v_mfma_f32_16x16x32_bf16 v[28:31], v[164:167], v[204:207], v[28:31]
	v_mfma_f32_16x16x32_bf16 v[20:23], v[156:159], v[216:219], v[20:23]
	v_mfma_f32_16x16x32_bf16 v[12:15], v[164:167], v[216:219], v[12:15]
	v_mfma_f32_16x16x32_bf16 v[60:63], v[160:163], v[192:195], v[60:63]
	v_mfma_f32_16x16x32_bf16 v[56:59], v[168:171], v[192:195], v[56:59]
	v_mfma_f32_16x16x32_bf16 v[52:55], v[160:163], v[200:203], v[52:55]
	v_mfma_f32_16x16x32_bf16 v[44:47], v[168:171], v[200:203], v[44:47]
	v_mfma_f32_16x16x32_bf16 v[36:39], v[160:163], v[212:215], v[36:39]
	v_mfma_f32_16x16x32_bf16 v[28:31], v[168:171], v[212:215], v[28:31]
	v_mfma_f32_16x16x32_bf16 v[20:23], v[160:163], v[220:223], v[20:23]
	v_mfma_f32_16x16x32_bf16 v[12:15], v[168:171], v[220:223], v[12:15]
	s_setprio 0
	s_setprio 1
	v_mfma_f32_16x16x32_bf16 v[48:51], v[172:175], v[188:191], v[48:51]
	v_mfma_f32_16x16x32_bf16 v[40:43], v[180:183], v[188:191], v[40:43]
	v_mfma_f32_16x16x32_bf16 v[32:35], v[172:175], v[196:199], v[32:35]
	v_mfma_f32_16x16x32_bf16 v[24:27], v[180:183], v[196:199], v[24:27]
	v_mfma_f32_16x16x32_bf16 v[16:19], v[172:175], v[204:207], v[16:19]
	v_mfma_f32_16x16x32_bf16 v[8:11], v[180:183], v[204:207], v[8:11]
	v_mfma_f32_16x16x32_bf16 v[4:7], v[172:175], v[216:219], v[4:7]
	v_mfma_f32_16x16x32_bf16 v[0:3], v[180:183], v[216:219], v[0:3]
	v_mfma_f32_16x16x32_bf16 v[48:51], v[176:179], v[192:195], v[48:51]
	v_mfma_f32_16x16x32_bf16 v[40:43], v[184:187], v[192:195], v[40:43]
	v_mfma_f32_16x16x32_bf16 v[32:35], v[176:179], v[200:203], v[32:35]
	v_mfma_f32_16x16x32_bf16 v[24:27], v[184:187], v[200:203], v[24:27]
	v_mfma_f32_16x16x32_bf16 v[16:19], v[176:179], v[212:215], v[16:19]
	v_mfma_f32_16x16x32_bf16 v[8:11], v[184:187], v[212:215], v[8:11]
	v_mfma_f32_16x16x32_bf16 v[4:7], v[176:179], v[220:223], v[4:7]
	v_mfma_f32_16x16x32_bf16 v[0:3], v[184:187], v[220:223], v[0:3]
	s_setprio 0
	s_barrier
	s_add_i32 s95, s95, 2
	s_add_u32 s68, s68, 0x100
	s_addc_u32 s69, s69, 0
	s_add_u32 s93, s93, 0x100
	s_addc_u32 s94, s94, 0
	s_cmp_gt_u32 s95, 13
	s_cbranch_scc0 .LBB0_1891
	s_and_b64 vcc, exec, s[20:21]
	s_cbranch_vccz .LBB0_1894
	s_barrier

.LBB0_2179:
	v_add_u32_e32 v208, 0x80, v178
	v_add_u32_e32 v209, 0x80, v182
	v_add_u32_e32 v216, 0x80, v176
	v_add_u32_e32 v217, 0x80, v180
	ds_read_b128 v[128:131], v213
	ds_read_b128 v[132:135], v213 offset:1024
	ds_read_b128 v[136:139], v213 offset:2048
	ds_read_b128 v[140:143], v213 offset:3072
	ds_read_b128 v[144:147], v214
	ds_read_b128 v[148:151], v214 offset:1024
	ds_read_b128 v[152:155], v214 offset:2048
	ds_read_b128 v[156:159], v214 offset:3072
	s_add_u32 s4, s56, 0xfffc0080
	s_addc_u32 s5, s57, -1
	s_cmp_eq_u32 s77, 12
	s_cselect_b32 s61, s25, s5
	s_cselect_b32 s60, s55, s4
	s_cselect_b32 s59, s23, s76
	s_cselect_b32 s58, s74, s75
	s_add_i32 m0, s33, 0xc000
	ds_read_b128 v[160:163], v215
	ds_read_b128 v[164:167], v215 offset:1024
	ds_read_b128 v[168:171], v215 offset:2048
	ds_read_b128 v[172:175], v215 offset:3072
	ds_read_b128 v[192:195], v215 offset:4096
	ds_read_b128 v[196:199], v215 offset:5120
	ds_read_b128 v[200:203], v215 offset:6144
	ds_read_b128 v[204:207], v215 offset:7168
	global_load_lds_dwordx4 v184, s[56:57]
	s_add_i32 m0, s33, 0xe000
	s_nop 0
	global_load_lds_dwordx4 v186, s[56:57]
	s_waitcnt vmcnt(8)
	s_waitcnt lgkmcnt(0)
	s_barrier
	s_setprio 1
	s_waitcnt lgkmcnt(0)
	v_mfma_f32_16x16x32_bf16 v[124:127], v[128:131], v[160:163], v[124:127]
	v_mfma_f32_16x16x32_bf16 v[120:123], v[136:139], v[160:163], v[120:123]
	v_mfma_f32_16x16x32_bf16 v[108:111], v[128:131], v[168:171], v[108:111]
	v_mfma_f32_16x16x32_bf16 v[104:107], v[136:139], v[168:171], v[104:107]
	v_mfma_f32_16x16x32_bf16 v[92:95], v[128:131], v[192:195], v[92:95]
	v_mfma_f32_16x16x32_bf16 v[88:91], v[136:139], v[192:195], v[88:91]
	v_mfma_f32_16x16x32_bf16 v[76:79], v[128:131], v[200:203], v[76:79]
	v_mfma_f32_16x16x32_bf16 v[72:75], v[136:139], v[200:203], v[72:75]
	v_mfma_f32_16x16x32_bf16 v[124:127], v[132:135], v[164:167], v[124:127]
	v_mfma_f32_16x16x32_bf16 v[120:123], v[140:143], v[164:167], v[120:123]
	v_mfma_f32_16x16x32_bf16 v[108:111], v[132:135], v[172:175], v[108:111]
	v_mfma_f32_16x16x32_bf16 v[104:107], v[140:143], v[172:175], v[104:107]
	v_mfma_f32_16x16x32_bf16 v[92:95], v[132:135], v[196:199], v[92:95]
	v_mfma_f32_16x16x32_bf16 v[88:91], v[140:143], v[196:199], v[88:91]
	v_mfma_f32_16x16x32_bf16 v[76:79], v[132:135], v[204:207], v[76:79]
	v_mfma_f32_16x16x32_bf16 v[72:75], v[140:143], v[204:207], v[72:75]
	s_setprio 0
	s_setprio 1
	v_mfma_f32_16x16x32_bf16 v[116:119], v[144:147], v[160:163], v[116:119]
	v_mfma_f32_16x16x32_bf16 v[112:115], v[152:155], v[160:163], v[112:115]
	v_mfma_f32_16x16x32_bf16 v[100:103], v[144:147], v[168:171], v[100:103]
	v_mfma_f32_16x16x32_bf16 v[96:99], v[152:155], v[168:171], v[96:99]
	v_mfma_f32_16x16x32_bf16 v[84:87], v[144:147], v[192:195], v[84:87]
	v_mfma_f32_16x16x32_bf16 v[80:83], v[152:155], v[192:195], v[80:83]
	v_mfma_f32_16x16x32_bf16 v[68:71], v[144:147], v[200:203], v[68:71]
	v_mfma_f32_16x16x32_bf16 v[64:67], v[152:155], v[200:203], v[64:67]
	v_mfma_f32_16x16x32_bf16 v[116:119], v[148:151], v[164:167], v[116:119]
	v_mfma_f32_16x16x32_bf16 v[112:115], v[156:159], v[164:167], v[112:115]
	v_mfma_f32_16x16x32_bf16 v[100:103], v[148:151], v[172:175], v[100:103]
	v_mfma_f32_16x16x32_bf16 v[96:99], v[156:159], v[172:175], v[96:99]
	v_mfma_f32_16x16x32_bf16 v[84:87], v[148:151], v[196:199], v[84:87]
	v_mfma_f32_16x16x32_bf16 v[80:83], v[156:159], v[196:199], v[80:83]
	v_mfma_f32_16x16x32_bf16 v[68:71], v[148:151], v[204:207], v[68:71]
	v_mfma_f32_16x16x32_bf16 v[64:67], v[156:159], v[204:207], v[64:67]
	s_setprio 0
	s_barrier
	s_add_i32 s4, s71, s3
	s_mov_b32 m0, s4
	ds_read_b128 v[160:163], v215 offset:16384
	ds_read_b128 v[164:167], v215 offset:17408
	ds_read_b128 v[168:171], v215 offset:18432
	ds_read_b128 v[172:175], v215 offset:19456
	ds_read_b128 v[192:195], v215 offset:20480
	ds_read_b128 v[196:199], v215 offset:21504
	ds_read_b128 v[200:203], v215 offset:22528
	ds_read_b128 v[204:207], v215 offset:23552
	global_load_lds_dwordx4 v178, s[58:59]
	s_add_i32 m0, s4, 0x2000
	s_add_u32 s4, s58, 0x40000
	s_addc_u32 s5, s59, 0
	s_add_i32 s26, s72, s3
	global_load_lds_dwordx4 v182, s[58:59]
	s_mov_b32 m0, s26
	s_nop 0
	global_load_lds_dwordx4 v178, s[4:5]
	s_add_i32 m0, s26, 0x2000
	s_nop 0
	global_load_lds_dwordx4 v182, s[4:5]
	s_mov_b32 m0, s33
	s_nop 0
	global_load_lds_dwordx4 v176, s[60:61]
	s_mov_b32 m0, s46
	s_nop 0
	global_load_lds_dwordx4 v180, s[60:61]
	s_waitcnt vmcnt(8)
	s_waitcnt lgkmcnt(0)
	s_barrier
	s_setprio 1
	s_waitcnt lgkmcnt(0)
	v_mfma_f32_16x16x32_bf16 v[60:63], v[128:131], v[160:163], v[60:63]
	v_mfma_f32_16x16x32_bf16 v[56:59], v[136:139], v[160:163], v[56:59]
	v_mfma_f32_16x16x32_bf16 v[44:47], v[128:131], v[168:171], v[44:47]
	v_mfma_f32_16x16x32_bf16 v[40:43], v[136:139], v[168:171], v[40:43]
	v_mfma_f32_16x16x32_bf16 v[28:31], v[128:131], v[192:195], v[28:31]
	v_mfma_f32_16x16x32_bf16 v[24:27], v[136:139], v[192:195], v[24:27]
	v_mfma_f32_16x16x32_bf16 v[12:15], v[128:131], v[200:203], v[12:15]
	v_mfma_f32_16x16x32_bf16 v[8:11], v[136:139], v[200:203], v[8:11]
	v_mfma_f32_16x16x32_bf16 v[60:63], v[132:135], v[164:167], v[60:63]
	v_mfma_f32_16x16x32_bf16 v[56:59], v[140:143], v[164:167], v[56:59]
	v_mfma_f32_16x16x32_bf16 v[44:47], v[132:135], v[172:175], v[44:47]
	v_mfma_f32_16x16x32_bf16 v[40:43], v[140:143], v[172:175], v[40:43]
	v_mfma_f32_16x16x32_bf16 v[28:31], v[132:135], v[196:199], v[28:31]
	v_mfma_f32_16x16x32_bf16 v[24:27], v[140:143], v[196:199], v[24:27]
	v_mfma_f32_16x16x32_bf16 v[12:15], v[132:135], v[204:207], v[12:15]
	v_mfma_f32_16x16x32_bf16 v[8:11], v[140:143], v[204:207], v[8:11]
	s_setprio 0
	s_setprio 1
	v_mfma_f32_16x16x32_bf16 v[52:55], v[144:147], v[160:163], v[52:55]
	v_mfma_f32_16x16x32_bf16 v[48:51], v[152:155], v[160:163], v[48:51]
	v_mfma_f32_16x16x32_bf16 v[36:39], v[144:147], v[168:171], v[36:39]
	v_mfma_f32_16x16x32_bf16 v[32:35], v[152:155], v[168:171], v[32:35]
	v_mfma_f32_16x16x32_bf16 v[20:23], v[144:147], v[192:195], v[20:23]
	v_mfma_f32_16x16x32_bf16 v[16:19], v[152:155], v[192:195], v[16:19]
	v_mfma_f32_16x16x32_bf16 v[4:7], v[144:147], v[200:203], v[4:7]
	v_mfma_f32_16x16x32_bf16 v[0:3], v[152:155], v[200:203], v[0:3]
	v_mfma_f32_16x16x32_bf16 v[52:55], v[148:151], v[164:167], v[52:55]
	v_mfma_f32_16x16x32_bf16 v[48:51], v[156:159], v[164:167], v[48:51]
	v_mfma_f32_16x16x32_bf16 v[36:39], v[148:151], v[172:175], v[36:39]
	v_mfma_f32_16x16x32_bf16 v[32:35], v[156:159], v[172:175], v[32:35]
	v_mfma_f32_16x16x32_bf16 v[20:23], v[148:151], v[196:199], v[20:23]
	v_mfma_f32_16x16x32_bf16 v[16:19], v[156:159], v[196:199], v[16:19]
	v_mfma_f32_16x16x32_bf16 v[4:7], v[148:151], v[204:207], v[4:7]
	v_mfma_f32_16x16x32_bf16 v[0:3], v[156:159], v[204:207], v[0:3]
	s_setprio 0
	s_barrier
	s_add_i32 s26, 0, 0x18000
	s_add_i32 s27, 0, 0x1c000
	v_add_u32_e32 v140, s26, v212
	v_add_u32_e32 v156, s27, v212
	ds_read_b128 v[128:131], v140
	ds_read_b128 v[132:135], v140 offset:1024
	ds_read_b128 v[136:139], v140 offset:2048
	ds_read_b128 v[140:143], v140 offset:3072
	ds_read_b128 v[144:147], v156
	ds_read_b128 v[148:151], v156 offset:1024
	ds_read_b128 v[152:155], v156 offset:2048
	ds_read_b128 v[156:159], v156 offset:3072
	s_add_u32 s4, s60, 0x40000
	s_addc_u32 s5, s61, 0
	s_mov_b32 m0, s47
	ds_read_b128 v[160:163], v215 offset:32768
	ds_read_b128 v[164:167], v215 offset:33792
	ds_read_b128 v[168:171], v215 offset:34816
	ds_read_b128 v[172:175], v215 offset:35840
	ds_read_b128 v[192:195], v215 offset:36864
	ds_read_b128 v[196:199], v215 offset:37888
	ds_read_b128 v[200:203], v215 offset:38912
	ds_read_b128 v[204:207], v215 offset:39936
	global_load_lds_dwordx4 v176, s[4:5]
	s_mov_b32 m0, s62
	s_nop 0
	global_load_lds_dwordx4 v180, s[4:5]
	s_waitcnt vmcnt(8)
	s_waitcnt lgkmcnt(0)
	s_barrier
	s_setprio 1
	s_waitcnt lgkmcnt(0)
	v_mfma_f32_16x16x32_bf16 v[124:127], v[128:131], v[160:163], v[124:127]
	v_mfma_f32_16x16x32_bf16 v[120:123], v[136:139], v[160:163], v[120:123]
	v_mfma_f32_16x16x32_bf16 v[108:111], v[128:131], v[168:171], v[108:111]
	v_mfma_f32_16x16x32_bf16 v[104:107], v[136:139], v[168:171], v[104:107]
	v_mfma_f32_16x16x32_bf16 v[92:95], v[128:131], v[192:195], v[92:95]
	v_mfma_f32_16x16x32_bf16 v[88:91], v[136:139], v[192:195], v[88:91]
	v_mfma_f32_16x16x32_bf16 v[76:79], v[128:131], v[200:203], v[76:79]
	v_mfma_f32_16x16x32_bf16 v[72:75], v[136:139], v[200:203], v[72:75]
	v_mfma_f32_16x16x32_bf16 v[124:127], v[132:135], v[164:167], v[124:127]
	v_mfma_f32_16x16x32_bf16 v[120:123], v[140:143], v[164:167], v[120:123]
	v_mfma_f32_16x16x32_bf16 v[108:111], v[132:135], v[172:175], v[108:111]
	v_mfma_f32_16x16x32_bf16 v[104:107], v[140:143], v[172:175], v[104:107]
	v_mfma_f32_16x16x32_bf16 v[92:95], v[132:135], v[196:199], v[92:95]
	v_mfma_f32_16x16x32_bf16 v[88:91], v[140:143], v[196:199], v[88:91]
	v_mfma_f32_16x16x32_bf16 v[76:79], v[132:135], v[204:207], v[76:79]
	v_mfma_f32_16x16x32_bf16 v[72:75], v[140:143], v[204:207], v[72:75]
	s_setprio 0
	s_setprio 1
	v_mfma_f32_16x16x32_bf16 v[116:119], v[144:147], v[160:163], v[116:119]
	v_mfma_f32_16x16x32_bf16 v[112:115], v[152:155], v[160:163], v[112:115]
	v_mfma_f32_16x16x32_bf16 v[100:103], v[144:147], v[168:171], v[100:103]
	v_mfma_f32_16x16x32_bf16 v[96:99], v[152:155], v[168:171], v[96:99]
	v_mfma_f32_16x16x32_bf16 v[84:87], v[144:147], v[192:195], v[84:87]
	v_mfma_f32_16x16x32_bf16 v[80:83], v[152:155], v[192:195], v[80:83]
	v_mfma_f32_16x16x32_bf16 v[68:71], v[144:147], v[200:203], v[68:71]
	v_mfma_f32_16x16x32_bf16 v[64:67], v[152:155], v[200:203], v[64:67]
	v_mfma_f32_16x16x32_bf16 v[116:119], v[148:151], v[164:167], v[116:119]
	v_mfma_f32_16x16x32_bf16 v[112:115], v[156:159], v[164:167], v[112:115]
	v_mfma_f32_16x16x32_bf16 v[100:103], v[148:151], v[172:175], v[100:103]
	v_mfma_f32_16x16x32_bf16 v[96:99], v[156:159], v[172:175], v[96:99]
	v_mfma_f32_16x16x32_bf16 v[84:87], v[148:151], v[196:199], v[84:87]
	v_mfma_f32_16x16x32_bf16 v[80:83], v[156:159], v[196:199], v[80:83]
	v_mfma_f32_16x16x32_bf16 v[68:71], v[148:151], v[204:207], v[68:71]
	v_mfma_f32_16x16x32_bf16 v[64:67], v[156:159], v[204:207], v[64:67]
	s_setprio 0
	s_barrier
	s_add_i32 s4, s26, s3
	s_mov_b32 m0, s4
	ds_read_b128 v[160:163], v215 offset:49152
	ds_read_b128 v[164:167], v215 offset:50176
	ds_read_b128 v[168:171], v215 offset:51200
	ds_read_b128 v[172:175], v215 offset:52224
	ds_read_b128 v[192:195], v215 offset:53248
	ds_read_b128 v[196:199], v215 offset:54272
	ds_read_b128 v[200:203], v215 offset:55296
	ds_read_b128 v[204:207], v215 offset:56320
	global_load_lds_dwordx4 v208, s[58:59]
	s_add_i32 m0, s4, 0x2000
	s_add_u32 s4, s58, 0x40080
	s_addc_u32 s5, s59, 0
	s_add_i32 s26, s27, s3
	global_load_lds_dwordx4 v209, s[58:59]
	s_mov_b32 m0, s26
	s_nop 0
	global_load_lds_dwordx4 v178, s[4:5]
	s_add_i32 m0, s26, 0x2000
	s_nop 0
	global_load_lds_dwordx4 v182, s[4:5]
	s_mov_b32 m0, s66
	s_nop 0
	global_load_lds_dwordx4 v216, s[60:61]
	s_mov_b32 m0, s67
	s_nop 0
	global_load_lds_dwordx4 v217, s[60:61]
	s_waitcnt vmcnt(8)
	s_waitcnt lgkmcnt(0)
	s_barrier
	s_setprio 1
	s_waitcnt lgkmcnt(0)
	v_mfma_f32_16x16x32_bf16 v[60:63], v[128:131], v[160:163], v[60:63]
	v_mfma_f32_16x16x32_bf16 v[56:59], v[136:139], v[160:163], v[56:59]
	v_mfma_f32_16x16x32_bf16 v[44:47], v[128:131], v[168:171], v[44:47]
	v_mfma_f32_16x16x32_bf16 v[40:43], v[136:139], v[168:171], v[40:43]
	v_mfma_f32_16x16x32_bf16 v[28:31], v[128:131], v[192:195], v[28:31]
	v_mfma_f32_16x16x32_bf16 v[24:27], v[136:139], v[192:195], v[24:27]
	v_mfma_f32_16x16x32_bf16 v[12:15], v[128:131], v[200:203], v[12:15]
	v_mfma_f32_16x16x32_bf16 v[8:11], v[136:139], v[200:203], v[8:11]
	v_mfma_f32_16x16x32_bf16 v[60:63], v[132:135], v[164:167], v[60:63]
	v_mfma_f32_16x16x32_bf16 v[56:59], v[140:143], v[164:167], v[56:59]
	v_mfma_f32_16x16x32_bf16 v[44:47], v[132:135], v[172:175], v[44:47]
	v_mfma_f32_16x16x32_bf16 v[40:43], v[140:143], v[172:175], v[40:43]
	v_mfma_f32_16x16x32_bf16 v[28:31], v[132:135], v[196:199], v[28:31]
	v_mfma_f32_16x16x32_bf16 v[24:27], v[140:143], v[196:199], v[24:27]
	v_mfma_f32_16x16x32_bf16 v[12:15], v[132:135], v[204:207], v[12:15]
	v_mfma_f32_16x16x32_bf16 v[8:11], v[140:143], v[204:207], v[8:11]
	s_setprio 0
	s_setprio 1
	v_mfma_f32_16x16x32_bf16 v[52:55], v[144:147], v[160:163], v[52:55]
	v_mfma_f32_16x16x32_bf16 v[48:51], v[152:155], v[160:163], v[48:51]
	v_mfma_f32_16x16x32_bf16 v[36:39], v[144:147], v[168:171], v[36:39]
	v_mfma_f32_16x16x32_bf16 v[32:35], v[152:155], v[168:171], v[32:35]
	v_mfma_f32_16x16x32_bf16 v[20:23], v[144:147], v[192:195], v[20:23]
	v_mfma_f32_16x16x32_bf16 v[16:19], v[152:155], v[192:195], v[16:19]
	v_mfma_f32_16x16x32_bf16 v[4:7], v[144:147], v[200:203], v[4:7]
	v_mfma_f32_16x16x32_bf16 v[0:3], v[152:155], v[200:203], v[0:3]
	v_mfma_f32_16x16x32_bf16 v[52:55], v[148:151], v[164:167], v[52:55]
	v_mfma_f32_16x16x32_bf16 v[48:51], v[156:159], v[164:167], v[48:51]
	v_mfma_f32_16x16x32_bf16 v[36:39], v[148:151], v[172:175], v[36:39]
	v_mfma_f32_16x16x32_bf16 v[32:35], v[156:159], v[172:175], v[32:35]
	v_mfma_f32_16x16x32_bf16 v[20:23], v[148:151], v[196:199], v[20:23]
	v_mfma_f32_16x16x32_bf16 v[16:19], v[156:159], v[196:199], v[16:19]
	v_mfma_f32_16x16x32_bf16 v[4:7], v[148:151], v[204:207], v[4:7]
	v_mfma_f32_16x16x32_bf16 v[0:3], v[156:159], v[204:207], v[0:3]
	s_setprio 0
	s_barrier
	s_add_i32 s77, s77, 2
	s_add_u32 s56, s56, 0x100
	s_addc_u32 s57, s57, 0
	s_add_u32 s75, s75, 0x100
	s_addc_u32 s76, s76, 0
	s_cmp_gt_u32 s77, 13
	s_cbranch_scc0 .LBB0_2179
	s_and_b64 vcc, exec, s[20:21]
	s_cbranch_vccz .LBB0_2182
	s_barrier

.LBB0_2280:
	v_add_u32_e32 v208, 0x80, v130
	v_add_u32_e32 v209, 0x80, v134
	v_add_u32_e32 v220, 0x80, v128
	v_add_u32_e32 v221, 0x80, v132
	ds_read_b128 v[152:155], v147
	ds_read_b128 v[156:159], v147 offset:1024
	ds_read_b128 v[160:163], v147 offset:2048
	ds_read_b128 v[164:167], v147 offset:3072
	ds_read_b128 v[168:171], v149
	ds_read_b128 v[172:175], v149 offset:1024
	ds_read_b128 v[176:179], v149 offset:2048
	ds_read_b128 v[180:183], v149 offset:3072
	s_add_u32 s4, s50, 0xfffc0080
	s_addc_u32 s5, s51, -1
	s_cmp_eq_u32 s74, 12
	s_cselect_b32 s55, s11, s5
	s_cselect_b32 s54, s23, s4
	s_cselect_b32 s53, s21, s73
	s_cselect_b32 s52, s71, s72
	s_add_i32 m0, s47, 0xc000
	ds_read_b128 v[184:187], v151
	ds_read_b128 v[188:191], v151 offset:1024
	ds_read_b128 v[192:195], v151 offset:2048
	ds_read_b128 v[196:199], v151 offset:3072
	ds_read_b128 v[200:203], v151 offset:4096
	ds_read_b128 v[204:207], v151 offset:5120
	ds_read_b128 v[212:215], v151 offset:6144
	ds_read_b128 v[216:219], v151 offset:7168
	global_load_lds_dwordx4 v136, s[50:51]
	s_add_i32 m0, s47, 0xe000
	s_nop 0
	global_load_lds_dwordx4 v138, s[50:51]
	s_waitcnt vmcnt(8)
	s_waitcnt lgkmcnt(0)
	s_barrier
	s_setprio 1
	s_waitcnt lgkmcnt(0)
	v_mfma_f32_16x16x32_bf16 v[124:127], v[152:155], v[184:187], v[124:127]
	v_mfma_f32_16x16x32_bf16 v[120:123], v[160:163], v[184:187], v[120:123]
	v_mfma_f32_16x16x32_bf16 v[108:111], v[152:155], v[192:195], v[108:111]
	v_mfma_f32_16x16x32_bf16 v[104:107], v[160:163], v[192:195], v[104:107]
	v_mfma_f32_16x16x32_bf16 v[92:95], v[152:155], v[200:203], v[92:95]
	v_mfma_f32_16x16x32_bf16 v[88:91], v[160:163], v[200:203], v[88:91]
	v_mfma_f32_16x16x32_bf16 v[76:79], v[152:155], v[212:215], v[76:79]
	v_mfma_f32_16x16x32_bf16 v[72:75], v[160:163], v[212:215], v[72:75]
	v_mfma_f32_16x16x32_bf16 v[124:127], v[156:159], v[188:191], v[124:127]
	v_mfma_f32_16x16x32_bf16 v[120:123], v[164:167], v[188:191], v[120:123]
	v_mfma_f32_16x16x32_bf16 v[108:111], v[156:159], v[196:199], v[108:111]
	v_mfma_f32_16x16x32_bf16 v[104:107], v[164:167], v[196:199], v[104:107]
	v_mfma_f32_16x16x32_bf16 v[92:95], v[156:159], v[204:207], v[92:95]
	v_mfma_f32_16x16x32_bf16 v[88:91], v[164:167], v[204:207], v[88:91]
	v_mfma_f32_16x16x32_bf16 v[76:79], v[156:159], v[216:219], v[76:79]
	v_mfma_f32_16x16x32_bf16 v[72:75], v[164:167], v[216:219], v[72:75]
	s_setprio 0
	s_setprio 1
	v_mfma_f32_16x16x32_bf16 v[116:119], v[168:171], v[184:187], v[116:119]
	v_mfma_f32_16x16x32_bf16 v[112:115], v[176:179], v[184:187], v[112:115]
	v_mfma_f32_16x16x32_bf16 v[100:103], v[168:171], v[192:195], v[100:103]
	v_mfma_f32_16x16x32_bf16 v[96:99], v[176:179], v[192:195], v[96:99]
	v_mfma_f32_16x16x32_bf16 v[84:87], v[168:171], v[200:203], v[84:87]
	v_mfma_f32_16x16x32_bf16 v[80:83], v[176:179], v[200:203], v[80:83]
	v_mfma_f32_16x16x32_bf16 v[68:71], v[168:171], v[212:215], v[68:71]
	v_mfma_f32_16x16x32_bf16 v[64:67], v[176:179], v[212:215], v[64:67]
	v_mfma_f32_16x16x32_bf16 v[116:119], v[172:175], v[188:191], v[116:119]
	v_mfma_f32_16x16x32_bf16 v[112:115], v[180:183], v[188:191], v[112:115]
	v_mfma_f32_16x16x32_bf16 v[100:103], v[172:175], v[196:199], v[100:103]
	v_mfma_f32_16x16x32_bf16 v[96:99], v[180:183], v[196:199], v[96:99]
	v_mfma_f32_16x16x32_bf16 v[84:87], v[172:175], v[204:207], v[84:87]
	v_mfma_f32_16x16x32_bf16 v[80:83], v[180:183], v[204:207], v[80:83]
	v_mfma_f32_16x16x32_bf16 v[68:71], v[172:175], v[216:219], v[68:71]
	v_mfma_f32_16x16x32_bf16 v[64:67], v[180:183], v[216:219], v[64:67]
	s_setprio 0
	s_barrier
	s_add_i32 s4, s66, s46
	s_mov_b32 m0, s4
	ds_read_b128 v[184:187], v151 offset:16384
	ds_read_b128 v[188:191], v151 offset:17408
	ds_read_b128 v[192:195], v151 offset:18432
	ds_read_b128 v[196:199], v151 offset:19456
	ds_read_b128 v[200:203], v151 offset:20480
	ds_read_b128 v[204:207], v151 offset:21504
	ds_read_b128 v[212:215], v151 offset:22528
	ds_read_b128 v[216:219], v151 offset:23552
	global_load_lds_dwordx4 v130, s[52:53]
	s_add_i32 m0, s4, 0x2000
	s_add_u32 s4, s52, 0x40000
	s_addc_u32 s5, s53, 0
	s_add_i32 s26, s67, s46
	global_load_lds_dwordx4 v134, s[52:53]
	s_mov_b32 m0, s26
	s_nop 0
	global_load_lds_dwordx4 v130, s[4:5]
	s_add_i32 m0, s26, 0x2000
	s_nop 0
	global_load_lds_dwordx4 v134, s[4:5]
	s_mov_b32 m0, s47
	s_nop 0
	global_load_lds_dwordx4 v128, s[54:55]
	s_mov_b32 m0, s56
	s_nop 0
	global_load_lds_dwordx4 v132, s[54:55]
	s_waitcnt vmcnt(8)
	s_waitcnt lgkmcnt(0)
	s_barrier
	s_setprio 1
	s_waitcnt lgkmcnt(0)
	v_mfma_f32_16x16x32_bf16 v[60:63], v[152:155], v[184:187], v[60:63]
	v_mfma_f32_16x16x32_bf16 v[56:59], v[160:163], v[184:187], v[56:59]
	v_mfma_f32_16x16x32_bf16 v[44:47], v[152:155], v[192:195], v[44:47]
	v_mfma_f32_16x16x32_bf16 v[40:43], v[160:163], v[192:195], v[40:43]
	v_mfma_f32_16x16x32_bf16 v[28:31], v[152:155], v[200:203], v[28:31]
	v_mfma_f32_16x16x32_bf16 v[24:27], v[160:163], v[200:203], v[24:27]
	v_mfma_f32_16x16x32_bf16 v[12:15], v[152:155], v[212:215], v[12:15]
	v_mfma_f32_16x16x32_bf16 v[8:11], v[160:163], v[212:215], v[8:11]
	v_mfma_f32_16x16x32_bf16 v[60:63], v[156:159], v[188:191], v[60:63]
	v_mfma_f32_16x16x32_bf16 v[56:59], v[164:167], v[188:191], v[56:59]
	v_mfma_f32_16x16x32_bf16 v[44:47], v[156:159], v[196:199], v[44:47]
	v_mfma_f32_16x16x32_bf16 v[40:43], v[164:167], v[196:199], v[40:43]
	v_mfma_f32_16x16x32_bf16 v[28:31], v[156:159], v[204:207], v[28:31]
	v_mfma_f32_16x16x32_bf16 v[24:27], v[164:167], v[204:207], v[24:27]
	v_mfma_f32_16x16x32_bf16 v[12:15], v[156:159], v[216:219], v[12:15]
	v_mfma_f32_16x16x32_bf16 v[8:11], v[164:167], v[216:219], v[8:11]
	s_setprio 0
	s_setprio 1
	v_mfma_f32_16x16x32_bf16 v[52:55], v[168:171], v[184:187], v[52:55]
	v_mfma_f32_16x16x32_bf16 v[48:51], v[176:179], v[184:187], v[48:51]
	v_mfma_f32_16x16x32_bf16 v[36:39], v[168:171], v[192:195], v[36:39]
	v_mfma_f32_16x16x32_bf16 v[32:35], v[176:179], v[192:195], v[32:35]
	v_mfma_f32_16x16x32_bf16 v[20:23], v[168:171], v[200:203], v[20:23]
	v_mfma_f32_16x16x32_bf16 v[16:19], v[176:179], v[200:203], v[16:19]
	v_mfma_f32_16x16x32_bf16 v[4:7], v[168:171], v[212:215], v[4:7]
	v_mfma_f32_16x16x32_bf16 v[0:3], v[176:179], v[212:215], v[0:3]
	v_mfma_f32_16x16x32_bf16 v[52:55], v[172:175], v[188:191], v[52:55]
	v_mfma_f32_16x16x32_bf16 v[48:51], v[180:183], v[188:191], v[48:51]
	v_mfma_f32_16x16x32_bf16 v[36:39], v[172:175], v[196:199], v[36:39]
	v_mfma_f32_16x16x32_bf16 v[32:35], v[180:183], v[196:199], v[32:35]
	v_mfma_f32_16x16x32_bf16 v[20:23], v[172:175], v[204:207], v[20:23]
	v_mfma_f32_16x16x32_bf16 v[16:19], v[180:183], v[204:207], v[16:19]
	v_mfma_f32_16x16x32_bf16 v[4:7], v[172:175], v[216:219], v[4:7]
	v_mfma_f32_16x16x32_bf16 v[0:3], v[180:183], v[216:219], v[0:3]
	s_setprio 0
	s_barrier
	s_add_i32 s26, 0, 0x18000
	v_add_u32_e32 v146, s26, v145
	s_add_i32 s27, 0, 0x1c000
	ds_read_b128 v[152:155], v146
	ds_read_b128 v[156:159], v146 offset:1024
	ds_read_b128 v[160:163], v146 offset:2048
	ds_read_b128 v[164:167], v146 offset:3072
	v_add_u32_e32 v146, s27, v145
	ds_read_b128 v[168:171], v146
	ds_read_b128 v[172:175], v146 offset:1024
	ds_read_b128 v[176:179], v146 offset:2048
	ds_read_b128 v[180:183], v146 offset:3072
	s_add_u32 s4, s54, 0x40000
	s_addc_u32 s5, s55, 0
	s_mov_b32 m0, s57
	ds_read_b128 v[184:187], v151 offset:32768
	ds_read_b128 v[188:191], v151 offset:33792
	ds_read_b128 v[192:195], v151 offset:34816
	ds_read_b128 v[196:199], v151 offset:35840
	ds_read_b128 v[200:203], v151 offset:36864
	ds_read_b128 v[204:207], v151 offset:37888
	ds_read_b128 v[212:215], v151 offset:38912
	ds_read_b128 v[216:219], v151 offset:39936
	global_load_lds_dwordx4 v128, s[4:5]
	s_mov_b32 m0, s58
	s_nop 0
	global_load_lds_dwordx4 v132, s[4:5]
	s_waitcnt vmcnt(8)
	s_waitcnt lgkmcnt(0)
	s_barrier
	s_setprio 1
	s_waitcnt lgkmcnt(0)
	v_mfma_f32_16x16x32_bf16 v[124:127], v[152:155], v[184:187], v[124:127]
	v_mfma_f32_16x16x32_bf16 v[120:123], v[160:163], v[184:187], v[120:123]
	v_mfma_f32_16x16x32_bf16 v[108:111], v[152:155], v[192:195], v[108:111]
	v_mfma_f32_16x16x32_bf16 v[104:107], v[160:163], v[192:195], v[104:107]
	v_mfma_f32_16x16x32_bf16 v[92:95], v[152:155], v[200:203], v[92:95]
	v_mfma_f32_16x16x32_bf16 v[88:91], v[160:163], v[200:203], v[88:91]
	v_mfma_f32_16x16x32_bf16 v[76:79], v[152:155], v[212:215], v[76:79]
	v_mfma_f32_16x16x32_bf16 v[72:75], v[160:163], v[212:215], v[72:75]
	v_mfma_f32_16x16x32_bf16 v[124:127], v[156:159], v[188:191], v[124:127]
	v_mfma_f32_16x16x32_bf16 v[120:123], v[164:167], v[188:191], v[120:123]
	v_mfma_f32_16x16x32_bf16 v[108:111], v[156:159], v[196:199], v[108:111]
	v_mfma_f32_16x16x32_bf16 v[104:107], v[164:167], v[196:199], v[104:107]
	v_mfma_f32_16x16x32_bf16 v[92:95], v[156:159], v[204:207], v[92:95]
	v_mfma_f32_16x16x32_bf16 v[88:91], v[164:167], v[204:207], v[88:91]
	v_mfma_f32_16x16x32_bf16 v[76:79], v[156:159], v[216:219], v[76:79]
	v_mfma_f32_16x16x32_bf16 v[72:75], v[164:167], v[216:219], v[72:75]
	s_setprio 0
	s_setprio 1
	v_mfma_f32_16x16x32_bf16 v[116:119], v[168:171], v[184:187], v[116:119]
	v_mfma_f32_16x16x32_bf16 v[112:115], v[176:179], v[184:187], v[112:115]
	v_mfma_f32_16x16x32_bf16 v[100:103], v[168:171], v[192:195], v[100:103]
	v_mfma_f32_16x16x32_bf16 v[96:99], v[176:179], v[192:195], v[96:99]
	v_mfma_f32_16x16x32_bf16 v[84:87], v[168:171], v[200:203], v[84:87]
	v_mfma_f32_16x16x32_bf16 v[80:83], v[176:179], v[200:203], v[80:83]
	v_mfma_f32_16x16x32_bf16 v[68:71], v[168:171], v[212:215], v[68:71]
	v_mfma_f32_16x16x32_bf16 v[64:67], v[176:179], v[212:215], v[64:67]
	v_mfma_f32_16x16x32_bf16 v[116:119], v[172:175], v[188:191], v[116:119]
	v_mfma_f32_16x16x32_bf16 v[112:115], v[180:183], v[188:191], v[112:115]
	v_mfma_f32_16x16x32_bf16 v[100:103], v[172:175], v[196:199], v[100:103]
	v_mfma_f32_16x16x32_bf16 v[96:99], v[180:183], v[196:199], v[96:99]
	v_mfma_f32_16x16x32_bf16 v[84:87], v[172:175], v[204:207], v[84:87]
	v_mfma_f32_16x16x32_bf16 v[80:83], v[180:183], v[204:207], v[80:83]
	v_mfma_f32_16x16x32_bf16 v[68:71], v[172:175], v[216:219], v[68:71]
	v_mfma_f32_16x16x32_bf16 v[64:67], v[180:183], v[216:219], v[64:67]
	s_setprio 0
	s_barrier
	s_add_i32 s4, s26, s46
	s_mov_b32 m0, s4
	ds_read_b128 v[184:187], v151 offset:49152
	ds_read_b128 v[188:191], v151 offset:50176
	ds_read_b128 v[192:195], v151 offset:51200
	ds_read_b128 v[196:199], v151 offset:52224
	ds_read_b128 v[200:203], v151 offset:53248
	ds_read_b128 v[204:207], v151 offset:54272
	ds_read_b128 v[212:215], v151 offset:55296
	ds_read_b128 v[216:219], v151 offset:56320
	global_load_lds_dwordx4 v208, s[52:53]
	s_add_i32 m0, s4, 0x2000
	s_add_u32 s4, s52, 0x40080
	s_addc_u32 s5, s53, 0
	s_add_i32 s26, s27, s46
	global_load_lds_dwordx4 v209, s[52:53]
	s_mov_b32 m0, s26
	s_nop 0
	global_load_lds_dwordx4 v130, s[4:5]
	s_add_i32 m0, s26, 0x2000
	s_nop 0
	global_load_lds_dwordx4 v134, s[4:5]
	s_mov_b32 m0, s62
	s_nop 0
	global_load_lds_dwordx4 v220, s[54:55]
	s_mov_b32 m0, s63
	s_nop 0
	global_load_lds_dwordx4 v221, s[54:55]
	s_waitcnt vmcnt(8)
	s_waitcnt lgkmcnt(0)
	s_barrier
	s_setprio 1
	s_waitcnt lgkmcnt(0)
	v_mfma_f32_16x16x32_bf16 v[60:63], v[152:155], v[184:187], v[60:63]
	v_mfma_f32_16x16x32_bf16 v[56:59], v[160:163], v[184:187], v[56:59]
	v_mfma_f32_16x16x32_bf16 v[44:47], v[152:155], v[192:195], v[44:47]
	v_mfma_f32_16x16x32_bf16 v[40:43], v[160:163], v[192:195], v[40:43]
	v_mfma_f32_16x16x32_bf16 v[28:31], v[152:155], v[200:203], v[28:31]
	v_mfma_f32_16x16x32_bf16 v[24:27], v[160:163], v[200:203], v[24:27]
	v_mfma_f32_16x16x32_bf16 v[12:15], v[152:155], v[212:215], v[12:15]
	v_mfma_f32_16x16x32_bf16 v[8:11], v[160:163], v[212:215], v[8:11]
	v_mfma_f32_16x16x32_bf16 v[60:63], v[156:159], v[188:191], v[60:63]
	v_mfma_f32_16x16x32_bf16 v[56:59], v[164:167], v[188:191], v[56:59]
	v_mfma_f32_16x16x32_bf16 v[44:47], v[156:159], v[196:199], v[44:47]
	v_mfma_f32_16x16x32_bf16 v[40:43], v[164:167], v[196:199], v[40:43]
	v_mfma_f32_16x16x32_bf16 v[28:31], v[156:159], v[204:207], v[28:31]
	v_mfma_f32_16x16x32_bf16 v[24:27], v[164:167], v[204:207], v[24:27]
	v_mfma_f32_16x16x32_bf16 v[12:15], v[156:159], v[216:219], v[12:15]
	v_mfma_f32_16x16x32_bf16 v[8:11], v[164:167], v[216:219], v[8:11]
	s_setprio 0
	s_setprio 1
	v_mfma_f32_16x16x32_bf16 v[52:55], v[168:171], v[184:187], v[52:55]
	v_mfma_f32_16x16x32_bf16 v[48:51], v[176:179], v[184:187], v[48:51]
	v_mfma_f32_16x16x32_bf16 v[36:39], v[168:171], v[192:195], v[36:39]
	v_mfma_f32_16x16x32_bf16 v[32:35], v[176:179], v[192:195], v[32:35]
	v_mfma_f32_16x16x32_bf16 v[20:23], v[168:171], v[200:203], v[20:23]
	v_mfma_f32_16x16x32_bf16 v[16:19], v[176:179], v[200:203], v[16:19]
	v_mfma_f32_16x16x32_bf16 v[4:7], v[168:171], v[212:215], v[4:7]
	v_mfma_f32_16x16x32_bf16 v[0:3], v[176:179], v[212:215], v[0:3]
	v_mfma_f32_16x16x32_bf16 v[52:55], v[172:175], v[188:191], v[52:55]
	v_mfma_f32_16x16x32_bf16 v[48:51], v[180:183], v[188:191], v[48:51]
	v_mfma_f32_16x16x32_bf16 v[36:39], v[172:175], v[196:199], v[36:39]
	v_mfma_f32_16x16x32_bf16 v[32:35], v[180:183], v[196:199], v[32:35]
	v_mfma_f32_16x16x32_bf16 v[20:23], v[172:175], v[204:207], v[20:23]
	v_mfma_f32_16x16x32_bf16 v[16:19], v[180:183], v[204:207], v[16:19]
	v_mfma_f32_16x16x32_bf16 v[4:7], v[172:175], v[216:219], v[4:7]
	v_mfma_f32_16x16x32_bf16 v[0:3], v[180:183], v[216:219], v[0:3]
	s_setprio 0
	s_barrier
	s_add_i32 s74, s74, 2
	s_add_u32 s50, s50, 0x100
	s_addc_u32 s51, s51, 0
	s_add_u32 s72, s72, 0x100
	s_addc_u32 s73, s73, 0
	s_cmp_gt_u32 s74, 13
	s_cbranch_scc0 .LBB0_2280
	s_and_b64 vcc, exec, s[16:17]
	s_cbranch_vccz .LBB0_2283
	s_barrier

.LBB0_2366:
	v_add_u32_e32 v208, 0x80, v178
	v_add_u32_e32 v209, 0x80, v182
	v_add_u32_e32 v216, 0x80, v176
	v_add_u32_e32 v217, 0x80, v180
	ds_read_b128 v[128:131], v213
	ds_read_b128 v[132:135], v213 offset:1024
	ds_read_b128 v[136:139], v213 offset:2048
	ds_read_b128 v[140:143], v213 offset:3072
	ds_read_b128 v[144:147], v214
	ds_read_b128 v[148:151], v214 offset:1024
	ds_read_b128 v[152:155], v214 offset:2048
	ds_read_b128 v[156:159], v214 offset:3072
	s_add_u32 s24, s22, 0x100
	s_addc_u32 s25, s23, 0
	s_cmp_eq_u32 s69, 40
	s_cselect_b32 s51, s9, s25
	s_cselect_b32 s50, s8, s24
	s_cselect_b32 s49, s21, s68
	s_cselect_b32 s48, s20, s67
	s_add_i32 m0, s33, 0xc000
	ds_read_b128 v[160:163], v215
	ds_read_b128 v[164:167], v215 offset:1024
	ds_read_b128 v[168:171], v215 offset:2048
	ds_read_b128 v[172:175], v215 offset:3072
	ds_read_b128 v[192:195], v215 offset:4096
	ds_read_b128 v[196:199], v215 offset:5120
	ds_read_b128 v[200:203], v215 offset:6144
	ds_read_b128 v[204:207], v215 offset:7168
	global_load_lds_dwordx4 v184, s[22:23]
	s_add_i32 m0, s33, 0xe000
	s_nop 0
	global_load_lds_dwordx4 v186, s[22:23]
	s_waitcnt vmcnt(8)
	s_waitcnt lgkmcnt(0)
	s_barrier
	s_setprio 1
	s_waitcnt lgkmcnt(0)
	v_mfma_f32_16x16x32_bf16 v[124:127], v[128:131], v[160:163], v[124:127]
	v_mfma_f32_16x16x32_bf16 v[120:123], v[136:139], v[160:163], v[120:123]
	v_mfma_f32_16x16x32_bf16 v[108:111], v[128:131], v[168:171], v[108:111]
	v_mfma_f32_16x16x32_bf16 v[104:107], v[136:139], v[168:171], v[104:107]
	v_mfma_f32_16x16x32_bf16 v[92:95], v[128:131], v[192:195], v[92:95]
	v_mfma_f32_16x16x32_bf16 v[88:91], v[136:139], v[192:195], v[88:91]
	v_mfma_f32_16x16x32_bf16 v[76:79], v[128:131], v[200:203], v[76:79]
	v_mfma_f32_16x16x32_bf16 v[72:75], v[136:139], v[200:203], v[72:75]
	v_mfma_f32_16x16x32_bf16 v[124:127], v[132:135], v[164:167], v[124:127]
	v_mfma_f32_16x16x32_bf16 v[120:123], v[140:143], v[164:167], v[120:123]
	v_mfma_f32_16x16x32_bf16 v[108:111], v[132:135], v[172:175], v[108:111]
	v_mfma_f32_16x16x32_bf16 v[104:107], v[140:143], v[172:175], v[104:107]
	v_mfma_f32_16x16x32_bf16 v[92:95], v[132:135], v[196:199], v[92:95]
	v_mfma_f32_16x16x32_bf16 v[88:91], v[140:143], v[196:199], v[88:91]
	v_mfma_f32_16x16x32_bf16 v[76:79], v[132:135], v[204:207], v[76:79]
	v_mfma_f32_16x16x32_bf16 v[72:75], v[140:143], v[204:207], v[72:75]
	s_setprio 0
	s_setprio 1
	v_mfma_f32_16x16x32_bf16 v[116:119], v[144:147], v[160:163], v[116:119]
	v_mfma_f32_16x16x32_bf16 v[112:115], v[152:155], v[160:163], v[112:115]
	v_mfma_f32_16x16x32_bf16 v[100:103], v[144:147], v[168:171], v[100:103]
	v_mfma_f32_16x16x32_bf16 v[96:99], v[152:155], v[168:171], v[96:99]
	v_mfma_f32_16x16x32_bf16 v[84:87], v[144:147], v[192:195], v[84:87]
	v_mfma_f32_16x16x32_bf16 v[80:83], v[152:155], v[192:195], v[80:83]
	v_mfma_f32_16x16x32_bf16 v[68:71], v[144:147], v[200:203], v[68:71]
	v_mfma_f32_16x16x32_bf16 v[64:67], v[152:155], v[200:203], v[64:67]
	v_mfma_f32_16x16x32_bf16 v[116:119], v[148:151], v[164:167], v[116:119]
	v_mfma_f32_16x16x32_bf16 v[112:115], v[156:159], v[164:167], v[112:115]
	v_mfma_f32_16x16x32_bf16 v[100:103], v[148:151], v[172:175], v[100:103]
	v_mfma_f32_16x16x32_bf16 v[96:99], v[156:159], v[172:175], v[96:99]
	v_mfma_f32_16x16x32_bf16 v[84:87], v[148:151], v[196:199], v[84:87]
	v_mfma_f32_16x16x32_bf16 v[80:83], v[156:159], v[196:199], v[80:83]
	v_mfma_f32_16x16x32_bf16 v[68:71], v[148:151], v[204:207], v[68:71]
	v_mfma_f32_16x16x32_bf16 v[64:67], v[156:159], v[204:207], v[64:67]
	s_setprio 0
	s_barrier
	s_add_i32 s22, s61, s3
	s_mov_b32 m0, s22
	ds_read_b128 v[160:163], v215 offset:16384
	ds_read_b128 v[164:167], v215 offset:17408
	ds_read_b128 v[168:171], v215 offset:18432
	ds_read_b128 v[172:175], v215 offset:19456
	ds_read_b128 v[192:195], v215 offset:20480
	ds_read_b128 v[196:199], v215 offset:21504
	ds_read_b128 v[200:203], v215 offset:22528
	ds_read_b128 v[204:207], v215 offset:23552
	global_load_lds_dwordx4 v178, s[48:49]
	s_add_i32 m0, s22, 0x2000
	s_add_u32 s22, s48, 0xb0000
	s_addc_u32 s23, s49, 0
	s_add_i32 s26, s62, s3
	global_load_lds_dwordx4 v182, s[48:49]
	s_mov_b32 m0, s26
	s_nop 0
	global_load_lds_dwordx4 v178, s[22:23]
	s_add_i32 m0, s26, 0x2000
	s_nop 0
	global_load_lds_dwordx4 v182, s[22:23]
	s_mov_b32 m0, s33
	s_nop 0
	global_load_lds_dwordx4 v176, s[50:51]
	s_mov_b32 m0, s46
	s_nop 0
	global_load_lds_dwordx4 v180, s[50:51]
	s_waitcnt vmcnt(8)
	s_waitcnt lgkmcnt(0)
	s_barrier
	s_setprio 1
	s_waitcnt lgkmcnt(0)
	v_mfma_f32_16x16x32_bf16 v[60:63], v[128:131], v[160:163], v[60:63]
	v_mfma_f32_16x16x32_bf16 v[56:59], v[136:139], v[160:163], v[56:59]
	v_mfma_f32_16x16x32_bf16 v[44:47], v[128:131], v[168:171], v[44:47]
	v_mfma_f32_16x16x32_bf16 v[40:43], v[136:139], v[168:171], v[40:43]
	v_mfma_f32_16x16x32_bf16 v[28:31], v[128:131], v[192:195], v[28:31]
	v_mfma_f32_16x16x32_bf16 v[24:27], v[136:139], v[192:195], v[24:27]
	v_mfma_f32_16x16x32_bf16 v[12:15], v[128:131], v[200:203], v[12:15]
	v_mfma_f32_16x16x32_bf16 v[8:11], v[136:139], v[200:203], v[8:11]
	v_mfma_f32_16x16x32_bf16 v[60:63], v[132:135], v[164:167], v[60:63]
	v_mfma_f32_16x16x32_bf16 v[56:59], v[140:143], v[164:167], v[56:59]
	v_mfma_f32_16x16x32_bf16 v[44:47], v[132:135], v[172:175], v[44:47]
	v_mfma_f32_16x16x32_bf16 v[40:43], v[140:143], v[172:175], v[40:43]
	v_mfma_f32_16x16x32_bf16 v[28:31], v[132:135], v[196:199], v[28:31]
	v_mfma_f32_16x16x32_bf16 v[24:27], v[140:143], v[196:199], v[24:27]
	v_mfma_f32_16x16x32_bf16 v[12:15], v[132:135], v[204:207], v[12:15]
	v_mfma_f32_16x16x32_bf16 v[8:11], v[140:143], v[204:207], v[8:11]
	s_setprio 0
	s_setprio 1
	v_mfma_f32_16x16x32_bf16 v[52:55], v[144:147], v[160:163], v[52:55]
	v_mfma_f32_16x16x32_bf16 v[48:51], v[152:155], v[160:163], v[48:51]
	v_mfma_f32_16x16x32_bf16 v[36:39], v[144:147], v[168:171], v[36:39]
	v_mfma_f32_16x16x32_bf16 v[32:35], v[152:155], v[168:171], v[32:35]
	v_mfma_f32_16x16x32_bf16 v[20:23], v[144:147], v[192:195], v[20:23]
	v_mfma_f32_16x16x32_bf16 v[16:19], v[152:155], v[192:195], v[16:19]
	v_mfma_f32_16x16x32_bf16 v[4:7], v[144:147], v[200:203], v[4:7]
	v_mfma_f32_16x16x32_bf16 v[0:3], v[152:155], v[200:203], v[0:3]
	v_mfma_f32_16x16x32_bf16 v[52:55], v[148:151], v[164:167], v[52:55]
	v_mfma_f32_16x16x32_bf16 v[48:51], v[156:159], v[164:167], v[48:51]
	v_mfma_f32_16x16x32_bf16 v[36:39], v[148:151], v[172:175], v[36:39]
	v_mfma_f32_16x16x32_bf16 v[32:35], v[156:159], v[172:175], v[32:35]
	v_mfma_f32_16x16x32_bf16 v[20:23], v[148:151], v[196:199], v[20:23]
	v_mfma_f32_16x16x32_bf16 v[16:19], v[156:159], v[196:199], v[16:19]
	v_mfma_f32_16x16x32_bf16 v[4:7], v[148:151], v[204:207], v[4:7]
	v_mfma_f32_16x16x32_bf16 v[0:3], v[156:159], v[204:207], v[0:3]
	s_setprio 0
	s_barrier
	s_add_i32 s26, 0, 0x18000
	s_add_i32 s27, 0, 0x1c000
	v_add_u32_e32 v140, s26, v212
	v_add_u32_e32 v156, s27, v212
	ds_read_b128 v[128:131], v140
	ds_read_b128 v[132:135], v140 offset:1024
	ds_read_b128 v[136:139], v140 offset:2048
	ds_read_b128 v[140:143], v140 offset:3072
	ds_read_b128 v[144:147], v156
	ds_read_b128 v[148:151], v156 offset:1024
	ds_read_b128 v[152:155], v156 offset:2048
	ds_read_b128 v[156:159], v156 offset:3072
	s_add_u32 s22, s50, 0xb0000
	s_addc_u32 s23, s51, 0
	s_mov_b32 m0, s47
	ds_read_b128 v[160:163], v215 offset:32768
	ds_read_b128 v[164:167], v215 offset:33792
	ds_read_b128 v[168:171], v215 offset:34816
	ds_read_b128 v[172:175], v215 offset:35840
	ds_read_b128 v[192:195], v215 offset:36864
	ds_read_b128 v[196:199], v215 offset:37888
	ds_read_b128 v[200:203], v215 offset:38912
	ds_read_b128 v[204:207], v215 offset:39936
	global_load_lds_dwordx4 v176, s[22:23]
	s_mov_b32 m0, s52
	s_nop 0
	global_load_lds_dwordx4 v180, s[22:23]
	s_waitcnt vmcnt(8)
	s_waitcnt lgkmcnt(0)
	s_barrier
	s_setprio 1
	s_waitcnt lgkmcnt(0)
	v_mfma_f32_16x16x32_bf16 v[124:127], v[128:131], v[160:163], v[124:127]
	v_mfma_f32_16x16x32_bf16 v[120:123], v[136:139], v[160:163], v[120:123]
	v_mfma_f32_16x16x32_bf16 v[108:111], v[128:131], v[168:171], v[108:111]
	v_mfma_f32_16x16x32_bf16 v[104:107], v[136:139], v[168:171], v[104:107]
	v_mfma_f32_16x16x32_bf16 v[92:95], v[128:131], v[192:195], v[92:95]
	v_mfma_f32_16x16x32_bf16 v[88:91], v[136:139], v[192:195], v[88:91]
	v_mfma_f32_16x16x32_bf16 v[76:79], v[128:131], v[200:203], v[76:79]
	v_mfma_f32_16x16x32_bf16 v[72:75], v[136:139], v[200:203], v[72:75]
	v_mfma_f32_16x16x32_bf16 v[124:127], v[132:135], v[164:167], v[124:127]
	v_mfma_f32_16x16x32_bf16 v[120:123], v[140:143], v[164:167], v[120:123]
	v_mfma_f32_16x16x32_bf16 v[108:111], v[132:135], v[172:175], v[108:111]
	v_mfma_f32_16x16x32_bf16 v[104:107], v[140:143], v[172:175], v[104:107]
	v_mfma_f32_16x16x32_bf16 v[92:95], v[132:135], v[196:199], v[92:95]
	v_mfma_f32_16x16x32_bf16 v[88:91], v[140:143], v[196:199], v[88:91]
	v_mfma_f32_16x16x32_bf16 v[76:79], v[132:135], v[204:207], v[76:79]
	v_mfma_f32_16x16x32_bf16 v[72:75], v[140:143], v[204:207], v[72:75]
	s_setprio 0
	s_setprio 1
	v_mfma_f32_16x16x32_bf16 v[116:119], v[144:147], v[160:163], v[116:119]
	v_mfma_f32_16x16x32_bf16 v[112:115], v[152:155], v[160:163], v[112:115]
	v_mfma_f32_16x16x32_bf16 v[100:103], v[144:147], v[168:171], v[100:103]
	v_mfma_f32_16x16x32_bf16 v[96:99], v[152:155], v[168:171], v[96:99]
	v_mfma_f32_16x16x32_bf16 v[84:87], v[144:147], v[192:195], v[84:87]
	v_mfma_f32_16x16x32_bf16 v[80:83], v[152:155], v[192:195], v[80:83]
	v_mfma_f32_16x16x32_bf16 v[68:71], v[144:147], v[200:203], v[68:71]
	v_mfma_f32_16x16x32_bf16 v[64:67], v[152:155], v[200:203], v[64:67]
	v_mfma_f32_16x16x32_bf16 v[116:119], v[148:151], v[164:167], v[116:119]
	v_mfma_f32_16x16x32_bf16 v[112:115], v[156:159], v[164:167], v[112:115]
	v_mfma_f32_16x16x32_bf16 v[100:103], v[148:151], v[172:175], v[100:103]
	v_mfma_f32_16x16x32_bf16 v[96:99], v[156:159], v[172:175], v[96:99]
	v_mfma_f32_16x16x32_bf16 v[84:87], v[148:151], v[196:199], v[84:87]
	v_mfma_f32_16x16x32_bf16 v[80:83], v[156:159], v[196:199], v[80:83]
	v_mfma_f32_16x16x32_bf16 v[68:71], v[148:151], v[204:207], v[68:71]
	v_mfma_f32_16x16x32_bf16 v[64:67], v[156:159], v[204:207], v[64:67]
	s_setprio 0
	s_barrier
	s_add_i32 s22, s26, s3
	s_mov_b32 m0, s22
	ds_read_b128 v[160:163], v215 offset:49152
	ds_read_b128 v[164:167], v215 offset:50176
	ds_read_b128 v[168:171], v215 offset:51200
	ds_read_b128 v[172:175], v215 offset:52224
	ds_read_b128 v[192:195], v215 offset:53248
	ds_read_b128 v[196:199], v215 offset:54272
	ds_read_b128 v[200:203], v215 offset:55296
	ds_read_b128 v[204:207], v215 offset:56320
	global_load_lds_dwordx4 v208, s[48:49]
	s_add_i32 m0, s22, 0x2000
	s_add_u32 s22, s48, 0xb0080
	s_addc_u32 s23, s49, 0
	s_add_i32 s26, s27, s3
	global_load_lds_dwordx4 v209, s[48:49]
	s_mov_b32 m0, s26
	s_nop 0
	global_load_lds_dwordx4 v178, s[22:23]
	s_add_i32 m0, s26, 0x2000
	s_nop 0
	global_load_lds_dwordx4 v182, s[22:23]
	s_mov_b32 m0, s56
	s_nop 0
	global_load_lds_dwordx4 v216, s[50:51]
	s_mov_b32 m0, s57
	s_nop 0
	global_load_lds_dwordx4 v217, s[50:51]
	s_waitcnt vmcnt(8)
	s_waitcnt lgkmcnt(0)
	s_barrier
	s_setprio 1
	s_waitcnt lgkmcnt(0)
	v_mfma_f32_16x16x32_bf16 v[60:63], v[128:131], v[160:163], v[60:63]
	v_mfma_f32_16x16x32_bf16 v[56:59], v[136:139], v[160:163], v[56:59]
	v_mfma_f32_16x16x32_bf16 v[44:47], v[128:131], v[168:171], v[44:47]
	v_mfma_f32_16x16x32_bf16 v[40:43], v[136:139], v[168:171], v[40:43]
	v_mfma_f32_16x16x32_bf16 v[28:31], v[128:131], v[192:195], v[28:31]
	v_mfma_f32_16x16x32_bf16 v[24:27], v[136:139], v[192:195], v[24:27]
	v_mfma_f32_16x16x32_bf16 v[12:15], v[128:131], v[200:203], v[12:15]
	v_mfma_f32_16x16x32_bf16 v[8:11], v[136:139], v[200:203], v[8:11]
	v_mfma_f32_16x16x32_bf16 v[60:63], v[132:135], v[164:167], v[60:63]
	v_mfma_f32_16x16x32_bf16 v[56:59], v[140:143], v[164:167], v[56:59]
	v_mfma_f32_16x16x32_bf16 v[44:47], v[132:135], v[172:175], v[44:47]
	v_mfma_f32_16x16x32_bf16 v[40:43], v[140:143], v[172:175], v[40:43]
	v_mfma_f32_16x16x32_bf16 v[28:31], v[132:135], v[196:199], v[28:31]
	v_mfma_f32_16x16x32_bf16 v[24:27], v[140:143], v[196:199], v[24:27]
	v_mfma_f32_16x16x32_bf16 v[12:15], v[132:135], v[204:207], v[12:15]
	v_mfma_f32_16x16x32_bf16 v[8:11], v[140:143], v[204:207], v[8:11]
	s_setprio 0
	s_setprio 1
	v_mfma_f32_16x16x32_bf16 v[52:55], v[144:147], v[160:163], v[52:55]
	v_mfma_f32_16x16x32_bf16 v[48:51], v[152:155], v[160:163], v[48:51]
	v_mfma_f32_16x16x32_bf16 v[36:39], v[144:147], v[168:171], v[36:39]
	v_mfma_f32_16x16x32_bf16 v[32:35], v[152:155], v[168:171], v[32:35]
	v_mfma_f32_16x16x32_bf16 v[20:23], v[144:147], v[192:195], v[20:23]
	v_mfma_f32_16x16x32_bf16 v[16:19], v[152:155], v[192:195], v[16:19]
	v_mfma_f32_16x16x32_bf16 v[4:7], v[144:147], v[200:203], v[4:7]
	v_mfma_f32_16x16x32_bf16 v[0:3], v[152:155], v[200:203], v[0:3]
	v_mfma_f32_16x16x32_bf16 v[52:55], v[148:151], v[164:167], v[52:55]
	v_mfma_f32_16x16x32_bf16 v[48:51], v[156:159], v[164:167], v[48:51]
	v_mfma_f32_16x16x32_bf16 v[36:39], v[148:151], v[172:175], v[36:39]
	v_mfma_f32_16x16x32_bf16 v[32:35], v[156:159], v[172:175], v[32:35]
	v_mfma_f32_16x16x32_bf16 v[20:23], v[148:151], v[196:199], v[20:23]
	v_mfma_f32_16x16x32_bf16 v[16:19], v[156:159], v[196:199], v[16:19]
	v_mfma_f32_16x16x32_bf16 v[4:7], v[148:151], v[204:207], v[4:7]
	v_mfma_f32_16x16x32_bf16 v[0:3], v[156:159], v[204:207], v[0:3]
	s_setprio 0
	s_barrier
	s_add_i32 s69, s69, 2
	s_add_u32 s67, s67, 0x100
	s_addc_u32 s68, s68, 0
	s_cmp_gt_u32 s69, 41
	s_mov_b64 s[22:23], s[24:25]
	s_cbranch_scc0 .LBB0_2366
	s_and_b64 vcc, exec, s[18:19]
	s_cbranch_vccz .LBB0_2369
	s_barrier

	.amdhsa_kernel _Z8yoco_fwd6Params
		.amdhsa_group_segment_fixed_size 0
		.amdhsa_private_segment_fixed_size 0
		.amdhsa_kernarg_size 576
		.amdhsa_user_sgpr_count 2
		.amdhsa_user_sgpr_dispatch_ptr 0
		.amdhsa_user_sgpr_queue_ptr 0
		.amdhsa_user_sgpr_kernarg_segment_ptr 1
		.amdhsa_user_sgpr_dispatch_id 0
		.amdhsa_user_sgpr_kernarg_preload_length 0
		.amdhsa_user_sgpr_kernarg_preload_offset 0
		.amdhsa_user_sgpr_private_segment_size 0
		.amdhsa_uses_dynamic_stack 0
		.amdhsa_enable_private_segment 0
		.amdhsa_system_sgpr_workgroup_id_x 1
		.amdhsa_system_sgpr_workgroup_id_y 0
		.amdhsa_system_sgpr_workgroup_id_z 0
		.amdhsa_system_sgpr_workgroup_info 0
		.amdhsa_system_vgpr_workitem_id 2
		.amdhsa_next_free_vgpr 256
		.amdhsa_next_free_sgpr 102
		.amdhsa_accum_offset 256
		.amdhsa_reserve_vcc 1
		.amdhsa_float_round_mode_32 0
		.amdhsa_float_round_mode_16_64 0
		.amdhsa_float_denorm_mode_32 3
		.amdhsa_float_denorm_mode_16_64 3
		.amdhsa_dx10_clamp 1
		.amdhsa_ieee_mode 1
		.amdhsa_fp16_overflow 0
		.amdhsa_tg_split 0
		.amdhsa_exception_fp_ieee_invalid_op 0
		.amdhsa_exception_fp_denorm_src 0
		.amdhsa_exception_fp_ieee_div_zero 0
		.amdhsa_exception_fp_ieee_overflow 0
		.amdhsa_exception_fp_ieee_underflow 0
		.amdhsa_exception_fp_ieee_inexact 0
		.amdhsa_exception_int_div_zero 0
	.end_amdhsa_kernel

amdhsa.kernels:
  - .agpr_count:     0
    .args:
      - .offset:         0
        .size:           320
        .value_kind:     by_value
      - .offset:         320
        .size:           4
        .value_kind:     hidden_block_count_x
      - .offset:         324
        .size:           4
        .value_kind:     hidden_block_count_y
      - .offset:         328
        .size:           4
        .value_kind:     hidden_block_count_z
      - .offset:         332
        .size:           2
        .value_kind:     hidden_group_size_x
      - .offset:         334
        .size:           2
        .value_kind:     hidden_group_size_y
      - .offset:         336
        .size:           2
        .value_kind:     hidden_group_size_z
      - .offset:         338
        .size:           2
        .value_kind:     hidden_remainder_x
      - .offset:         340
        .size:           2
        .value_kind:     hidden_remainder_y
      - .offset:         342
        .size:           2
        .value_kind:     hidden_remainder_z
      - .offset:         360
        .size:           8
        .value_kind:     hidden_global_offset_x
      - .offset:         368
        .size:           8
        .value_kind:     hidden_global_offset_y
      - .offset:         376
        .size:           8
        .value_kind:     hidden_global_offset_z
      - .offset:         384
        .size:           2
        .value_kind:     hidden_grid_dims
      - .offset:         408
        .size:           8
        .value_kind:     hidden_multigrid_sync_arg
      - .offset:         440
        .size:           4
        .value_kind:     hidden_dynamic_lds_size
    .group_segment_fixed_size: 0
    .kernarg_segment_align: 8
    .kernarg_segment_size: 576
    .language:       OpenCL C
    .language_version:
      - 2
      - 0
    .max_flat_workgroup_size: 512
    .name:           _Z8yoco_fwd6Params
    .private_segment_fixed_size: 0
    .sgpr_count:     108
    .sgpr_spill_count: 13
    .symbol:         _Z8yoco_fwd6Params.kd
    .uniform_work_group_size: 1
    .uses_dynamic_stack: false
    .vgpr_count:     256
    .vgpr_spill_count: 0
    .wavefront_size: 64
